# P0: adaLN GEMV weight loads software-pipelined 4 deep; weight transpose loops unrolled so 32 loads are in flight
# baseline (speedup 1.0000x reference)
.LBB0_99:
	s_mul_hi_i32 s14, s19, 0x2aaaaaab
	s_lshr_b32 s15, s14, 31
	s_ashr_i32 s20, s14, 6
	s_add_i32 s20, s20, s15
	s_mul_i32 s14, s20, 0x180
	s_sub_i32 s14, s19, s14
	s_lshl_b32 s14, s14, 5
	s_ashr_i32 s15, s14, 31
	s_mul_i32 s22, s20, 0x6000000
	s_lshl_b64 s[16:17], s[14:15], 2
	s_mul_hi_i32 s21, s20, 0x6000000
	s_add_u32 s16, s22, s16
	s_addc_u32 s17, s21, s17
	v_lshl_add_u64 v[12:13], v[10:11], 0, s[16:17]
	s_mov_b64 s[16:17], 0
	v_mov_b32_e32 v6, v18
	v_mov_b32_e32 v22, v9
	v_mov_b32_e32 v14, 0
	v_mov_b32_e32 v15, v7
	v_mov_b32_e32 v16, 0
	v_mov_b32_e32 v17, v7
	v_mov_b32_e32 v21, 0
	v_add_co_u32_e32 v24, vcc, 0xfffac000, v12
	s_nop 0
	v_addc_co_u32_e32 v25, vcc, -1, v13, vcc
	v_add_co_u32_e32 v26, vcc, 0xfffb8000, v12
	global_load_dword v64, v[24:25], off
	s_nop 0
	v_addc_co_u32_e32 v27, vcc, -1, v13, vcc
	v_add_co_u32_e32 v24, vcc, 0xfffc4000, v12
	s_nop 1
	v_addc_co_u32_e32 v25, vcc, -1, v13, vcc
	v_add_co_u32_e32 v28, vcc, 0xfffd0000, v12
	global_load_dword v66, v[26:27], off
	global_load_dword v68, v[24:25], off
	v_addc_co_u32_e32 v29, vcc, -1, v13, vcc
	v_add_co_u32_e32 v24, vcc, 0xfffdc000, v12
	s_nop 1
	v_addc_co_u32_e32 v25, vcc, -1, v13, vcc
	v_add_co_u32_e32 v26, vcc, 0xfffe8000, v12
	global_load_dword v70, v[28:29], off
	global_load_dword v72, v[24:25], off
	v_addc_co_u32_e32 v27, vcc, -1, v13, vcc
	v_add_co_u32_e32 v24, vcc, 0xffff4000, v12
	global_load_dword v74, v[26:27], off
	s_nop 0
	v_addc_co_u32_e32 v25, vcc, -1, v13, vcc
	global_load_dword v76, v[24:25], off
	global_load_dword v78, v[12:13], off
	v_lshl_add_u64 v[12:13], v[12:13], 0, s[12:13]
	v_add_co_u32_e32 v24, vcc, 0xfffac000, v12
	s_nop 0
	v_addc_co_u32_e32 v25, vcc, -1, v13, vcc
	v_add_co_u32_e32 v26, vcc, 0xfffb8000, v12
	global_load_dword v96, v[24:25], off
	s_nop 0
	v_addc_co_u32_e32 v27, vcc, -1, v13, vcc
	v_add_co_u32_e32 v24, vcc, 0xfffc4000, v12
	s_nop 1
	v_addc_co_u32_e32 v25, vcc, -1, v13, vcc
	v_add_co_u32_e32 v28, vcc, 0xfffd0000, v12
	global_load_dword v98, v[26:27], off
	global_load_dword v100, v[24:25], off
	v_addc_co_u32_e32 v29, vcc, -1, v13, vcc
	v_add_co_u32_e32 v24, vcc, 0xfffdc000, v12
	s_nop 1
	v_addc_co_u32_e32 v25, vcc, -1, v13, vcc
	v_add_co_u32_e32 v26, vcc, 0xfffe8000, v12
	global_load_dword v102, v[28:29], off
	global_load_dword v104, v[24:25], off
	v_addc_co_u32_e32 v27, vcc, -1, v13, vcc
	v_add_co_u32_e32 v24, vcc, 0xffff4000, v12
	global_load_dword v106, v[26:27], off
	s_nop 0
	v_addc_co_u32_e32 v25, vcc, -1, v13, vcc
	global_load_dword v108, v[24:25], off
	global_load_dword v110, v[12:13], off
	v_lshl_add_u64 v[12:13], v[12:13], 0, s[12:13]
	v_add_co_u32_e32 v24, vcc, 0xfffac000, v12
	s_nop 0
	v_addc_co_u32_e32 v25, vcc, -1, v13, vcc
	v_add_co_u32_e32 v26, vcc, 0xfffb8000, v12
	global_load_dword v112, v[24:25], off
	s_nop 0
	v_addc_co_u32_e32 v27, vcc, -1, v13, vcc
	v_add_co_u32_e32 v24, vcc, 0xfffc4000, v12
	s_nop 1
	v_addc_co_u32_e32 v25, vcc, -1, v13, vcc
	v_add_co_u32_e32 v28, vcc, 0xfffd0000, v12
	global_load_dword v114, v[26:27], off
	global_load_dword v116, v[24:25], off
	v_addc_co_u32_e32 v29, vcc, -1, v13, vcc
	v_add_co_u32_e32 v24, vcc, 0xfffdc000, v12
	s_nop 1
	v_addc_co_u32_e32 v25, vcc, -1, v13, vcc
	v_add_co_u32_e32 v26, vcc, 0xfffe8000, v12
	global_load_dword v118, v[28:29], off
	global_load_dword v120, v[24:25], off
	v_addc_co_u32_e32 v27, vcc, -1, v13, vcc
	v_add_co_u32_e32 v24, vcc, 0xffff4000, v12
	global_load_dword v122, v[26:27], off
	s_nop 0
	v_addc_co_u32_e32 v25, vcc, -1, v13, vcc
	global_load_dword v124, v[24:25], off
	global_load_dword v126, v[12:13], off
	v_lshl_add_u64 v[12:13], v[12:13], 0, s[12:13]
	s_mov_b32 s100, 3
.Lada_loop:
	v_add_co_u32_e32 v24, vcc, 0xfffac000, v12
	s_nop 0
	v_addc_co_u32_e32 v25, vcc, -1, v13, vcc
	v_add_co_u32_e32 v26, vcc, 0xfffb8000, v12
	global_load_dword v128, v[24:25], off
	s_nop 0
	v_addc_co_u32_e32 v27, vcc, -1, v13, vcc
	v_add_co_u32_e32 v24, vcc, 0xfffc4000, v12
	s_nop 1
	v_addc_co_u32_e32 v25, vcc, -1, v13, vcc
	v_add_co_u32_e32 v28, vcc, 0xfffd0000, v12
	global_load_dword v130, v[26:27], off
	global_load_dword v132, v[24:25], off
	v_addc_co_u32_e32 v29, vcc, -1, v13, vcc
	v_add_co_u32_e32 v24, vcc, 0xfffdc000, v12
	s_nop 1
	v_addc_co_u32_e32 v25, vcc, -1, v13, vcc
	v_add_co_u32_e32 v26, vcc, 0xfffe8000, v12
	global_load_dword v134, v[28:29], off
	global_load_dword v136, v[24:25], off
	v_addc_co_u32_e32 v27, vcc, -1, v13, vcc
	v_add_co_u32_e32 v24, vcc, 0xffff4000, v12
	global_load_dword v138, v[26:27], off
	s_nop 0
	v_addc_co_u32_e32 v25, vcc, -1, v13, vcc
	global_load_dword v140, v[24:25], off
	global_load_dword v142, v[12:13], off
	v_lshl_add_u64 v[12:13], v[12:13], 0, s[12:13]
	ds_read_b128 v[24:27], v6
	ds_read_b128 v[28:31], v6 offset:16
	ds_read_b128 v[32:35], v6 offset:8192
	ds_read_b128 v[36:39], v6 offset:8208
	ds_read_b128 v[40:43], v6 offset:16384
	ds_read_b128 v[44:47], v6 offset:16400
	ds_read_b128 v[48:51], v6 offset:24576
	ds_read_b128 v[52:55], v6 offset:24592
	ds_read_b128 v[56:59], v6 offset:32768
	ds_read_b128 v[60:63], v6 offset:32784
	s_waitcnt lgkmcnt(9)
	v_mov_b32_e32 v80, v24
	s_waitcnt lgkmcnt(7)
	v_mov_b32_e32 v81, v32
	v_mov_b32_e32 v32, v25
	v_mov_b32_e32 v24, v26
	v_mov_b32_e32 v25, v34
	v_mov_b32_e32 v34, v27
	v_mov_b32_e32 v26, v28
	s_waitcnt lgkmcnt(6)
	v_mov_b32_e32 v27, v36
	v_mov_b32_e32 v36, v29
	v_mov_b32_e32 v28, v30
	v_mov_b32_e32 v29, v38
	v_mov_b32_e32 v38, v31
	s_waitcnt lgkmcnt(5)
	v_mov_b32_e32 v30, v40
	s_waitcnt lgkmcnt(3)
	v_mov_b32_e32 v31, v48
	v_mov_b32_e32 v48, v41
	v_mov_b32_e32 v40, v42
	v_mov_b32_e32 v41, v50
	v_mov_b32_e32 v50, v43
	v_mov_b32_e32 v42, v44
	s_waitcnt lgkmcnt(2)
	v_mov_b32_e32 v43, v52
	v_mov_b32_e32 v52, v45
	v_mov_b32_e32 v44, v46
	v_mov_b32_e32 v45, v54
	v_mov_b32_e32 v54, v47
	v_add_u32_e32 v6, 32, v6
	s_waitcnt vmcnt(31)
	v_pk_fma_f32 v[14:15], v[80:81], v[64:65], v[14:15] op_sel_hi:[1,0,1]
	v_pk_fma_f32 v[16:17], v[30:31], v[64:65], v[16:17] op_sel_hi:[1,0,1]
	s_waitcnt lgkmcnt(1)
	v_fmac_f32_e32 v21, v56, v64
	s_waitcnt vmcnt(30)
	v_fmac_f32_e32 v21, v57, v66
	v_pk_fma_f32 v[14:15], v[32:33], v[66:67], v[14:15] op_sel_hi:[1,0,1]
	v_pk_fma_f32 v[16:17], v[48:49], v[66:67], v[16:17] op_sel_hi:[1,0,1]
	s_waitcnt vmcnt(29)
	v_fmac_f32_e32 v21, v58, v68
	v_pk_fma_f32 v[14:15], v[24:25], v[68:69], v[14:15] op_sel_hi:[1,0,1]
	v_pk_fma_f32 v[16:17], v[40:41], v[68:69], v[16:17] op_sel_hi:[1,0,1]
	s_waitcnt vmcnt(28)
	v_fmac_f32_e32 v21, v59, v70
	v_pk_fma_f32 v[14:15], v[34:35], v[70:71], v[14:15] op_sel_hi:[1,0,1]
	v_pk_fma_f32 v[16:17], v[50:51], v[70:71], v[16:17] op_sel_hi:[1,0,1]
	s_waitcnt vmcnt(27) lgkmcnt(0)
	v_fmac_f32_e32 v21, v60, v72
	v_pk_fma_f32 v[14:15], v[26:27], v[72:73], v[14:15] op_sel_hi:[1,0,1]
	v_pk_fma_f32 v[16:17], v[42:43], v[72:73], v[16:17] op_sel_hi:[1,0,1]
	s_waitcnt vmcnt(26)
	v_fmac_f32_e32 v21, v61, v74
	v_pk_fma_f32 v[14:15], v[36:37], v[74:75], v[14:15] op_sel_hi:[1,0,1]
	v_pk_fma_f32 v[16:17], v[52:53], v[74:75], v[16:17] op_sel_hi:[1,0,1]
	s_waitcnt vmcnt(25)
	v_fmac_f32_e32 v21, v62, v76
	v_pk_fma_f32 v[14:15], v[28:29], v[76:77], v[14:15] op_sel_hi:[1,0,1]
	v_pk_fma_f32 v[16:17], v[44:45], v[76:77], v[16:17] op_sel_hi:[1,0,1]
	s_waitcnt vmcnt(24)
	v_pk_fma_f32 v[14:15], v[38:39], v[78:79], v[14:15] op_sel_hi:[1,0,1]
	v_pk_fma_f32 v[16:17], v[54:55], v[78:79], v[16:17] op_sel_hi:[1,0,1]
	v_fmac_f32_e32 v21, v63, v78
	v_add_co_u32_e32 v24, vcc, 0xfffac000, v12
	s_nop 0
	v_addc_co_u32_e32 v25, vcc, -1, v13, vcc
	v_add_co_u32_e32 v26, vcc, 0xfffb8000, v12
	global_load_dword v64, v[24:25], off
	s_nop 0
	v_addc_co_u32_e32 v27, vcc, -1, v13, vcc
	v_add_co_u32_e32 v24, vcc, 0xfffc4000, v12
	s_nop 1
	v_addc_co_u32_e32 v25, vcc, -1, v13, vcc
	v_add_co_u32_e32 v28, vcc, 0xfffd0000, v12
	global_load_dword v66, v[26:27], off
	global_load_dword v68, v[24:25], off
	v_addc_co_u32_e32 v29, vcc, -1, v13, vcc
	v_add_co_u32_e32 v24, vcc, 0xfffdc000, v12
	s_nop 1
	v_addc_co_u32_e32 v25, vcc, -1, v13, vcc
	v_add_co_u32_e32 v26, vcc, 0xfffe8000, v12
	global_load_dword v70, v[28:29], off
	global_load_dword v72, v[24:25], off
	v_addc_co_u32_e32 v27, vcc, -1, v13, vcc
	v_add_co_u32_e32 v24, vcc, 0xffff4000, v12
	global_load_dword v74, v[26:27], off
	s_nop 0
	v_addc_co_u32_e32 v25, vcc, -1, v13, vcc
	global_load_dword v76, v[24:25], off
	global_load_dword v78, v[12:13], off
	v_lshl_add_u64 v[12:13], v[12:13], 0, s[12:13]
	ds_read_b128 v[24:27], v6
	ds_read_b128 v[28:31], v6 offset:16
	ds_read_b128 v[32:35], v6 offset:8192
	ds_read_b128 v[36:39], v6 offset:8208
	ds_read_b128 v[40:43], v6 offset:16384
	ds_read_b128 v[44:47], v6 offset:16400
	ds_read_b128 v[48:51], v6 offset:24576
	ds_read_b128 v[52:55], v6 offset:24592
	ds_read_b128 v[56:59], v6 offset:32768
	ds_read_b128 v[60:63], v6 offset:32784
	s_waitcnt lgkmcnt(9)
	v_mov_b32_e32 v80, v24
	s_waitcnt lgkmcnt(7)
	v_mov_b32_e32 v81, v32
	v_mov_b32_e32 v32, v25
	v_mov_b32_e32 v24, v26
	v_mov_b32_e32 v25, v34
	v_mov_b32_e32 v34, v27
	v_mov_b32_e32 v26, v28
	s_waitcnt lgkmcnt(6)
	v_mov_b32_e32 v27, v36
	v_mov_b32_e32 v36, v29
	v_mov_b32_e32 v28, v30
	v_mov_b32_e32 v29, v38
	v_mov_b32_e32 v38, v31
	s_waitcnt lgkmcnt(5)
	v_mov_b32_e32 v30, v40
	s_waitcnt lgkmcnt(3)
	v_mov_b32_e32 v31, v48
	v_mov_b32_e32 v48, v41
	v_mov_b32_e32 v40, v42
	v_mov_b32_e32 v41, v50
	v_mov_b32_e32 v50, v43
	v_mov_b32_e32 v42, v44
	s_waitcnt lgkmcnt(2)
	v_mov_b32_e32 v43, v52
	v_mov_b32_e32 v52, v45
	v_mov_b32_e32 v44, v46
	v_mov_b32_e32 v45, v54
	v_mov_b32_e32 v54, v47
	v_add_u32_e32 v6, 32, v6
	s_waitcnt vmcnt(31)
	v_pk_fma_f32 v[14:15], v[80:81], v[96:97], v[14:15] op_sel_hi:[1,0,1]
	v_pk_fma_f32 v[16:17], v[30:31], v[96:97], v[16:17] op_sel_hi:[1,0,1]
	s_waitcnt lgkmcnt(1)
	v_fmac_f32_e32 v21, v56, v96
	s_waitcnt vmcnt(30)
	v_fmac_f32_e32 v21, v57, v98
	v_pk_fma_f32 v[14:15], v[32:33], v[98:99], v[14:15] op_sel_hi:[1,0,1]
	v_pk_fma_f32 v[16:17], v[48:49], v[98:99], v[16:17] op_sel_hi:[1,0,1]
	s_waitcnt vmcnt(29)
	v_fmac_f32_e32 v21, v58, v100
	v_pk_fma_f32 v[14:15], v[24:25], v[100:101], v[14:15] op_sel_hi:[1,0,1]
	v_pk_fma_f32 v[16:17], v[40:41], v[100:101], v[16:17] op_sel_hi:[1,0,1]
	s_waitcnt vmcnt(28)
	v_fmac_f32_e32 v21, v59, v102
	v_pk_fma_f32 v[14:15], v[34:35], v[102:103], v[14:15] op_sel_hi:[1,0,1]
	v_pk_fma_f32 v[16:17], v[50:51], v[102:103], v[16:17] op_sel_hi:[1,0,1]
	s_waitcnt vmcnt(27) lgkmcnt(0)
	v_fmac_f32_e32 v21, v60, v104
	v_pk_fma_f32 v[14:15], v[26:27], v[104:105], v[14:15] op_sel_hi:[1,0,1]
	v_pk_fma_f32 v[16:17], v[42:43], v[104:105], v[16:17] op_sel_hi:[1,0,1]
	s_waitcnt vmcnt(26)
	v_fmac_f32_e32 v21, v61, v106
	v_pk_fma_f32 v[14:15], v[36:37], v[106:107], v[14:15] op_sel_hi:[1,0,1]
	v_pk_fma_f32 v[16:17], v[52:53], v[106:107], v[16:17] op_sel_hi:[1,0,1]
	s_waitcnt vmcnt(25)
	v_fmac_f32_e32 v21, v62, v108
	v_pk_fma_f32 v[14:15], v[28:29], v[108:109], v[14:15] op_sel_hi:[1,0,1]
	v_pk_fma_f32 v[16:17], v[44:45], v[108:109], v[16:17] op_sel_hi:[1,0,1]
	s_waitcnt vmcnt(24)
	v_pk_fma_f32 v[14:15], v[38:39], v[110:111], v[14:15] op_sel_hi:[1,0,1]
	v_pk_fma_f32 v[16:17], v[54:55], v[110:111], v[16:17] op_sel_hi:[1,0,1]
	v_fmac_f32_e32 v21, v63, v110
	v_add_co_u32_e32 v24, vcc, 0xfffac000, v12
	s_nop 0
	v_addc_co_u32_e32 v25, vcc, -1, v13, vcc
	v_add_co_u32_e32 v26, vcc, 0xfffb8000, v12
	global_load_dword v96, v[24:25], off
	s_nop 0
	v_addc_co_u32_e32 v27, vcc, -1, v13, vcc
	v_add_co_u32_e32 v24, vcc, 0xfffc4000, v12
	s_nop 1
	v_addc_co_u32_e32 v25, vcc, -1, v13, vcc
	v_add_co_u32_e32 v28, vcc, 0xfffd0000, v12
	global_load_dword v98, v[26:27], off
	global_load_dword v100, v[24:25], off
	v_addc_co_u32_e32 v29, vcc, -1, v13, vcc
	v_add_co_u32_e32 v24, vcc, 0xfffdc000, v12
	s_nop 1
	v_addc_co_u32_e32 v25, vcc, -1, v13, vcc
	v_add_co_u32_e32 v26, vcc, 0xfffe8000, v12
	global_load_dword v102, v[28:29], off
	global_load_dword v104, v[24:25], off
	v_addc_co_u32_e32 v27, vcc, -1, v13, vcc
	v_add_co_u32_e32 v24, vcc, 0xffff4000, v12
	global_load_dword v106, v[26:27], off
	s_nop 0
	v_addc_co_u32_e32 v25, vcc, -1, v13, vcc
	global_load_dword v108, v[24:25], off
	global_load_dword v110, v[12:13], off
	v_lshl_add_u64 v[12:13], v[12:13], 0, s[12:13]
	ds_read_b128 v[24:27], v6
	ds_read_b128 v[28:31], v6 offset:16
	ds_read_b128 v[32:35], v6 offset:8192
	ds_read_b128 v[36:39], v6 offset:8208
	ds_read_b128 v[40:43], v6 offset:16384
	ds_read_b128 v[44:47], v6 offset:16400
	ds_read_b128 v[48:51], v6 offset:24576
	ds_read_b128 v[52:55], v6 offset:24592
	ds_read_b128 v[56:59], v6 offset:32768
	ds_read_b128 v[60:63], v6 offset:32784
	s_waitcnt lgkmcnt(9)
	v_mov_b32_e32 v80, v24
	s_waitcnt lgkmcnt(7)
	v_mov_b32_e32 v81, v32
	v_mov_b32_e32 v32, v25
	v_mov_b32_e32 v24, v26
	v_mov_b32_e32 v25, v34
	v_mov_b32_e32 v34, v27
	v_mov_b32_e32 v26, v28
	s_waitcnt lgkmcnt(6)
	v_mov_b32_e32 v27, v36
	v_mov_b32_e32 v36, v29
	v_mov_b32_e32 v28, v30
	v_mov_b32_e32 v29, v38
	v_mov_b32_e32 v38, v31
	s_waitcnt lgkmcnt(5)
	v_mov_b32_e32 v30, v40
	s_waitcnt lgkmcnt(3)
	v_mov_b32_e32 v31, v48
	v_mov_b32_e32 v48, v41
	v_mov_b32_e32 v40, v42
	v_mov_b32_e32 v41, v50
	v_mov_b32_e32 v50, v43
	v_mov_b32_e32 v42, v44
	s_waitcnt lgkmcnt(2)
	v_mov_b32_e32 v43, v52
	v_mov_b32_e32 v52, v45
	v_mov_b32_e32 v44, v46
	v_mov_b32_e32 v45, v54
	v_mov_b32_e32 v54, v47
	v_add_u32_e32 v6, 32, v6
	s_waitcnt vmcnt(31)
	v_pk_fma_f32 v[14:15], v[80:81], v[112:113], v[14:15] op_sel_hi:[1,0,1]
	v_pk_fma_f32 v[16:17], v[30:31], v[112:113], v[16:17] op_sel_hi:[1,0,1]
	s_waitcnt lgkmcnt(1)
	v_fmac_f32_e32 v21, v56, v112
	s_waitcnt vmcnt(30)
	v_fmac_f32_e32 v21, v57, v114
	v_pk_fma_f32 v[14:15], v[32:33], v[114:115], v[14:15] op_sel_hi:[1,0,1]
	v_pk_fma_f32 v[16:17], v[48:49], v[114:115], v[16:17] op_sel_hi:[1,0,1]
	s_waitcnt vmcnt(29)
	v_fmac_f32_e32 v21, v58, v116
	v_pk_fma_f32 v[14:15], v[24:25], v[116:117], v[14:15] op_sel_hi:[1,0,1]
	v_pk_fma_f32 v[16:17], v[40:41], v[116:117], v[16:17] op_sel_hi:[1,0,1]
	s_waitcnt vmcnt(28)
	v_fmac_f32_e32 v21, v59, v118
	v_pk_fma_f32 v[14:15], v[34:35], v[118:119], v[14:15] op_sel_hi:[1,0,1]
	v_pk_fma_f32 v[16:17], v[50:51], v[118:119], v[16:17] op_sel_hi:[1,0,1]
	s_waitcnt vmcnt(27) lgkmcnt(0)
	v_fmac_f32_e32 v21, v60, v120
	v_pk_fma_f32 v[14:15], v[26:27], v[120:121], v[14:15] op_sel_hi:[1,0,1]
	v_pk_fma_f32 v[16:17], v[42:43], v[120:121], v[16:17] op_sel_hi:[1,0,1]
	s_waitcnt vmcnt(26)
	v_fmac_f32_e32 v21, v61, v122
	v_pk_fma_f32 v[14:15], v[36:37], v[122:123], v[14:15] op_sel_hi:[1,0,1]
	v_pk_fma_f32 v[16:17], v[52:53], v[122:123], v[16:17] op_sel_hi:[1,0,1]
	s_waitcnt vmcnt(25)
	v_fmac_f32_e32 v21, v62, v124
	v_pk_fma_f32 v[14:15], v[28:29], v[124:125], v[14:15] op_sel_hi:[1,0,1]
	v_pk_fma_f32 v[16:17], v[44:45], v[124:125], v[16:17] op_sel_hi:[1,0,1]
	s_waitcnt vmcnt(24)
	v_pk_fma_f32 v[14:15], v[38:39], v[126:127], v[14:15] op_sel_hi:[1,0,1]
	v_pk_fma_f32 v[16:17], v[54:55], v[126:127], v[16:17] op_sel_hi:[1,0,1]
	v_fmac_f32_e32 v21, v63, v126
	v_add_co_u32_e32 v24, vcc, 0xfffac000, v12
	s_nop 0
	v_addc_co_u32_e32 v25, vcc, -1, v13, vcc
	v_add_co_u32_e32 v26, vcc, 0xfffb8000, v12
	global_load_dword v112, v[24:25], off
	s_nop 0
	v_addc_co_u32_e32 v27, vcc, -1, v13, vcc
	v_add_co_u32_e32 v24, vcc, 0xfffc4000, v12
	s_nop 1
	v_addc_co_u32_e32 v25, vcc, -1, v13, vcc
	v_add_co_u32_e32 v28, vcc, 0xfffd0000, v12
	global_load_dword v114, v[26:27], off
	global_load_dword v116, v[24:25], off
	v_addc_co_u32_e32 v29, vcc, -1, v13, vcc
	v_add_co_u32_e32 v24, vcc, 0xfffdc000, v12
	s_nop 1
	v_addc_co_u32_e32 v25, vcc, -1, v13, vcc
	v_add_co_u32_e32 v26, vcc, 0xfffe8000, v12
	global_load_dword v118, v[28:29], off
	global_load_dword v120, v[24:25], off
	v_addc_co_u32_e32 v27, vcc, -1, v13, vcc
	v_add_co_u32_e32 v24, vcc, 0xffff4000, v12
	global_load_dword v122, v[26:27], off
	s_nop 0
	v_addc_co_u32_e32 v25, vcc, -1, v13, vcc
	global_load_dword v124, v[24:25], off
	global_load_dword v126, v[12:13], off
	v_lshl_add_u64 v[12:13], v[12:13], 0, s[12:13]
	ds_read_b128 v[24:27], v6
	ds_read_b128 v[28:31], v6 offset:16
	ds_read_b128 v[32:35], v6 offset:8192
	ds_read_b128 v[36:39], v6 offset:8208
	ds_read_b128 v[40:43], v6 offset:16384
	ds_read_b128 v[44:47], v6 offset:16400
	ds_read_b128 v[48:51], v6 offset:24576
	ds_read_b128 v[52:55], v6 offset:24592
	ds_read_b128 v[56:59], v6 offset:32768
	ds_read_b128 v[60:63], v6 offset:32784
	s_waitcnt lgkmcnt(9)
	v_mov_b32_e32 v80, v24
	s_waitcnt lgkmcnt(7)
	v_mov_b32_e32 v81, v32
	v_mov_b32_e32 v32, v25
	v_mov_b32_e32 v24, v26
	v_mov_b32_e32 v25, v34
	v_mov_b32_e32 v34, v27
	v_mov_b32_e32 v26, v28
	s_waitcnt lgkmcnt(6)
	v_mov_b32_e32 v27, v36
	v_mov_b32_e32 v36, v29
	v_mov_b32_e32 v28, v30
	v_mov_b32_e32 v29, v38
	v_mov_b32_e32 v38, v31
	s_waitcnt lgkmcnt(5)
	v_mov_b32_e32 v30, v40
	s_waitcnt lgkmcnt(3)
	v_mov_b32_e32 v31, v48
	v_mov_b32_e32 v48, v41
	v_mov_b32_e32 v40, v42
	v_mov_b32_e32 v41, v50
	v_mov_b32_e32 v50, v43
	v_mov_b32_e32 v42, v44
	s_waitcnt lgkmcnt(2)
	v_mov_b32_e32 v43, v52
	v_mov_b32_e32 v52, v45
	v_mov_b32_e32 v44, v46
	v_mov_b32_e32 v45, v54
	v_mov_b32_e32 v54, v47
	v_add_u32_e32 v6, 32, v6
	s_waitcnt vmcnt(31)
	v_pk_fma_f32 v[14:15], v[80:81], v[128:129], v[14:15] op_sel_hi:[1,0,1]
	v_pk_fma_f32 v[16:17], v[30:31], v[128:129], v[16:17] op_sel_hi:[1,0,1]
	s_waitcnt lgkmcnt(1)
	v_fmac_f32_e32 v21, v56, v128
	s_waitcnt vmcnt(30)
	v_fmac_f32_e32 v21, v57, v130
	v_pk_fma_f32 v[14:15], v[32:33], v[130:131], v[14:15] op_sel_hi:[1,0,1]
	v_pk_fma_f32 v[16:17], v[48:49], v[130:131], v[16:17] op_sel_hi:[1,0,1]
	s_waitcnt vmcnt(29)
	v_fmac_f32_e32 v21, v58, v132
	v_pk_fma_f32 v[14:15], v[24:25], v[132:133], v[14:15] op_sel_hi:[1,0,1]
	v_pk_fma_f32 v[16:17], v[40:41], v[132:133], v[16:17] op_sel_hi:[1,0,1]
	s_waitcnt vmcnt(28)
	v_fmac_f32_e32 v21, v59, v134
	v_pk_fma_f32 v[14:15], v[34:35], v[134:135], v[14:15] op_sel_hi:[1,0,1]
	v_pk_fma_f32 v[16:17], v[50:51], v[134:135], v[16:17] op_sel_hi:[1,0,1]
	s_waitcnt vmcnt(27) lgkmcnt(0)
	v_fmac_f32_e32 v21, v60, v136
	v_pk_fma_f32 v[14:15], v[26:27], v[136:137], v[14:15] op_sel_hi:[1,0,1]
	v_pk_fma_f32 v[16:17], v[42:43], v[136:137], v[16:17] op_sel_hi:[1,0,1]
	s_waitcnt vmcnt(26)
	v_fmac_f32_e32 v21, v61, v138
	v_pk_fma_f32 v[14:15], v[36:37], v[138:139], v[14:15] op_sel_hi:[1,0,1]
	v_pk_fma_f32 v[16:17], v[52:53], v[138:139], v[16:17] op_sel_hi:[1,0,1]
	s_waitcnt vmcnt(25)
	v_fmac_f32_e32 v21, v62, v140
	v_pk_fma_f32 v[14:15], v[28:29], v[140:141], v[14:15] op_sel_hi:[1,0,1]
	v_pk_fma_f32 v[16:17], v[44:45], v[140:141], v[16:17] op_sel_hi:[1,0,1]
	s_waitcnt vmcnt(24)
	v_pk_fma_f32 v[14:15], v[38:39], v[142:143], v[14:15] op_sel_hi:[1,0,1]
	v_pk_fma_f32 v[16:17], v[54:55], v[142:143], v[16:17] op_sel_hi:[1,0,1]
	v_fmac_f32_e32 v21, v63, v142
	s_sub_u32 s100, s100, 1
	s_cmp_lg_u32 s100, 0
	s_cbranch_scc1 .Lada_loop
	v_add_co_u32_e32 v24, vcc, 0xfffac000, v12
	s_nop 0
	v_addc_co_u32_e32 v25, vcc, -1, v13, vcc
	v_add_co_u32_e32 v26, vcc, 0xfffb8000, v12
	global_load_dword v128, v[24:25], off
	s_nop 0
	v_addc_co_u32_e32 v27, vcc, -1, v13, vcc
	v_add_co_u32_e32 v24, vcc, 0xfffc4000, v12
	s_nop 1
	v_addc_co_u32_e32 v25, vcc, -1, v13, vcc
	v_add_co_u32_e32 v28, vcc, 0xfffd0000, v12
	global_load_dword v130, v[26:27], off
	global_load_dword v132, v[24:25], off
	v_addc_co_u32_e32 v29, vcc, -1, v13, vcc
	v_add_co_u32_e32 v24, vcc, 0xfffdc000, v12
	s_nop 1
	v_addc_co_u32_e32 v25, vcc, -1, v13, vcc
	v_add_co_u32_e32 v26, vcc, 0xfffe8000, v12
	global_load_dword v134, v[28:29], off
	global_load_dword v136, v[24:25], off
	v_addc_co_u32_e32 v27, vcc, -1, v13, vcc
	v_add_co_u32_e32 v24, vcc, 0xffff4000, v12
	global_load_dword v138, v[26:27], off
	s_nop 0
	v_addc_co_u32_e32 v25, vcc, -1, v13, vcc
	global_load_dword v140, v[24:25], off
	global_load_dword v142, v[12:13], off
	v_lshl_add_u64 v[12:13], v[12:13], 0, s[12:13]
	ds_read_b128 v[24:27], v6
	ds_read_b128 v[28:31], v6 offset:16
	ds_read_b128 v[32:35], v6 offset:8192
	ds_read_b128 v[36:39], v6 offset:8208
	ds_read_b128 v[40:43], v6 offset:16384
	ds_read_b128 v[44:47], v6 offset:16400
	ds_read_b128 v[48:51], v6 offset:24576
	ds_read_b128 v[52:55], v6 offset:24592
	ds_read_b128 v[56:59], v6 offset:32768
	ds_read_b128 v[60:63], v6 offset:32784
	s_waitcnt lgkmcnt(9)
	v_mov_b32_e32 v80, v24
	s_waitcnt lgkmcnt(7)
	v_mov_b32_e32 v81, v32
	v_mov_b32_e32 v32, v25
	v_mov_b32_e32 v24, v26
	v_mov_b32_e32 v25, v34
	v_mov_b32_e32 v34, v27
	v_mov_b32_e32 v26, v28
	s_waitcnt lgkmcnt(6)
	v_mov_b32_e32 v27, v36
	v_mov_b32_e32 v36, v29
	v_mov_b32_e32 v28, v30
	v_mov_b32_e32 v29, v38
	v_mov_b32_e32 v38, v31
	s_waitcnt lgkmcnt(5)
	v_mov_b32_e32 v30, v40
	s_waitcnt lgkmcnt(3)
	v_mov_b32_e32 v31, v48
	v_mov_b32_e32 v48, v41
	v_mov_b32_e32 v40, v42
	v_mov_b32_e32 v41, v50
	v_mov_b32_e32 v50, v43
	v_mov_b32_e32 v42, v44
	s_waitcnt lgkmcnt(2)
	v_mov_b32_e32 v43, v52
	v_mov_b32_e32 v52, v45
	v_mov_b32_e32 v44, v46
	v_mov_b32_e32 v45, v54
	v_mov_b32_e32 v54, v47
	v_add_u32_e32 v6, 32, v6
	s_waitcnt vmcnt(31)
	v_pk_fma_f32 v[14:15], v[80:81], v[64:65], v[14:15] op_sel_hi:[1,0,1]
	v_pk_fma_f32 v[16:17], v[30:31], v[64:65], v[16:17] op_sel_hi:[1,0,1]
	s_waitcnt lgkmcnt(1)
	v_fmac_f32_e32 v21, v56, v64
	s_waitcnt vmcnt(30)
	v_fmac_f32_e32 v21, v57, v66
	v_pk_fma_f32 v[14:15], v[32:33], v[66:67], v[14:15] op_sel_hi:[1,0,1]
	v_pk_fma_f32 v[16:17], v[48:49], v[66:67], v[16:17] op_sel_hi:[1,0,1]
	s_waitcnt vmcnt(29)
	v_fmac_f32_e32 v21, v58, v68
	v_pk_fma_f32 v[14:15], v[24:25], v[68:69], v[14:15] op_sel_hi:[1,0,1]
	v_pk_fma_f32 v[16:17], v[40:41], v[68:69], v[16:17] op_sel_hi:[1,0,1]
	s_waitcnt vmcnt(28)
	v_fmac_f32_e32 v21, v59, v70
	v_pk_fma_f32 v[14:15], v[34:35], v[70:71], v[14:15] op_sel_hi:[1,0,1]
	v_pk_fma_f32 v[16:17], v[50:51], v[70:71], v[16:17] op_sel_hi:[1,0,1]
	s_waitcnt vmcnt(27) lgkmcnt(0)
	v_fmac_f32_e32 v21, v60, v72
	v_pk_fma_f32 v[14:15], v[26:27], v[72:73], v[14:15] op_sel_hi:[1,0,1]
	v_pk_fma_f32 v[16:17], v[42:43], v[72:73], v[16:17] op_sel_hi:[1,0,1]
	s_waitcnt vmcnt(26)
	v_fmac_f32_e32 v21, v61, v74
	v_pk_fma_f32 v[14:15], v[36:37], v[74:75], v[14:15] op_sel_hi:[1,0,1]
	v_pk_fma_f32 v[16:17], v[52:53], v[74:75], v[16:17] op_sel_hi:[1,0,1]
	s_waitcnt vmcnt(25)
	v_fmac_f32_e32 v21, v62, v76
	v_pk_fma_f32 v[14:15], v[28:29], v[76:77], v[14:15] op_sel_hi:[1,0,1]
	v_pk_fma_f32 v[16:17], v[44:45], v[76:77], v[16:17] op_sel_hi:[1,0,1]
	s_waitcnt vmcnt(24)
	v_pk_fma_f32 v[14:15], v[38:39], v[78:79], v[14:15] op_sel_hi:[1,0,1]
	v_pk_fma_f32 v[16:17], v[54:55], v[78:79], v[16:17] op_sel_hi:[1,0,1]
	v_fmac_f32_e32 v21, v63, v78
	ds_read_b128 v[24:27], v6
	ds_read_b128 v[28:31], v6 offset:16
	ds_read_b128 v[32:35], v6 offset:8192
	ds_read_b128 v[36:39], v6 offset:8208
	ds_read_b128 v[40:43], v6 offset:16384
	ds_read_b128 v[44:47], v6 offset:16400
	ds_read_b128 v[48:51], v6 offset:24576
	ds_read_b128 v[52:55], v6 offset:24592
	ds_read_b128 v[56:59], v6 offset:32768
	ds_read_b128 v[60:63], v6 offset:32784
	s_waitcnt lgkmcnt(9)
	v_mov_b32_e32 v80, v24
	s_waitcnt lgkmcnt(7)
	v_mov_b32_e32 v81, v32
	v_mov_b32_e32 v32, v25
	v_mov_b32_e32 v24, v26
	v_mov_b32_e32 v25, v34
	v_mov_b32_e32 v34, v27
	v_mov_b32_e32 v26, v28
	s_waitcnt lgkmcnt(6)
	v_mov_b32_e32 v27, v36
	v_mov_b32_e32 v36, v29
	v_mov_b32_e32 v28, v30
	v_mov_b32_e32 v29, v38
	v_mov_b32_e32 v38, v31
	s_waitcnt lgkmcnt(5)
	v_mov_b32_e32 v30, v40
	s_waitcnt lgkmcnt(3)
	v_mov_b32_e32 v31, v48
	v_mov_b32_e32 v48, v41
	v_mov_b32_e32 v40, v42
	v_mov_b32_e32 v41, v50
	v_mov_b32_e32 v50, v43
	v_mov_b32_e32 v42, v44
	s_waitcnt lgkmcnt(2)
	v_mov_b32_e32 v43, v52
	v_mov_b32_e32 v52, v45
	v_mov_b32_e32 v44, v46
	v_mov_b32_e32 v45, v54
	v_mov_b32_e32 v54, v47
	v_add_u32_e32 v6, 32, v6
	s_waitcnt vmcnt(23)
	v_pk_fma_f32 v[14:15], v[80:81], v[96:97], v[14:15] op_sel_hi:[1,0,1]
	v_pk_fma_f32 v[16:17], v[30:31], v[96:97], v[16:17] op_sel_hi:[1,0,1]
	s_waitcnt lgkmcnt(1)
	v_fmac_f32_e32 v21, v56, v96
	s_waitcnt vmcnt(22)
	v_fmac_f32_e32 v21, v57, v98
	v_pk_fma_f32 v[14:15], v[32:33], v[98:99], v[14:15] op_sel_hi:[1,0,1]
	v_pk_fma_f32 v[16:17], v[48:49], v[98:99], v[16:17] op_sel_hi:[1,0,1]
	s_waitcnt vmcnt(21)
	v_fmac_f32_e32 v21, v58, v100
	v_pk_fma_f32 v[14:15], v[24:25], v[100:101], v[14:15] op_sel_hi:[1,0,1]
	v_pk_fma_f32 v[16:17], v[40:41], v[100:101], v[16:17] op_sel_hi:[1,0,1]
	s_waitcnt vmcnt(20)
	v_fmac_f32_e32 v21, v59, v102
	v_pk_fma_f32 v[14:15], v[34:35], v[102:103], v[14:15] op_sel_hi:[1,0,1]
	v_pk_fma_f32 v[16:17], v[50:51], v[102:103], v[16:17] op_sel_hi:[1,0,1]
	s_waitcnt vmcnt(19) lgkmcnt(0)
	v_fmac_f32_e32 v21, v60, v104
	v_pk_fma_f32 v[14:15], v[26:27], v[104:105], v[14:15] op_sel_hi:[1,0,1]
	v_pk_fma_f32 v[16:17], v[42:43], v[104:105], v[16:17] op_sel_hi:[1,0,1]
	s_waitcnt vmcnt(18)
	v_fmac_f32_e32 v21, v61, v106
	v_pk_fma_f32 v[14:15], v[36:37], v[106:107], v[14:15] op_sel_hi:[1,0,1]
	v_pk_fma_f32 v[16:17], v[52:53], v[106:107], v[16:17] op_sel_hi:[1,0,1]
	s_waitcnt vmcnt(17)
	v_fmac_f32_e32 v21, v62, v108
	v_pk_fma_f32 v[14:15], v[28:29], v[108:109], v[14:15] op_sel_hi:[1,0,1]
	v_pk_fma_f32 v[16:17], v[44:45], v[108:109], v[16:17] op_sel_hi:[1,0,1]
	s_waitcnt vmcnt(16)
	v_pk_fma_f32 v[14:15], v[38:39], v[110:111], v[14:15] op_sel_hi:[1,0,1]
	v_pk_fma_f32 v[16:17], v[54:55], v[110:111], v[16:17] op_sel_hi:[1,0,1]
	v_fmac_f32_e32 v21, v63, v110
	ds_read_b128 v[24:27], v6
	ds_read_b128 v[28:31], v6 offset:16
	ds_read_b128 v[32:35], v6 offset:8192
	ds_read_b128 v[36:39], v6 offset:8208
	ds_read_b128 v[40:43], v6 offset:16384
	ds_read_b128 v[44:47], v6 offset:16400
	ds_read_b128 v[48:51], v6 offset:24576
	ds_read_b128 v[52:55], v6 offset:24592
	ds_read_b128 v[56:59], v6 offset:32768
	ds_read_b128 v[60:63], v6 offset:32784
	s_waitcnt lgkmcnt(9)
	v_mov_b32_e32 v80, v24
	s_waitcnt lgkmcnt(7)
	v_mov_b32_e32 v81, v32
	v_mov_b32_e32 v32, v25
	v_mov_b32_e32 v24, v26
	v_mov_b32_e32 v25, v34
	v_mov_b32_e32 v34, v27
	v_mov_b32_e32 v26, v28
	s_waitcnt lgkmcnt(6)
	v_mov_b32_e32 v27, v36
	v_mov_b32_e32 v36, v29
	v_mov_b32_e32 v28, v30
	v_mov_b32_e32 v29, v38
	v_mov_b32_e32 v38, v31
	s_waitcnt lgkmcnt(5)
	v_mov_b32_e32 v30, v40
	s_waitcnt lgkmcnt(3)
	v_mov_b32_e32 v31, v48
	v_mov_b32_e32 v48, v41
	v_mov_b32_e32 v40, v42
	v_mov_b32_e32 v41, v50
	v_mov_b32_e32 v50, v43
	v_mov_b32_e32 v42, v44
	s_waitcnt lgkmcnt(2)
	v_mov_b32_e32 v43, v52
	v_mov_b32_e32 v52, v45
	v_mov_b32_e32 v44, v46
	v_mov_b32_e32 v45, v54
	v_mov_b32_e32 v54, v47
	v_add_u32_e32 v6, 32, v6
	s_waitcnt vmcnt(15)
	v_pk_fma_f32 v[14:15], v[80:81], v[112:113], v[14:15] op_sel_hi:[1,0,1]
	v_pk_fma_f32 v[16:17], v[30:31], v[112:113], v[16:17] op_sel_hi:[1,0,1]
	s_waitcnt lgkmcnt(1)
	v_fmac_f32_e32 v21, v56, v112
	s_waitcnt vmcnt(14)
	v_fmac_f32_e32 v21, v57, v114
	v_pk_fma_f32 v[14:15], v[32:33], v[114:115], v[14:15] op_sel_hi:[1,0,1]
	v_pk_fma_f32 v[16:17], v[48:49], v[114:115], v[16:17] op_sel_hi:[1,0,1]
	s_waitcnt vmcnt(13)
	v_fmac_f32_e32 v21, v58, v116
	v_pk_fma_f32 v[14:15], v[24:25], v[116:117], v[14:15] op_sel_hi:[1,0,1]
	v_pk_fma_f32 v[16:17], v[40:41], v[116:117], v[16:17] op_sel_hi:[1,0,1]
	s_waitcnt vmcnt(12)
	v_fmac_f32_e32 v21, v59, v118
	v_pk_fma_f32 v[14:15], v[34:35], v[118:119], v[14:15] op_sel_hi:[1,0,1]
	v_pk_fma_f32 v[16:17], v[50:51], v[118:119], v[16:17] op_sel_hi:[1,0,1]
	s_waitcnt vmcnt(11) lgkmcnt(0)
	v_fmac_f32_e32 v21, v60, v120
	v_pk_fma_f32 v[14:15], v[26:27], v[120:121], v[14:15] op_sel_hi:[1,0,1]
	v_pk_fma_f32 v[16:17], v[42:43], v[120:121], v[16:17] op_sel_hi:[1,0,1]
	s_waitcnt vmcnt(10)
	v_fmac_f32_e32 v21, v61, v122
	v_pk_fma_f32 v[14:15], v[36:37], v[122:123], v[14:15] op_sel_hi:[1,0,1]
	v_pk_fma_f32 v[16:17], v[52:53], v[122:123], v[16:17] op_sel_hi:[1,0,1]
	s_waitcnt vmcnt(9)
	v_fmac_f32_e32 v21, v62, v124
	v_pk_fma_f32 v[14:15], v[28:29], v[124:125], v[14:15] op_sel_hi:[1,0,1]
	v_pk_fma_f32 v[16:17], v[44:45], v[124:125], v[16:17] op_sel_hi:[1,0,1]
	s_waitcnt vmcnt(8)
	v_pk_fma_f32 v[14:15], v[38:39], v[126:127], v[14:15] op_sel_hi:[1,0,1]
	v_pk_fma_f32 v[16:17], v[54:55], v[126:127], v[16:17] op_sel_hi:[1,0,1]
	v_fmac_f32_e32 v21, v63, v126
	ds_read_b128 v[24:27], v6
	ds_read_b128 v[28:31], v6 offset:16
	ds_read_b128 v[32:35], v6 offset:8192
	ds_read_b128 v[36:39], v6 offset:8208
	ds_read_b128 v[40:43], v6 offset:16384
	ds_read_b128 v[44:47], v6 offset:16400
	ds_read_b128 v[48:51], v6 offset:24576
	ds_read_b128 v[52:55], v6 offset:24592
	ds_read_b128 v[56:59], v6 offset:32768
	ds_read_b128 v[60:63], v6 offset:32784
	s_waitcnt lgkmcnt(9)
	v_mov_b32_e32 v80, v24
	s_waitcnt lgkmcnt(7)
	v_mov_b32_e32 v81, v32
	v_mov_b32_e32 v32, v25
	v_mov_b32_e32 v24, v26
	v_mov_b32_e32 v25, v34
	v_mov_b32_e32 v34, v27
	v_mov_b32_e32 v26, v28
	s_waitcnt lgkmcnt(6)
	v_mov_b32_e32 v27, v36
	v_mov_b32_e32 v36, v29
	v_mov_b32_e32 v28, v30
	v_mov_b32_e32 v29, v38
	v_mov_b32_e32 v38, v31
	s_waitcnt lgkmcnt(5)
	v_mov_b32_e32 v30, v40
	s_waitcnt lgkmcnt(3)
	v_mov_b32_e32 v31, v48
	v_mov_b32_e32 v48, v41
	v_mov_b32_e32 v40, v42
	v_mov_b32_e32 v41, v50
	v_mov_b32_e32 v50, v43
	v_mov_b32_e32 v42, v44
	s_waitcnt lgkmcnt(2)
	v_mov_b32_e32 v43, v52
	v_mov_b32_e32 v52, v45
	v_mov_b32_e32 v44, v46
	v_mov_b32_e32 v45, v54
	v_mov_b32_e32 v54, v47
	v_add_u32_e32 v6, 32, v6
	s_waitcnt vmcnt(7)
	v_pk_fma_f32 v[14:15], v[80:81], v[128:129], v[14:15] op_sel_hi:[1,0,1]
	v_pk_fma_f32 v[16:17], v[30:31], v[128:129], v[16:17] op_sel_hi:[1,0,1]
	s_waitcnt lgkmcnt(1)
	v_fmac_f32_e32 v21, v56, v128
	s_waitcnt vmcnt(6)
	v_fmac_f32_e32 v21, v57, v130
	v_pk_fma_f32 v[14:15], v[32:33], v[130:131], v[14:15] op_sel_hi:[1,0,1]
	v_pk_fma_f32 v[16:17], v[48:49], v[130:131], v[16:17] op_sel_hi:[1,0,1]
	s_waitcnt vmcnt(5)
	v_fmac_f32_e32 v21, v58, v132
	v_pk_fma_f32 v[14:15], v[24:25], v[132:133], v[14:15] op_sel_hi:[1,0,1]
	v_pk_fma_f32 v[16:17], v[40:41], v[132:133], v[16:17] op_sel_hi:[1,0,1]
	s_waitcnt vmcnt(4)
	v_fmac_f32_e32 v21, v59, v134
	v_pk_fma_f32 v[14:15], v[34:35], v[134:135], v[14:15] op_sel_hi:[1,0,1]
	v_pk_fma_f32 v[16:17], v[50:51], v[134:135], v[16:17] op_sel_hi:[1,0,1]
	s_waitcnt vmcnt(3) lgkmcnt(0)
	v_fmac_f32_e32 v21, v60, v136
	v_pk_fma_f32 v[14:15], v[26:27], v[136:137], v[14:15] op_sel_hi:[1,0,1]
	v_pk_fma_f32 v[16:17], v[42:43], v[136:137], v[16:17] op_sel_hi:[1,0,1]
	s_waitcnt vmcnt(2)
	v_fmac_f32_e32 v21, v61, v138
	v_pk_fma_f32 v[14:15], v[36:37], v[138:139], v[14:15] op_sel_hi:[1,0,1]
	v_pk_fma_f32 v[16:17], v[52:53], v[138:139], v[16:17] op_sel_hi:[1,0,1]
	s_waitcnt vmcnt(1)
	v_fmac_f32_e32 v21, v62, v140
	v_pk_fma_f32 v[14:15], v[28:29], v[140:141], v[14:15] op_sel_hi:[1,0,1]
	v_pk_fma_f32 v[16:17], v[44:45], v[140:141], v[16:17] op_sel_hi:[1,0,1]
	s_waitcnt vmcnt(0)
	v_pk_fma_f32 v[14:15], v[38:39], v[142:143], v[14:15] op_sel_hi:[1,0,1]
	v_pk_fma_f32 v[16:17], v[54:55], v[142:143], v[16:17] op_sel_hi:[1,0,1]
	v_fmac_f32_e32 v21, v63, v142
	s_or_b64 exec, exec, s[16:17]
	v_add_u32_e32 v6, 0xa000, v19
	ds_write2_b32 v6, v14, v15 offset1:32
	ds_write2_b32 v6, v16, v17 offset0:64 offset1:96
	ds_write_b32 v19, v21 offset:41472
	s_waitcnt lgkmcnt(0)
	s_barrier
	s_and_saveexec_b64 s[16:17], s[4:5]
	s_cbranch_execz .LBB0_98
	s_load_dwordx2 s[22:23], s[6:7], 0x28
	s_mul_i32 s21, s20, 0x3000
	s_add_i32 s21, s21, s14
	v_or_b32_e32 v12, s21, v8
	v_ashrrev_i32_e32 v13, 31, v12
	s_waitcnt lgkmcnt(0)
	v_lshl_add_u64 v[12:13], v[12:13], 2, s[22:23]
	global_load_dword v21, v[12:13], off
	v_add_u32_e32 v16, v3, v1
	v_mad_u64_u32 v[12:13], s[20:21], s20, 5, v[2:3]
	v_mov_b64_e32 v[14:15], s[10:11]
	v_add_u32_e32 v17, 0xa000, v16
	v_add_u32_e32 v22, 0xa400, v16
	v_add_u32_e32 v23, 0xaa00, v16
	v_add_u32_e32 v24, 0xae00, v16
	v_add_u32_e32 v26, 0xb400, v16
	v_add_u32_e32 v28, 0xb800, v16
	v_add_u32_e32 v30, 0xbe00, v16
	v_add_u32_e32 v32, 0xc200, v16
	v_mad_i64_i32 v[12:13], s[20:21], v12, s18, v[14:15]
	ds_read2_b32 v[14:15], v17 offset1:160
	ds_read2_b32 v[16:17], v22 offset0:64 offset1:224
	ds_read2_b32 v[22:23], v23 offset1:160
	ds_read2_b32 v[24:25], v24 offset0:64 offset1:224
	ds_read2_b32 v[26:27], v26 offset1:160
	ds_read2_b32 v[28:29], v28 offset0:64 offset1:224
	ds_read2_b32 v[30:31], v30 offset1:160
	ds_read2_b32 v[32:33], v32 offset0:64 offset1:224
	s_waitcnt lgkmcnt(7)
	v_add_f32_e32 v14, 0, v14
	v_add_f32_e32 v14, v14, v15
	s_waitcnt lgkmcnt(6)
	v_add_f32_e32 v14, v14, v16
	v_add_f32_e32 v14, v14, v17
	s_waitcnt lgkmcnt(5)
	v_add_f32_e32 v14, v14, v22
	v_add_f32_e32 v14, v14, v23
	s_waitcnt lgkmcnt(4)
	v_add_f32_e32 v14, v14, v24
	v_add_f32_e32 v14, v14, v25
	s_waitcnt lgkmcnt(3)
	v_add_f32_e32 v14, v14, v26
	v_add_f32_e32 v14, v14, v27
	s_waitcnt lgkmcnt(2)
	v_add_f32_e32 v14, v14, v28
	v_add_f32_e32 v14, v14, v29
	s_waitcnt lgkmcnt(1)
	v_add_f32_e32 v14, v14, v30
	v_add_f32_e32 v14, v14, v31
	s_waitcnt lgkmcnt(0)
	v_add_f32_e32 v14, v14, v32
	v_lshlrev_b32_e32 v6, 2, v8
	v_lshl_add_u64 v[12:13], s[14:15], 2, v[12:13]
	v_add_f32_e32 v14, v14, v33
	v_lshl_add_u64 v[12:13], v[12:13], 0, v[6:7]
	s_waitcnt vmcnt(0)
	v_add_f32_e32 v14, v14, v21
	global_store_dword v[12:13], v14, off
	s_branch .LBB0_98

.LBB0_106:
	v_mul_hi_i32 v3, v7, s38
	v_lshrrev_b32_e32 v4, 31, v3
	v_ashrrev_i32_e32 v3, 10, v3
	v_add_u32_e32 v12, v3, v4
	v_mul_i32_i24_e32 v3, 0x5b10, v12
	v_sub_u32_e32 v3, v7, v3
	v_cmp_lt_i32_e32 vcc, s39, v3
	s_and_saveexec_b64 s[24:25], vcc
	s_xor_b64 s[24:25], exec, s[24:25]
	s_cbranch_execz .LBB0_140
	v_cmp_lt_u32_e32 vcc, s40, v3
	s_and_saveexec_b64 s[26:27], vcc
	s_xor_b64 s[26:27], exec, s[26:27]
	s_cbranch_execz .LBB0_135
	v_cmp_lt_u32_e32 vcc, s41, v3
	s_and_saveexec_b64 s[28:29], vcc
	s_xor_b64 s[28:29], exec, s[28:29]
	s_cbranch_execz .LBB0_130
	v_cmp_lt_u32_e32 vcc, s42, v3
	s_and_saveexec_b64 s[30:31], vcc
	s_xor_b64 s[30:31], exec, s[30:31]
	s_cbranch_execz .LBB0_125
	v_cmp_lt_u32_e32 vcc, s43, v3
	s_and_saveexec_b64 s[34:35], vcc
	s_xor_b64 s[34:35], exec, s[34:35]
	s_cbranch_execz .LBB0_120
	v_cmp_lt_u32_e32 vcc, s44, v3
	s_and_saveexec_b64 s[36:37], vcc
	s_xor_b64 s[36:37], exec, s[36:37]
	s_cbranch_execz .LBB0_115
	s_load_dwordx2 s[58:59], s[6:7], 0x60
	v_add_u32_e32 v3, 0xffffa530, v3
	v_ashrrev_i32_e32 v13, 31, v12
	v_lshlrev_b32_e32 v4, 5, v3
	v_lshlrev_b64 v[14:15], 19, v[12:13]
	v_and_b32_e32 v11, 0x3e0, v4
	s_waitcnt lgkmcnt(0)
	v_lshl_add_u64 v[16:17], s[58:59], 0, v[14:15]
	v_lshlrev_b32_e32 v3, 1, v3
	v_lshlrev_b32_e32 v4, 2, v11
	v_and_b32_e32 v14, 0x7fffffc0, v3
	v_lshl_add_u64 v[16:17], v[16:17], 0, v[4:5]
	v_mov_b32_e32 v9, v5
	s_mov_b32 s58, 1
	v_lshl_add_u64 v[16:17], v[16:17], 0, v[8:9]
	v_mov_b32_e32 v3, v14
	s_mov_b32 s59, 0
	s_mov_b32 s60, 32
	v_mov_b32_e32 v105, v5
	s_lshl_b32 s61, s58, 1
	s_lshl_b32 s62, s59, 1
	v_or_b32_e32 v113, s62, v2
	s_add_i32 s63, s61, 4
	s_add_i32 s64, s62, 4
	s_add_i32 s66, s62, 8
	v_add_u32_e32 v104, v113, v14
	v_or_b32_e32 v115, s63, v1
	v_or_b32_e32 v129, s64, v2
	v_mov_b32_e32 v131, v5
	v_or_b32_e32 v109, s61, v1
	s_add_i32 s68, s62, 12
	v_or_b32_e32 v151, s66, v2
	v_lshlrev_b64 v[144:145], 12, v[104:105]
	v_add_u32_e32 v130, v115, v3
	v_add_u32_e32 v104, v129, v14
	v_mov_b32_e32 v119, v5
	s_add_i32 s65, s61, 8
	s_add_i32 s67, s61, 12
	s_add_i32 s70, s62, 16
	v_add_u32_e32 v118, v109, v3
	v_or_b32_e32 v153, s68, v2
	v_lshlrev_b64 v[130:131], 12, v[130:131]
	v_lshlrev_b64 v[146:147], 12, v[104:105]
	v_add_u32_e32 v104, v151, v14
	s_add_i32 s72, s62, 20
	v_or_b32_e32 v150, s65, v1
	v_or_b32_e32 v152, s67, v1
	v_or_b32_e32 v155, s70, v2
	v_lshlrev_b64 v[118:119], 12, v[118:119]
	v_lshl_add_u64 v[144:145], v[16:17], 0, v[144:145]
	v_lshl_add_u64 v[130:131], v[16:17], 0, v[130:131]
	v_lshlrev_b64 v[148:149], 12, v[104:105]
	v_add_u32_e32 v104, v153, v14
	v_mov_b32_e32 v133, v5
	v_mov_b32_e32 v135, v5
	s_add_i32 s69, s61, 16
	s_add_i32 s71, s61, 20
	s_add_i32 s74, s62, 24
	v_or_b32_e32 v157, s72, v2
	v_add_u32_e32 v132, v150, v3
	v_add_u32_e32 v134, v152, v3
	v_lshl_add_u64 v[118:119], v[16:17], 0, v[118:119]
	v_lshl_add_u64 v[146:147], v[16:17], 0, v[146:147]
	global_load_dword v162, v[144:145], off
	global_load_dword v163, v[118:119], off
	global_load_dword v164, v[146:147], off
	global_load_dword v165, v[130:131], off
	v_lshlrev_b64 v[130:131], 12, v[104:105]
	v_add_u32_e32 v104, v155, v14
	s_add_i32 s73, s61, 24
	s_add_i32 s61, s61, 28
	s_add_i32 s62, s62, 28
	v_or_b32_e32 v154, s69, v1
	v_or_b32_e32 v156, s71, v1
	v_or_b32_e32 v159, s74, v2
	v_lshlrev_b64 v[132:133], 12, v[132:133]
	v_lshlrev_b64 v[134:135], 12, v[134:135]
	v_lshl_add_u64 v[118:119], v[16:17], 0, v[148:149]
	v_lshl_add_u64 v[130:131], v[16:17], 0, v[130:131]
	v_lshlrev_b64 v[144:145], 12, v[104:105]
	v_add_u32_e32 v104, v157, v14
	v_mov_b32_e32 v137, v5
	v_mov_b32_e32 v139, v5
	v_or_b32_e32 v158, s73, v1
	v_or_b32_e32 v160, s61, v1
	v_or_b32_e32 v161, s62, v2
	v_add_u32_e32 v136, v154, v3
	v_add_u32_e32 v138, v156, v3
	v_lshl_add_u64 v[132:133], v[16:17], 0, v[132:133]
	v_lshl_add_u64 v[134:135], v[16:17], 0, v[134:135]
	global_load_dword v166, v[118:119], off
	global_load_dword v167, v[132:133], off
	global_load_dword v168, v[130:131], off
	global_load_dword v169, v[134:135], off
	v_lshlrev_b64 v[130:131], 12, v[104:105]
	v_add_u32_e32 v104, v159, v14
	v_mov_b32_e32 v141, v5
	v_mov_b32_e32 v143, v5
	v_add_u32_e32 v140, v158, v3
	v_add_u32_e32 v142, v160, v3
	v_lshlrev_b64 v[136:137], 12, v[136:137]
	v_lshlrev_b64 v[138:139], 12, v[138:139]
	v_lshl_add_u64 v[118:119], v[16:17], 0, v[144:145]
	v_lshl_add_u64 v[130:131], v[16:17], 0, v[130:131]
	v_lshlrev_b64 v[132:133], 12, v[104:105]
	v_add_u32_e32 v104, v161, v14
	v_lshlrev_b64 v[140:141], 12, v[140:141]
	v_lshlrev_b64 v[142:143], 12, v[142:143]
	v_lshl_add_u64 v[136:137], v[16:17], 0, v[136:137]
	v_lshl_add_u64 v[138:139], v[16:17], 0, v[138:139]
	global_load_dword v170, v[118:119], off
	global_load_dword v171, v[136:137], off
	global_load_dword v172, v[130:131], off
	global_load_dword v173, v[138:139], off
	v_lshl_add_u64 v[118:119], v[16:17], 0, v[132:133]
	v_lshlrev_b64 v[130:131], 12, v[104:105]
	v_lshl_add_u64 v[140:141], v[16:17], 0, v[140:141]
	v_lshl_add_u64 v[142:143], v[16:17], 0, v[142:143]
	v_lshl_add_u64 v[130:131], v[16:17], 0, v[130:131]
	global_load_dword v104, v[118:119], off
	global_load_dword v174, v[140:141], off
	global_load_dword v175, v[130:131], off
	global_load_dword v176, v[142:143], off
	s_add_i32 s59, s59, 16
	s_add_i32 s58, s58, 16
	s_add_i32 s60, s60, -16
	v_mad_u64_u32 v[118:119], s[62:63], v113, s33, v[6:7]
	v_mad_u64_u32 v[130:131], s[62:63], v109, s33, v[6:7]
	v_mad_u64_u32 v[132:133], s[62:63], v129, s33, v[6:7]
	v_mad_u64_u32 v[134:135], s[62:63], v115, s33, v[6:7]
	v_mad_u64_u32 v[136:137], s[62:63], v151, s33, v[6:7]
	v_mad_u64_u32 v[138:139], s[62:63], v150, s33, v[6:7]
	v_mad_u64_u32 v[140:141], s[62:63], v153, s33, v[6:7]
	v_mad_u64_u32 v[142:143], s[62:63], v152, s33, v[6:7]
	v_mad_u64_u32 v[144:145], s[62:63], v155, s33, v[6:7]
	v_mad_u64_u32 v[146:147], s[62:63], v154, s33, v[6:7]
	v_mad_u64_u32 v[148:149], s[62:63], v157, s33, v[6:7]
	v_mad_u64_u32 v[150:151], s[62:63], v156, s33, v[6:7]
	v_mad_u64_u32 v[152:153], s[62:63], v159, s33, v[6:7]
	v_mad_u64_u32 v[154:155], s[62:63], v158, s33, v[6:7]
	v_mad_u64_u32 v[156:157], s[62:63], v161, s33, v[6:7]
	v_mad_u64_u32 v[158:159], s[62:63], v160, s33, v[6:7]
	s_lshl_b32 s61, s58, 1
	s_lshl_b32 s62, s59, 1
	v_or_b32_e32 v13, s62, v2
	s_add_i32 s63, s61, 4
	s_add_i32 s64, s62, 4
	s_add_i32 s66, s62, 8
	v_add_u32_e32 v4, v13, v14
	v_or_b32_e32 v15, s63, v1
	v_or_b32_e32 v29, s64, v2
	v_mov_b32_e32 v31, v5
	v_or_b32_e32 v9, s61, v1
	s_add_i32 s68, s62, 12
	v_or_b32_e32 v51, s66, v2
	v_lshlrev_b64 v[44:45], 12, v[4:5]
	v_add_u32_e32 v30, v15, v3
	v_add_u32_e32 v4, v29, v14
	v_mov_b32_e32 v19, v5
	s_add_i32 s65, s61, 8
	s_add_i32 s67, s61, 12
	s_add_i32 s70, s62, 16
	v_add_u32_e32 v18, v9, v3
	v_or_b32_e32 v53, s68, v2
	v_lshlrev_b64 v[30:31], 12, v[30:31]
	v_lshlrev_b64 v[46:47], 12, v[4:5]
	v_add_u32_e32 v4, v51, v14
	s_add_i32 s72, s62, 20
	v_or_b32_e32 v50, s65, v1
	v_or_b32_e32 v52, s67, v1
	v_or_b32_e32 v55, s70, v2
	v_lshlrev_b64 v[18:19], 12, v[18:19]
	v_lshl_add_u64 v[44:45], v[16:17], 0, v[44:45]
	v_lshl_add_u64 v[30:31], v[16:17], 0, v[30:31]
	v_lshlrev_b64 v[48:49], 12, v[4:5]
	v_add_u32_e32 v4, v53, v14
	v_mov_b32_e32 v33, v5
	v_mov_b32_e32 v35, v5
	s_add_i32 s69, s61, 16
	s_add_i32 s71, s61, 20
	s_add_i32 s74, s62, 24
	v_or_b32_e32 v57, s72, v2
	v_add_u32_e32 v32, v50, v3
	v_add_u32_e32 v34, v52, v3
	v_lshl_add_u64 v[18:19], v[16:17], 0, v[18:19]
	v_lshl_add_u64 v[46:47], v[16:17], 0, v[46:47]
	global_load_dword v62, v[44:45], off
	global_load_dword v63, v[18:19], off
	global_load_dword v64, v[46:47], off
	global_load_dword v65, v[30:31], off
	v_lshlrev_b64 v[30:31], 12, v[4:5]
	v_add_u32_e32 v4, v55, v14
	s_add_i32 s73, s61, 24
	s_add_i32 s61, s61, 28
	s_add_i32 s62, s62, 28
	v_or_b32_e32 v54, s69, v1
	v_or_b32_e32 v56, s71, v1
	v_or_b32_e32 v59, s74, v2
	v_lshlrev_b64 v[32:33], 12, v[32:33]
	v_lshlrev_b64 v[34:35], 12, v[34:35]
	v_lshl_add_u64 v[18:19], v[16:17], 0, v[48:49]
	v_lshl_add_u64 v[30:31], v[16:17], 0, v[30:31]
	v_lshlrev_b64 v[44:45], 12, v[4:5]
	v_add_u32_e32 v4, v57, v14
	v_mov_b32_e32 v37, v5
	v_mov_b32_e32 v39, v5
	v_or_b32_e32 v58, s73, v1
	v_or_b32_e32 v60, s61, v1
	v_or_b32_e32 v61, s62, v2
	v_add_u32_e32 v36, v54, v3
	v_add_u32_e32 v38, v56, v3
	v_lshl_add_u64 v[32:33], v[16:17], 0, v[32:33]
	v_lshl_add_u64 v[34:35], v[16:17], 0, v[34:35]
	global_load_dword v66, v[18:19], off
	global_load_dword v67, v[32:33], off
	global_load_dword v68, v[30:31], off
	global_load_dword v69, v[34:35], off
	v_lshlrev_b64 v[30:31], 12, v[4:5]
	v_add_u32_e32 v4, v59, v14
	v_mov_b32_e32 v41, v5
	v_mov_b32_e32 v43, v5
	v_add_u32_e32 v40, v58, v3
	v_add_u32_e32 v42, v60, v3
	v_lshlrev_b64 v[36:37], 12, v[36:37]
	v_lshlrev_b64 v[38:39], 12, v[38:39]
	v_lshl_add_u64 v[18:19], v[16:17], 0, v[44:45]
	v_lshl_add_u64 v[30:31], v[16:17], 0, v[30:31]
	v_lshlrev_b64 v[32:33], 12, v[4:5]
	v_add_u32_e32 v4, v61, v14
	v_lshlrev_b64 v[40:41], 12, v[40:41]
	v_lshlrev_b64 v[42:43], 12, v[42:43]
	v_lshl_add_u64 v[36:37], v[16:17], 0, v[36:37]
	v_lshl_add_u64 v[38:39], v[16:17], 0, v[38:39]
	global_load_dword v70, v[18:19], off
	global_load_dword v71, v[36:37], off
	global_load_dword v72, v[30:31], off
	global_load_dword v73, v[38:39], off
	v_lshl_add_u64 v[18:19], v[16:17], 0, v[32:33]
	v_lshlrev_b64 v[30:31], 12, v[4:5]
	v_lshl_add_u64 v[40:41], v[16:17], 0, v[40:41]
	v_lshl_add_u64 v[42:43], v[16:17], 0, v[42:43]
	v_lshl_add_u64 v[30:31], v[16:17], 0, v[30:31]
	global_load_dword v4, v[18:19], off
	global_load_dword v74, v[40:41], off
	global_load_dword v75, v[30:31], off
	global_load_dword v76, v[42:43], off
	s_add_i32 s59, s59, 16
	s_add_i32 s58, s58, 16
	s_add_i32 s60, s60, -16
	v_mad_u64_u32 v[18:19], s[62:63], v13, s33, v[6:7]
	v_mad_u64_u32 v[30:31], s[62:63], v9, s33, v[6:7]
	v_mad_u64_u32 v[32:33], s[62:63], v29, s33, v[6:7]
	v_mad_u64_u32 v[34:35], s[62:63], v15, s33, v[6:7]
	v_mad_u64_u32 v[36:37], s[62:63], v51, s33, v[6:7]
	v_mad_u64_u32 v[38:39], s[62:63], v50, s33, v[6:7]
	v_mad_u64_u32 v[40:41], s[62:63], v53, s33, v[6:7]
	v_mad_u64_u32 v[42:43], s[62:63], v52, s33, v[6:7]
	v_mad_u64_u32 v[44:45], s[62:63], v55, s33, v[6:7]
	v_mad_u64_u32 v[46:47], s[62:63], v54, s33, v[6:7]
	v_mad_u64_u32 v[48:49], s[62:63], v57, s33, v[6:7]
	v_mad_u64_u32 v[50:51], s[62:63], v56, s33, v[6:7]
	v_mad_u64_u32 v[52:53], s[62:63], v59, s33, v[6:7]
	v_mad_u64_u32 v[54:55], s[62:63], v58, s33, v[6:7]
	v_mad_u64_u32 v[56:57], s[62:63], v61, s33, v[6:7]
	v_mad_u64_u32 v[58:59], s[62:63], v60, s33, v[6:7]
	s_waitcnt vmcnt(31)
	ds_write_b32 v118, v162
	s_waitcnt vmcnt(30)
	ds_write_b32 v130, v163
	s_waitcnt vmcnt(29)
	ds_write_b32 v132, v164
	s_waitcnt vmcnt(28)
	ds_write_b32 v134, v165
	s_waitcnt vmcnt(27)
	ds_write_b32 v136, v166
	s_waitcnt vmcnt(26)
	ds_write_b32 v138, v167
	s_waitcnt vmcnt(25)
	ds_write_b32 v140, v168
	s_waitcnt vmcnt(24)
	ds_write_b32 v142, v169
	s_waitcnt vmcnt(23)
	ds_write_b32 v144, v170
	s_waitcnt vmcnt(22)
	ds_write_b32 v146, v171
	s_waitcnt vmcnt(21)
	ds_write_b32 v148, v172
	s_waitcnt vmcnt(20)
	ds_write_b32 v150, v173
	s_waitcnt vmcnt(19)
	ds_write_b32 v152, v104
	s_waitcnt vmcnt(18)
	ds_write_b32 v154, v174
	s_waitcnt vmcnt(17)
	ds_write_b32 v156, v175
	s_waitcnt vmcnt(16)
	ds_write_b32 v158, v176
	s_waitcnt vmcnt(15)
	ds_write_b32 v18, v62
	s_waitcnt vmcnt(14)
	ds_write_b32 v30, v63
	s_waitcnt vmcnt(13)
	ds_write_b32 v32, v64
	s_waitcnt vmcnt(12)
	ds_write_b32 v34, v65
	s_waitcnt vmcnt(11)
	ds_write_b32 v36, v66
	s_waitcnt vmcnt(10)
	ds_write_b32 v38, v67
	s_waitcnt vmcnt(9)
	ds_write_b32 v40, v68
	s_waitcnt vmcnt(8)
	ds_write_b32 v42, v69
	s_waitcnt vmcnt(7)
	ds_write_b32 v44, v70
	s_waitcnt vmcnt(6)
	ds_write_b32 v46, v71
	s_waitcnt vmcnt(5)
	ds_write_b32 v48, v72
	s_waitcnt vmcnt(4)
	ds_write_b32 v50, v73
	s_waitcnt vmcnt(3)
	ds_write_b32 v52, v4
	s_waitcnt vmcnt(2)
	ds_write_b32 v54, v74
	s_waitcnt vmcnt(1)
	ds_write_b32 v56, v75
	s_waitcnt vmcnt(0)
	ds_write_b32 v58, v76
	s_waitcnt lgkmcnt(0)
	ds_read2_b32 v[16:17], v22 offset1:8
	ds_read2_b32 v[30:31], v22 offset0:33 offset1:41
	v_mul_hi_i32_i24_e32 v13, 0x1c0000, v12
	v_mul_i32_i24_e32 v12, 0x1c0000, v12
	ds_read2_b32 v[32:33], v22 offset0:66 offset1:74
	v_lshl_add_u64 v[12:13], s[8:9], 0, v[12:13]
	v_lshlrev_b32_e32 v4, 1, v14
	ds_read2_b32 v[34:35], v22 offset0:99 offset1:107
	v_lshl_add_u64 v[12:13], v[12:13], 0, v[4:5]
	s_waitcnt lgkmcnt(3)
	v_bfe_u32 v4, v16, 16, 1
	v_add_u32_e32 v3, 0x300, v11
	v_mov_b32_e32 v11, v5
	v_add3_u32 v4, v16, v4, s45
	s_waitcnt lgkmcnt(2)
	v_bfe_u32 v9, v30, 16, 1
	ds_read2_b32 v[36:37], v22 offset0:132 offset1:140
	v_lshl_add_u64 v[12:13], v[12:13], 0, v[10:11]
	v_lshrrev_b32_e32 v4, 16, v4
	v_add3_u32 v9, v30, v9, s45
	ds_read2_b32 v[38:39], v22 offset0:165 offset1:173
	v_lshl_add_u64 v[18:19], v[12:13], 0, s[22:23]
	v_and_or_b32 v12, v9, s46, v4
	s_waitcnt lgkmcnt(3)
	v_bfe_u32 v4, v32, 16, 1
	v_add3_u32 v4, v32, v4, s45
	s_waitcnt lgkmcnt(2)
	v_bfe_u32 v9, v34, 16, 1
	ds_read2_b32 v[40:41], v22 offset0:198 offset1:206
	v_lshrrev_b32_e32 v4, 16, v4
	v_add3_u32 v9, v34, v9, s45
	ds_read2_b32 v[42:43], v22 offset0:231 offset1:239
	v_and_or_b32 v13, v9, s46, v4
	s_waitcnt lgkmcnt(3)
	v_bfe_u32 v4, v36, 16, 1
	v_add3_u32 v4, v36, v4, s45
	s_waitcnt lgkmcnt(2)
	v_bfe_u32 v9, v38, 16, 1
	v_lshrrev_b32_e32 v4, 16, v4
	v_add3_u32 v9, v38, v9, s45
	v_and_or_b32 v14, v9, s46, v4
	s_waitcnt lgkmcnt(1)
	v_bfe_u32 v4, v40, 16, 1
	v_add3_u32 v4, v40, v4, s45
	s_waitcnt lgkmcnt(0)
	v_bfe_u32 v9, v42, 16, 1
	v_lshrrev_b32_e32 v4, 16, v4
	v_add3_u32 v9, v42, v9, s45
	v_and_or_b32 v15, v9, s46, v4
	v_or_b32_e32 v4, v3, v21
	v_lshlrev_b32_e32 v4, 10, v4
	v_lshl_add_u64 v[44:45], v[18:19], 0, v[4:5]
	v_bfe_u32 v4, v17, 16, 1
	v_add3_u32 v4, v17, v4, s45
	v_bfe_u32 v9, v31, 16, 1
	v_lshrrev_b32_e32 v4, 16, v4
	v_add3_u32 v9, v31, v9, s45
	global_store_dwordx4 v[44:45], v[12:15], off
	ds_read2_b32 v[16:17], v22 offset0:16 offset1:24
	v_readlane_b32 s66, v253, 1
	v_and_or_b32 v12, v9, s46, v4
	v_bfe_u32 v4, v33, 16, 1
	v_add3_u32 v4, v33, v4, s45
	v_bfe_u32 v9, v35, 16, 1
	v_lshrrev_b32_e32 v4, 16, v4
	v_add3_u32 v9, v35, v9, s45
	v_and_or_b32 v13, v9, s46, v4
	v_bfe_u32 v4, v37, 16, 1
	v_add3_u32 v4, v37, v4, s45
	v_bfe_u32 v9, v39, 16, 1
	v_lshrrev_b32_e32 v4, 16, v4
	v_add3_u32 v9, v39, v9, s45
	v_and_or_b32 v14, v9, s46, v4
	v_bfe_u32 v4, v41, 16, 1
	v_add3_u32 v4, v41, v4, s45
	v_bfe_u32 v9, v43, 16, 1
	v_lshrrev_b32_e32 v4, 16, v4
	v_add3_u32 v9, v43, v9, s45
	v_and_or_b32 v15, v9, s46, v4
	v_or_b32_e32 v4, v3, v23
	v_lshlrev_b32_e32 v4, 10, v4
	v_lshl_add_u64 v[30:31], v[18:19], 0, v[4:5]
	global_store_dwordx4 v[30:31], v[12:15], off
	ds_read2_b32 v[30:31], v22 offset0:49 offset1:57
	ds_read2_b32 v[32:33], v22 offset0:82 offset1:90
	ds_read2_b32 v[34:35], v22 offset0:115 offset1:123
	s_waitcnt lgkmcnt(3)
	v_bfe_u32 v4, v16, 16, 1
	v_add3_u32 v4, v16, v4, s45
	s_waitcnt lgkmcnt(2)
	v_bfe_u32 v9, v30, 16, 1
	ds_read2_b32 v[36:37], v22 offset0:148 offset1:156
	v_lshrrev_b32_e32 v4, 16, v4
	v_add3_u32 v9, v30, v9, s45
	ds_read2_b32 v[38:39], v22 offset0:181 offset1:189
	v_and_or_b32 v12, v9, s46, v4
	s_waitcnt lgkmcnt(3)
	v_bfe_u32 v4, v32, 16, 1
	v_add3_u32 v4, v32, v4, s45
	s_waitcnt lgkmcnt(2)
	v_bfe_u32 v9, v34, 16, 1
	ds_read2_b32 v[40:41], v22 offset0:214 offset1:222
	v_lshrrev_b32_e32 v4, 16, v4
	v_add3_u32 v9, v34, v9, s45
	ds_read2_b32 v[42:43], v22 offset0:247 offset1:255
	v_and_or_b32 v13, v9, s46, v4
	s_waitcnt lgkmcnt(3)
	v_bfe_u32 v4, v36, 16, 1
	v_add3_u32 v4, v36, v4, s45
	s_waitcnt lgkmcnt(2)
	v_bfe_u32 v9, v38, 16, 1
	v_lshrrev_b32_e32 v4, 16, v4
	v_add3_u32 v9, v38, v9, s45
	v_and_or_b32 v14, v9, s46, v4
	s_waitcnt lgkmcnt(1)
	v_bfe_u32 v4, v40, 16, 1
	v_add3_u32 v4, v40, v4, s45
	s_waitcnt lgkmcnt(0)
	v_bfe_u32 v9, v42, 16, 1
	v_lshrrev_b32_e32 v4, 16, v4
	v_add3_u32 v9, v42, v9, s45
	v_and_or_b32 v15, v9, s46, v4
	v_or_b32_e32 v4, v3, v24
	v_lshlrev_b32_e32 v4, 10, v4
	v_lshl_add_u64 v[44:45], v[18:19], 0, v[4:5]
	v_bfe_u32 v4, v17, 16, 1
	v_add3_u32 v4, v17, v4, s45
	v_bfe_u32 v9, v31, 16, 1
	v_lshrrev_b32_e32 v4, 16, v4
	v_add3_u32 v9, v31, v9, s45
	global_store_dwordx4 v[44:45], v[12:15], off
	v_or_b32_e32 v3, v3, v25
	s_nop 0
	v_and_or_b32 v12, v9, s46, v4
	v_bfe_u32 v4, v33, 16, 1
	v_add3_u32 v4, v33, v4, s45
	v_bfe_u32 v9, v35, 16, 1
	v_lshrrev_b32_e32 v4, 16, v4
	v_add3_u32 v9, v35, v9, s45
	v_and_or_b32 v13, v9, s46, v4
	v_bfe_u32 v4, v37, 16, 1
	v_add3_u32 v4, v37, v4, s45
	v_bfe_u32 v9, v39, 16, 1
	v_lshrrev_b32_e32 v4, 16, v4
	v_add3_u32 v9, v39, v9, s45
	v_and_or_b32 v14, v9, s46, v4
	v_bfe_u32 v4, v41, 16, 1
	v_add3_u32 v4, v41, v4, s45
	v_bfe_u32 v9, v43, 16, 1
	v_lshrrev_b32_e32 v4, 16, v4
	v_add3_u32 v9, v43, v9, s45
	v_and_or_b32 v15, v9, s46, v4
	v_lshlrev_b32_e32 v4, 10, v3
	v_lshl_add_u64 v[16:17], v[18:19], 0, v[4:5]
	global_store_dwordx4 v[16:17], v[12:15], off
	s_waitcnt lgkmcnt(0)
.LBB0_115:
	s_andn2_saveexec_b64 s[36:37], s[36:37]
	s_cbranch_execz .LBB0_119
	v_subrev_u16_e32 v3, 64, v3
	s_load_dwordx2 s[58:59], s[6:7], 0x58
	v_mul_lo_u16_sdwa v4, v3, s47 dst_sel:DWORD dst_unused:UNUSED_PAD src0_sel:BYTE_0 src1_sel:DWORD
	v_lshrrev_b16_e32 v4, 12, v4
	v_mul_lo_u16_e32 v9, 24, v4
	v_sub_u16_e32 v3, v3, v9
	v_mul_hi_i32_i24_e32 v15, 0x120000, v12
	v_mul_i32_i24_e32 v14, 0x120000, v12
	s_waitcnt lgkmcnt(0)
	v_lshl_add_u64 v[16:17], s[58:59], 0, v[14:15]
	v_lshlrev_b32_e32 v14, 6, v4
	v_lshlrev_b32_sdwa v4, v27, v3 dst_sel:DWORD dst_unused:UNUSED_PAD src0_sel:DWORD src1_sel:BYTE_0
	v_lshl_add_u64 v[16:17], v[16:17], 0, v[4:5]
	v_mov_b32_e32 v9, v5
	v_lshlrev_b32_sdwa v13, v26, v3 dst_sel:DWORD dst_unused:UNUSED_PAD src0_sel:DWORD src1_sel:BYTE_0
	v_lshl_add_u64 v[16:17], v[16:17], 0, v[8:9]
	v_mov_b32_e32 v3, v14
	s_mov_b32 s58, 1
	s_mov_b32 s59, 0
	s_mov_b32 s60, 32
	s_lshl_b32 s61, s58, 1
	s_lshl_b32 s62, s59, 1
	v_or_b32_e32 v104, s61, v1
	v_or_b32_e32 v109, s62, v2
	s_add_i32 s63, s61, 4
	s_add_i32 s64, s62, 4
	s_add_i32 s65, s61, 8
	s_add_i32 s66, s62, 8
	s_add_i32 s67, s61, 12
	s_add_i32 s68, s62, 12
	s_add_i32 s69, s61, 16
	s_add_i32 s70, s62, 16
	s_add_i32 s71, s61, 20
	s_add_i32 s72, s62, 20
	s_add_i32 s73, s61, 24
	s_add_i32 s74, s62, 24
	s_add_i32 s61, s61, 28
	s_add_i32 s62, s62, 28
	v_add_u32_e32 v111, v104, v3
	v_add_u32_e32 v115, v109, v14
	v_or_b32_e32 v129, s63, v1
	v_or_b32_e32 v160, s64, v2
	v_or_b32_e32 v161, s65, v1
	v_or_b32_e32 v162, s66, v2
	v_or_b32_e32 v163, s67, v1
	v_or_b32_e32 v164, s68, v2
	v_or_b32_e32 v165, s69, v1
	v_or_b32_e32 v166, s70, v2
	v_or_b32_e32 v167, s71, v1
	v_or_b32_e32 v168, s72, v2
	v_or_b32_e32 v169, s73, v1
	v_or_b32_e32 v170, s74, v2
	v_or_b32_e32 v171, s61, v1
	v_or_b32_e32 v172, s62, v2
	v_mad_u64_u32 v[118:119], s[62:63], v115, s48, v[16:17]
	v_mad_u64_u32 v[130:131], s[62:63], v111, s48, v[16:17]
	v_add_u32_e32 v111, v129, v3
	v_add_u32_e32 v115, v160, v14
	v_add_u32_e32 v138, v161, v3
	v_add_u32_e32 v136, v162, v14
	v_add_u32_e32 v142, v163, v3
	v_add_u32_e32 v140, v164, v14
	v_add_u32_e32 v146, v165, v3
	v_add_u32_e32 v144, v166, v14
	v_add_u32_e32 v150, v167, v3
	v_add_u32_e32 v148, v168, v14
	v_add_u32_e32 v154, v169, v3
	v_add_u32_e32 v152, v170, v14
	v_add_u32_e32 v158, v171, v3
	v_add_u32_e32 v156, v172, v14
	v_mad_u64_u32 v[132:133], s[62:63], v115, s48, v[16:17]
	v_mad_u64_u32 v[134:135], s[62:63], v111, s48, v[16:17]
	v_mad_u64_u32 v[136:137], s[62:63], v136, s48, v[16:17]
	v_mad_u64_u32 v[138:139], s[62:63], v138, s48, v[16:17]
	v_mad_u64_u32 v[140:141], s[62:63], v140, s48, v[16:17]
	v_mad_u64_u32 v[142:143], s[62:63], v142, s48, v[16:17]
	v_mad_u64_u32 v[144:145], s[62:63], v144, s48, v[16:17]
	v_mad_u64_u32 v[146:147], s[62:63], v146, s48, v[16:17]
	v_mad_u64_u32 v[148:149], s[62:63], v148, s48, v[16:17]
	v_mad_u64_u32 v[150:151], s[62:63], v150, s48, v[16:17]
	v_mad_u64_u32 v[152:153], s[62:63], v152, s48, v[16:17]
	v_mad_u64_u32 v[154:155], s[62:63], v154, s48, v[16:17]
	v_mad_u64_u32 v[156:157], s[62:63], v156, s48, v[16:17]
	v_mad_u64_u32 v[158:159], s[62:63], v158, s48, v[16:17]
	global_load_dword v111, v[118:119], off
	global_load_dword v115, v[130:131], off
	global_load_dword v173, v[132:133], off
	global_load_dword v174, v[134:135], off
	global_load_dword v175, v[136:137], off
	global_load_dword v176, v[138:139], off
	global_load_dword v177, v[140:141], off
	global_load_dword v178, v[142:143], off
	global_load_dword v179, v[144:145], off
	global_load_dword v180, v[146:147], off
	global_load_dword v181, v[148:149], off
	global_load_dword v182, v[150:151], off
	global_load_dword v183, v[152:153], off
	global_load_dword v184, v[154:155], off
	global_load_dword v185, v[156:157], off
	global_load_dword v186, v[158:159], off
	s_add_i32 s59, s59, 16
	s_add_i32 s58, s58, 16
	s_add_i32 s60, s60, -16
	v_mad_u64_u32 v[118:119], s[62:63], v109, s33, v[6:7]
	v_mad_u64_u32 v[130:131], s[62:63], v104, s33, v[6:7]
	v_mad_u64_u32 v[132:133], s[62:63], v160, s33, v[6:7]
	v_mad_u64_u32 v[134:135], s[62:63], v129, s33, v[6:7]
	v_mad_u64_u32 v[136:137], s[62:63], v162, s33, v[6:7]
	v_mad_u64_u32 v[138:139], s[62:63], v161, s33, v[6:7]
	v_mad_u64_u32 v[140:141], s[62:63], v164, s33, v[6:7]
	v_mad_u64_u32 v[142:143], s[62:63], v163, s33, v[6:7]
	v_mad_u64_u32 v[144:145], s[62:63], v166, s33, v[6:7]
	v_mad_u64_u32 v[146:147], s[62:63], v165, s33, v[6:7]
	v_mad_u64_u32 v[148:149], s[62:63], v168, s33, v[6:7]
	v_mad_u64_u32 v[150:151], s[62:63], v167, s33, v[6:7]
	v_mad_u64_u32 v[152:153], s[62:63], v170, s33, v[6:7]
	v_mad_u64_u32 v[154:155], s[62:63], v169, s33, v[6:7]
	v_mad_u64_u32 v[156:157], s[62:63], v172, s33, v[6:7]
	v_mad_u64_u32 v[158:159], s[62:63], v171, s33, v[6:7]
	s_lshl_b32 s61, s58, 1
	s_lshl_b32 s62, s59, 1
	v_or_b32_e32 v4, s61, v1
	v_or_b32_e32 v9, s62, v2
	s_add_i32 s63, s61, 4
	s_add_i32 s64, s62, 4
	s_add_i32 s65, s61, 8
	s_add_i32 s66, s62, 8
	s_add_i32 s67, s61, 12
	s_add_i32 s68, s62, 12
	s_add_i32 s69, s61, 16
	s_add_i32 s70, s62, 16
	s_add_i32 s71, s61, 20
	s_add_i32 s72, s62, 20
	s_add_i32 s73, s61, 24
	s_add_i32 s74, s62, 24
	s_add_i32 s61, s61, 28
	s_add_i32 s62, s62, 28
	v_add_u32_e32 v11, v4, v3
	v_add_u32_e32 v15, v9, v14
	v_or_b32_e32 v29, s63, v1
	v_or_b32_e32 v60, s64, v2
	v_or_b32_e32 v61, s65, v1
	v_or_b32_e32 v62, s66, v2
	v_or_b32_e32 v63, s67, v1
	v_or_b32_e32 v64, s68, v2
	v_or_b32_e32 v65, s69, v1
	v_or_b32_e32 v66, s70, v2
	v_or_b32_e32 v67, s71, v1
	v_or_b32_e32 v68, s72, v2
	v_or_b32_e32 v69, s73, v1
	v_or_b32_e32 v70, s74, v2
	v_or_b32_e32 v71, s61, v1
	v_or_b32_e32 v72, s62, v2
	v_mad_u64_u32 v[18:19], s[62:63], v15, s48, v[16:17]
	v_mad_u64_u32 v[30:31], s[62:63], v11, s48, v[16:17]
	v_add_u32_e32 v11, v29, v3
	v_add_u32_e32 v15, v60, v14
	v_add_u32_e32 v38, v61, v3
	v_add_u32_e32 v36, v62, v14
	v_add_u32_e32 v42, v63, v3
	v_add_u32_e32 v40, v64, v14
	v_add_u32_e32 v46, v65, v3
	v_add_u32_e32 v44, v66, v14
	v_add_u32_e32 v50, v67, v3
	v_add_u32_e32 v48, v68, v14
	v_add_u32_e32 v54, v69, v3
	v_add_u32_e32 v52, v70, v14
	v_add_u32_e32 v58, v71, v3
	v_add_u32_e32 v56, v72, v14
	v_mad_u64_u32 v[32:33], s[62:63], v15, s48, v[16:17]
	v_mad_u64_u32 v[34:35], s[62:63], v11, s48, v[16:17]
	v_mad_u64_u32 v[36:37], s[62:63], v36, s48, v[16:17]
	v_mad_u64_u32 v[38:39], s[62:63], v38, s48, v[16:17]
	v_mad_u64_u32 v[40:41], s[62:63], v40, s48, v[16:17]
	v_mad_u64_u32 v[42:43], s[62:63], v42, s48, v[16:17]
	v_mad_u64_u32 v[44:45], s[62:63], v44, s48, v[16:17]
	v_mad_u64_u32 v[46:47], s[62:63], v46, s48, v[16:17]
	v_mad_u64_u32 v[48:49], s[62:63], v48, s48, v[16:17]
	v_mad_u64_u32 v[50:51], s[62:63], v50, s48, v[16:17]
	v_mad_u64_u32 v[52:53], s[62:63], v52, s48, v[16:17]
	v_mad_u64_u32 v[54:55], s[62:63], v54, s48, v[16:17]
	v_mad_u64_u32 v[56:57], s[62:63], v56, s48, v[16:17]
	v_mad_u64_u32 v[58:59], s[62:63], v58, s48, v[16:17]
	global_load_dword v11, v[18:19], off
	global_load_dword v15, v[30:31], off
	global_load_dword v73, v[32:33], off
	global_load_dword v74, v[34:35], off
	global_load_dword v75, v[36:37], off
	global_load_dword v76, v[38:39], off
	global_load_dword v77, v[40:41], off
	global_load_dword v78, v[42:43], off
	global_load_dword v79, v[44:45], off
	global_load_dword v80, v[46:47], off
	global_load_dword v81, v[48:49], off
	global_load_dword v82, v[50:51], off
	global_load_dword v83, v[52:53], off
	global_load_dword v84, v[54:55], off
	global_load_dword v85, v[56:57], off
	global_load_dword v86, v[58:59], off
	s_add_i32 s59, s59, 16
	s_add_i32 s58, s58, 16
	s_add_i32 s60, s60, -16
	v_mad_u64_u32 v[18:19], s[62:63], v9, s33, v[6:7]
	v_mad_u64_u32 v[30:31], s[62:63], v4, s33, v[6:7]
	v_mad_u64_u32 v[32:33], s[62:63], v60, s33, v[6:7]
	v_mad_u64_u32 v[34:35], s[62:63], v29, s33, v[6:7]
	v_mad_u64_u32 v[36:37], s[62:63], v62, s33, v[6:7]
	v_mad_u64_u32 v[38:39], s[62:63], v61, s33, v[6:7]
	v_mad_u64_u32 v[40:41], s[62:63], v64, s33, v[6:7]
	v_mad_u64_u32 v[42:43], s[62:63], v63, s33, v[6:7]
	v_mad_u64_u32 v[44:45], s[62:63], v66, s33, v[6:7]
	v_mad_u64_u32 v[46:47], s[62:63], v65, s33, v[6:7]
	v_mad_u64_u32 v[48:49], s[62:63], v68, s33, v[6:7]
	v_mad_u64_u32 v[50:51], s[62:63], v67, s33, v[6:7]
	v_mad_u64_u32 v[52:53], s[62:63], v70, s33, v[6:7]
	v_mad_u64_u32 v[54:55], s[62:63], v69, s33, v[6:7]
	v_mad_u64_u32 v[56:57], s[62:63], v72, s33, v[6:7]
	v_mad_u64_u32 v[58:59], s[62:63], v71, s33, v[6:7]
	s_waitcnt vmcnt(31)
	ds_write_b32 v118, v111
	s_waitcnt vmcnt(30)
	ds_write_b32 v130, v115
	s_waitcnt vmcnt(29)
	ds_write_b32 v132, v173
	s_waitcnt vmcnt(28)
	ds_write_b32 v134, v174
	s_waitcnt vmcnt(27)
	ds_write_b32 v136, v175
	s_waitcnt vmcnt(26)
	ds_write_b32 v138, v176
	s_waitcnt vmcnt(25)
	ds_write_b32 v140, v177
	s_waitcnt vmcnt(24)
	ds_write_b32 v142, v178
	s_waitcnt vmcnt(23)
	ds_write_b32 v144, v179
	s_waitcnt vmcnt(22)
	ds_write_b32 v146, v180
	s_waitcnt vmcnt(21)
	ds_write_b32 v148, v181
	s_waitcnt vmcnt(20)
	ds_write_b32 v150, v182
	s_waitcnt vmcnt(19)
	ds_write_b32 v152, v183
	s_waitcnt vmcnt(18)
	ds_write_b32 v154, v184
	s_waitcnt vmcnt(17)
	ds_write_b32 v156, v185
	s_waitcnt vmcnt(16)
	ds_write_b32 v158, v186
	s_waitcnt vmcnt(15)
	ds_write_b32 v18, v11
	s_waitcnt vmcnt(14)
	ds_write_b32 v30, v15
	s_waitcnt vmcnt(13)
	ds_write_b32 v32, v73
	s_waitcnt vmcnt(12)
	ds_write_b32 v34, v74
	s_waitcnt vmcnt(11)
	ds_write_b32 v36, v75
	s_waitcnt vmcnt(10)
	ds_write_b32 v38, v76
	s_waitcnt vmcnt(9)
	ds_write_b32 v40, v77
	s_waitcnt vmcnt(8)
	ds_write_b32 v42, v78
	s_waitcnt vmcnt(7)
	ds_write_b32 v44, v79
	s_waitcnt vmcnt(6)
	ds_write_b32 v46, v80
	s_waitcnt vmcnt(5)
	ds_write_b32 v48, v81
	s_waitcnt vmcnt(4)
	ds_write_b32 v50, v82
	s_waitcnt vmcnt(3)
	ds_write_b32 v52, v83
	s_waitcnt vmcnt(2)
	ds_write_b32 v54, v84
	s_waitcnt vmcnt(1)
	ds_write_b32 v56, v85
	s_waitcnt vmcnt(0)
	ds_write_b32 v58, v86
	s_waitcnt lgkmcnt(0)
	ds_read2_b32 v[18:19], v22 offset1:8
	ds_read2_b32 v[32:33], v22 offset0:33 offset1:41
	ds_read2_b32 v[34:35], v22 offset0:66 offset1:74
	v_mul_hi_i32_i24_e32 v17, 0x1c0000, v12
	v_mul_i32_i24_e32 v16, 0x1c0000, v12
	ds_read2_b32 v[36:37], v22 offset0:99 offset1:107
	v_lshl_add_u64 v[16:17], s[10:11], 0, v[16:17]
	v_lshlrev_b32_e32 v4, 1, v14
	s_waitcnt lgkmcnt(3)
	v_bfe_u32 v3, v18, 16, 1
	v_lshl_add_u64 v[14:15], v[16:17], 0, v[4:5]
	v_add3_u32 v3, v18, v3, s45
	s_waitcnt lgkmcnt(2)
	v_bfe_u32 v4, v32, 16, 1
	ds_read2_b32 v[38:39], v22 offset0:132 offset1:140
	v_mov_b32_e32 v11, v5
	v_lshrrev_b32_e32 v3, 16, v3
	v_add3_u32 v4, v32, v4, s45
	ds_read2_b32 v[40:41], v22 offset0:165 offset1:173
	v_lshl_add_u64 v[30:31], v[14:15], 0, v[10:11]
	v_and_or_b32 v14, v4, s46, v3
	s_waitcnt lgkmcnt(3)
	v_bfe_u32 v3, v34, 16, 1
	v_add3_u32 v3, v34, v3, s45
	s_waitcnt lgkmcnt(2)
	v_bfe_u32 v4, v36, 16, 1
	ds_read2_b32 v[42:43], v22 offset0:198 offset1:206
	v_lshrrev_b32_e32 v3, 16, v3
	v_add3_u32 v4, v36, v4, s45
	ds_read2_b32 v[44:45], v22 offset0:231 offset1:239
	v_and_or_b32 v15, v4, s46, v3
	s_waitcnt lgkmcnt(3)
	v_bfe_u32 v3, v38, 16, 1
	v_add3_u32 v3, v38, v3, s45
	s_waitcnt lgkmcnt(2)
	v_bfe_u32 v4, v40, 16, 1
	v_lshrrev_b32_e32 v3, 16, v3
	v_add3_u32 v4, v40, v4, s45
	v_and_or_b32 v16, v4, s46, v3
	s_waitcnt lgkmcnt(1)
	v_bfe_u32 v3, v42, 16, 1
	v_add3_u32 v3, v42, v3, s45
	s_waitcnt lgkmcnt(0)
	v_bfe_u32 v4, v44, 16, 1
	v_lshrrev_b32_e32 v3, 16, v3
	v_add3_u32 v4, v44, v4, s45
	v_and_or_b32 v17, v4, s46, v3
	v_or_b32_e32 v3, v13, v21
	v_lshlrev_b32_e32 v4, 10, v3
	v_bfe_u32 v3, v19, 16, 1
	v_lshl_add_u64 v[46:47], v[30:31], 0, v[4:5]
	v_add3_u32 v3, v19, v3, s45
	v_bfe_u32 v4, v33, 16, 1
	v_lshrrev_b32_e32 v3, 16, v3
	v_add3_u32 v4, v33, v4, s45
	global_store_dwordx4 v[46:47], v[14:17], off
	ds_read2_b32 v[18:19], v22 offset0:16 offset1:24
	v_readlane_b32 s66, v253, 1
	v_and_or_b32 v14, v4, s46, v3
	v_bfe_u32 v3, v35, 16, 1
	v_add3_u32 v3, v35, v3, s45
	v_bfe_u32 v4, v37, 16, 1
	v_lshrrev_b32_e32 v3, 16, v3
	v_add3_u32 v4, v37, v4, s45
	v_and_or_b32 v15, v4, s46, v3
	v_bfe_u32 v3, v39, 16, 1
	v_add3_u32 v3, v39, v3, s45
	v_bfe_u32 v4, v41, 16, 1
	v_lshrrev_b32_e32 v3, 16, v3
	v_add3_u32 v4, v41, v4, s45
	v_and_or_b32 v16, v4, s46, v3
	v_bfe_u32 v3, v43, 16, 1
	v_add3_u32 v3, v43, v3, s45
	v_bfe_u32 v4, v45, 16, 1
	v_lshrrev_b32_e32 v3, 16, v3
	v_add3_u32 v4, v45, v4, s45
	v_and_or_b32 v17, v4, s46, v3
	v_or_b32_e32 v3, v13, v23
	v_lshlrev_b32_e32 v4, 10, v3
	v_lshl_add_u64 v[32:33], v[30:31], 0, v[4:5]
	global_store_dwordx4 v[32:33], v[14:17], off
	ds_read2_b32 v[32:33], v22 offset0:49 offset1:57
	ds_read2_b32 v[34:35], v22 offset0:82 offset1:90
	ds_read2_b32 v[36:37], v22 offset0:115 offset1:123
	s_waitcnt lgkmcnt(3)
	v_bfe_u32 v3, v18, 16, 1
	v_add3_u32 v3, v18, v3, s45
	s_waitcnt lgkmcnt(2)
	v_bfe_u32 v4, v32, 16, 1
	ds_read2_b32 v[38:39], v22 offset0:148 offset1:156
	v_lshrrev_b32_e32 v3, 16, v3
	v_add3_u32 v4, v32, v4, s45
	ds_read2_b32 v[40:41], v22 offset0:181 offset1:189
	v_and_or_b32 v14, v4, s46, v3
	s_waitcnt lgkmcnt(3)
	v_bfe_u32 v3, v34, 16, 1
	v_add3_u32 v3, v34, v3, s45
	s_waitcnt lgkmcnt(2)
	v_bfe_u32 v4, v36, 16, 1
	ds_read2_b32 v[42:43], v22 offset0:214 offset1:222
	v_lshrrev_b32_e32 v3, 16, v3
	v_add3_u32 v4, v36, v4, s45
	ds_read2_b32 v[44:45], v22 offset0:247 offset1:255
	v_and_or_b32 v15, v4, s46, v3
	s_waitcnt lgkmcnt(3)
	v_bfe_u32 v3, v38, 16, 1
	v_add3_u32 v3, v38, v3, s45
	s_waitcnt lgkmcnt(2)
	v_bfe_u32 v4, v40, 16, 1
	v_lshrrev_b32_e32 v3, 16, v3
	v_add3_u32 v4, v40, v4, s45
	v_and_or_b32 v16, v4, s46, v3
	s_waitcnt lgkmcnt(1)
	v_bfe_u32 v3, v42, 16, 1
	v_add3_u32 v3, v42, v3, s45
	s_waitcnt lgkmcnt(0)
	v_bfe_u32 v4, v44, 16, 1
	v_lshrrev_b32_e32 v3, 16, v3
	v_add3_u32 v4, v44, v4, s45
	v_and_or_b32 v17, v4, s46, v3
	v_or_b32_e32 v3, v13, v24
	v_lshlrev_b32_e32 v4, 10, v3
	v_bfe_u32 v3, v19, 16, 1
	v_lshl_add_u64 v[46:47], v[30:31], 0, v[4:5]
	v_add3_u32 v3, v19, v3, s45
	v_bfe_u32 v4, v33, 16, 1
	v_lshrrev_b32_e32 v3, 16, v3
	v_add3_u32 v4, v33, v4, s45
	global_store_dwordx4 v[46:47], v[14:17], off
	s_nop 1
	v_and_or_b32 v14, v4, s46, v3
	v_bfe_u32 v3, v35, 16, 1
	v_add3_u32 v3, v35, v3, s45
	v_bfe_u32 v4, v37, 16, 1
	v_lshrrev_b32_e32 v3, 16, v3
	v_add3_u32 v4, v37, v4, s45
	v_and_or_b32 v15, v4, s46, v3
	v_bfe_u32 v3, v39, 16, 1
	v_add3_u32 v3, v39, v3, s45
	v_bfe_u32 v4, v41, 16, 1
	v_lshrrev_b32_e32 v3, 16, v3
	v_add3_u32 v4, v41, v4, s45
	v_and_or_b32 v16, v4, s46, v3
	v_bfe_u32 v3, v43, 16, 1
	v_add3_u32 v3, v43, v3, s45
	v_bfe_u32 v4, v45, 16, 1
	v_lshrrev_b32_e32 v3, 16, v3
	v_add3_u32 v4, v45, v4, s45
	v_and_or_b32 v17, v4, s46, v3
	v_or_b32_e32 v3, v13, v25
	v_lshlrev_b32_e32 v4, 10, v3
	v_lshl_add_u64 v[12:13], v[30:31], 0, v[4:5]
	global_store_dwordx4 v[12:13], v[14:17], off
	s_waitcnt lgkmcnt(0)

.LBB0_120:
	s_andn2_saveexec_b64 s[34:35], s[34:35]
	s_cbranch_execz .LBB0_124
	s_load_dwordx2 s[36:37], s[6:7], 0xb0
	v_and_b32_e32 v4, 0x7fc0, v3
	v_lshlrev_b32_e32 v3, 5, v3
	v_and_b32_e32 v13, 0x7e0, v3
	v_add_u32_e32 v14, 0xffffbbc0, v4
	s_waitcnt lgkmcnt(0)
	v_mov_b64_e32 v[16:17], s[36:37]
	v_mad_i64_i32 v[16:17], s[36:37], v12, s49, v[16:17]
	v_lshlrev_b32_e32 v4, 2, v13
	v_lshl_add_u64 v[16:17], v[16:17], 0, v[4:5]
	v_mov_b32_e32 v9, v5
	v_lshl_add_u64 v[16:17], v[16:17], 0, v[8:9]
	v_mov_b32_e32 v3, v14
	s_mov_b32 s36, 1
	s_mov_b32 s37, 0
	s_mov_b32 s58, 32
	s_lshl_b32 s59, s36, 1
	s_lshl_b32 s60, s37, 1
	v_or_b32_e32 v104, s59, v1
	v_or_b32_e32 v109, s60, v2
	s_add_i32 s61, s59, 4
	s_add_i32 s62, s60, 4
	s_add_i32 s63, s59, 8
	s_add_i32 s64, s60, 8
	s_add_i32 s65, s59, 12
	s_add_i32 s66, s60, 12
	s_add_i32 s67, s59, 16
	s_add_i32 s68, s60, 16
	s_add_i32 s69, s59, 20
	s_add_i32 s70, s60, 20
	s_add_i32 s71, s59, 24
	s_add_i32 s72, s60, 24
	s_add_i32 s59, s59, 28
	s_add_i32 s60, s60, 28
	v_add_u32_e32 v130, v109, v14
	v_or_b32_e32 v111, s61, v1
	v_or_b32_e32 v115, s62, v2
	v_or_b32_e32 v129, s63, v1
	v_or_b32_e32 v160, s64, v2
	v_or_b32_e32 v161, s65, v1
	v_or_b32_e32 v162, s66, v2
	v_or_b32_e32 v163, s67, v1
	v_or_b32_e32 v164, s68, v2
	v_or_b32_e32 v165, s69, v1
	v_or_b32_e32 v166, s70, v2
	v_or_b32_e32 v167, s71, v1
	v_or_b32_e32 v168, s72, v2
	v_or_b32_e32 v169, s59, v1
	v_or_b32_e32 v170, s60, v2
	v_add_u32_e32 v118, v104, v3
	v_ashrrev_i32_e32 v131, 31, v130
	v_add_u32_e32 v132, v111, v3
	v_add_u32_e32 v134, v115, v14
	v_add_u32_e32 v136, v129, v3
	v_add_u32_e32 v138, v160, v14
	v_add_u32_e32 v140, v161, v3
	v_add_u32_e32 v142, v162, v14
	v_add_u32_e32 v144, v163, v3
	v_add_u32_e32 v146, v164, v14
	v_add_u32_e32 v148, v165, v3
	v_add_u32_e32 v150, v166, v14
	v_add_u32_e32 v152, v167, v3
	v_add_u32_e32 v154, v168, v14
	v_add_u32_e32 v156, v169, v3
	v_add_u32_e32 v158, v170, v14
	v_ashrrev_i32_e32 v119, 31, v118
	v_lshlrev_b64 v[130:131], 13, v[130:131]
	v_ashrrev_i32_e32 v135, 31, v134
	v_ashrrev_i32_e32 v133, 31, v132
	v_ashrrev_i32_e32 v139, 31, v138
	v_ashrrev_i32_e32 v137, 31, v136
	v_ashrrev_i32_e32 v143, 31, v142
	v_ashrrev_i32_e32 v141, 31, v140
	v_ashrrev_i32_e32 v147, 31, v146
	v_ashrrev_i32_e32 v145, 31, v144
	v_ashrrev_i32_e32 v151, 31, v150
	v_ashrrev_i32_e32 v149, 31, v148
	v_ashrrev_i32_e32 v155, 31, v154
	v_ashrrev_i32_e32 v153, 31, v152
	v_ashrrev_i32_e32 v159, 31, v158
	v_ashrrev_i32_e32 v157, 31, v156
	v_lshlrev_b64 v[118:119], 13, v[118:119]
	v_lshl_add_u64 v[130:131], v[16:17], 0, v[130:131]
	v_lshlrev_b64 v[132:133], 13, v[132:133]
	v_lshlrev_b64 v[134:135], 13, v[134:135]
	v_lshlrev_b64 v[136:137], 13, v[136:137]
	v_lshlrev_b64 v[138:139], 13, v[138:139]
	v_lshlrev_b64 v[140:141], 13, v[140:141]
	v_lshlrev_b64 v[142:143], 13, v[142:143]
	v_lshlrev_b64 v[144:145], 13, v[144:145]
	v_lshlrev_b64 v[146:147], 13, v[146:147]
	v_lshlrev_b64 v[148:149], 13, v[148:149]
	v_lshlrev_b64 v[150:151], 13, v[150:151]
	v_lshlrev_b64 v[152:153], 13, v[152:153]
	v_lshlrev_b64 v[154:155], 13, v[154:155]
	v_lshlrev_b64 v[156:157], 13, v[156:157]
	v_lshlrev_b64 v[158:159], 13, v[158:159]
	v_lshl_add_u64 v[118:119], v[16:17], 0, v[118:119]
	v_lshl_add_u64 v[134:135], v[16:17], 0, v[134:135]
	v_lshl_add_u64 v[132:133], v[16:17], 0, v[132:133]
	v_lshl_add_u64 v[138:139], v[16:17], 0, v[138:139]
	v_lshl_add_u64 v[136:137], v[16:17], 0, v[136:137]
	v_lshl_add_u64 v[142:143], v[16:17], 0, v[142:143]
	v_lshl_add_u64 v[140:141], v[16:17], 0, v[140:141]
	v_lshl_add_u64 v[146:147], v[16:17], 0, v[146:147]
	v_lshl_add_u64 v[144:145], v[16:17], 0, v[144:145]
	v_lshl_add_u64 v[150:151], v[16:17], 0, v[150:151]
	v_lshl_add_u64 v[148:149], v[16:17], 0, v[148:149]
	v_lshl_add_u64 v[154:155], v[16:17], 0, v[154:155]
	v_lshl_add_u64 v[152:153], v[16:17], 0, v[152:153]
	v_lshl_add_u64 v[158:159], v[16:17], 0, v[158:159]
	v_lshl_add_u64 v[156:157], v[16:17], 0, v[156:157]
	global_load_dword v171, v[130:131], off
	global_load_dword v172, v[118:119], off
	global_load_dword v173, v[134:135], off
	global_load_dword v174, v[132:133], off
	global_load_dword v175, v[138:139], off
	global_load_dword v176, v[136:137], off
	global_load_dword v177, v[142:143], off
	global_load_dword v178, v[140:141], off
	global_load_dword v179, v[146:147], off
	global_load_dword v180, v[144:145], off
	global_load_dword v181, v[150:151], off
	global_load_dword v182, v[148:149], off
	global_load_dword v183, v[154:155], off
	global_load_dword v184, v[152:153], off
	global_load_dword v185, v[158:159], off
	global_load_dword v186, v[156:157], off
	s_add_i32 s37, s37, 16
	s_add_i32 s36, s36, 16
	s_add_i32 s58, s58, -16
	v_mad_u64_u32 v[118:119], s[60:61], v109, s33, v[6:7]
	v_mad_u64_u32 v[130:131], s[60:61], v104, s33, v[6:7]
	v_mad_u64_u32 v[132:133], s[60:61], v115, s33, v[6:7]
	v_mad_u64_u32 v[134:135], s[60:61], v111, s33, v[6:7]
	v_mad_u64_u32 v[136:137], s[60:61], v160, s33, v[6:7]
	v_mad_u64_u32 v[138:139], s[60:61], v129, s33, v[6:7]
	v_mad_u64_u32 v[140:141], s[60:61], v162, s33, v[6:7]
	v_mad_u64_u32 v[142:143], s[60:61], v161, s33, v[6:7]
	v_mad_u64_u32 v[144:145], s[60:61], v164, s33, v[6:7]
	v_mad_u64_u32 v[146:147], s[60:61], v163, s33, v[6:7]
	v_mad_u64_u32 v[148:149], s[60:61], v166, s33, v[6:7]
	v_mad_u64_u32 v[150:151], s[60:61], v165, s33, v[6:7]
	v_mad_u64_u32 v[152:153], s[60:61], v168, s33, v[6:7]
	v_mad_u64_u32 v[154:155], s[60:61], v167, s33, v[6:7]
	v_mad_u64_u32 v[156:157], s[60:61], v170, s33, v[6:7]
	v_mad_u64_u32 v[158:159], s[60:61], v169, s33, v[6:7]
	s_lshl_b32 s59, s36, 1
	s_lshl_b32 s60, s37, 1
	v_or_b32_e32 v4, s59, v1
	v_or_b32_e32 v9, s60, v2
	s_add_i32 s61, s59, 4
	s_add_i32 s62, s60, 4
	s_add_i32 s63, s59, 8
	s_add_i32 s64, s60, 8
	s_add_i32 s65, s59, 12
	s_add_i32 s66, s60, 12
	s_add_i32 s67, s59, 16
	s_add_i32 s68, s60, 16
	s_add_i32 s69, s59, 20
	s_add_i32 s70, s60, 20
	s_add_i32 s71, s59, 24
	s_add_i32 s72, s60, 24
	s_add_i32 s59, s59, 28
	s_add_i32 s60, s60, 28
	v_add_u32_e32 v30, v9, v14
	v_or_b32_e32 v11, s61, v1
	v_or_b32_e32 v15, s62, v2
	v_or_b32_e32 v29, s63, v1
	v_or_b32_e32 v60, s64, v2
	v_or_b32_e32 v61, s65, v1
	v_or_b32_e32 v62, s66, v2
	v_or_b32_e32 v63, s67, v1
	v_or_b32_e32 v64, s68, v2
	v_or_b32_e32 v65, s69, v1
	v_or_b32_e32 v66, s70, v2
	v_or_b32_e32 v67, s71, v1
	v_or_b32_e32 v68, s72, v2
	v_or_b32_e32 v69, s59, v1
	v_or_b32_e32 v70, s60, v2
	v_add_u32_e32 v18, v4, v3
	v_ashrrev_i32_e32 v31, 31, v30
	v_add_u32_e32 v32, v11, v3
	v_add_u32_e32 v34, v15, v14
	v_add_u32_e32 v36, v29, v3
	v_add_u32_e32 v38, v60, v14
	v_add_u32_e32 v40, v61, v3
	v_add_u32_e32 v42, v62, v14
	v_add_u32_e32 v44, v63, v3
	v_add_u32_e32 v46, v64, v14
	v_add_u32_e32 v48, v65, v3
	v_add_u32_e32 v50, v66, v14
	v_add_u32_e32 v52, v67, v3
	v_add_u32_e32 v54, v68, v14
	v_add_u32_e32 v56, v69, v3
	v_add_u32_e32 v58, v70, v14
	v_ashrrev_i32_e32 v19, 31, v18
	v_lshlrev_b64 v[30:31], 13, v[30:31]
	v_ashrrev_i32_e32 v35, 31, v34
	v_ashrrev_i32_e32 v33, 31, v32
	v_ashrrev_i32_e32 v39, 31, v38
	v_ashrrev_i32_e32 v37, 31, v36
	v_ashrrev_i32_e32 v43, 31, v42
	v_ashrrev_i32_e32 v41, 31, v40
	v_ashrrev_i32_e32 v47, 31, v46
	v_ashrrev_i32_e32 v45, 31, v44
	v_ashrrev_i32_e32 v51, 31, v50
	v_ashrrev_i32_e32 v49, 31, v48
	v_ashrrev_i32_e32 v55, 31, v54
	v_ashrrev_i32_e32 v53, 31, v52
	v_ashrrev_i32_e32 v59, 31, v58
	v_ashrrev_i32_e32 v57, 31, v56
	v_lshlrev_b64 v[18:19], 13, v[18:19]
	v_lshl_add_u64 v[30:31], v[16:17], 0, v[30:31]
	v_lshlrev_b64 v[32:33], 13, v[32:33]
	v_lshlrev_b64 v[34:35], 13, v[34:35]
	v_lshlrev_b64 v[36:37], 13, v[36:37]
	v_lshlrev_b64 v[38:39], 13, v[38:39]
	v_lshlrev_b64 v[40:41], 13, v[40:41]
	v_lshlrev_b64 v[42:43], 13, v[42:43]
	v_lshlrev_b64 v[44:45], 13, v[44:45]
	v_lshlrev_b64 v[46:47], 13, v[46:47]
	v_lshlrev_b64 v[48:49], 13, v[48:49]
	v_lshlrev_b64 v[50:51], 13, v[50:51]
	v_lshlrev_b64 v[52:53], 13, v[52:53]
	v_lshlrev_b64 v[54:55], 13, v[54:55]
	v_lshlrev_b64 v[56:57], 13, v[56:57]
	v_lshlrev_b64 v[58:59], 13, v[58:59]
	v_lshl_add_u64 v[18:19], v[16:17], 0, v[18:19]
	v_lshl_add_u64 v[34:35], v[16:17], 0, v[34:35]
	v_lshl_add_u64 v[32:33], v[16:17], 0, v[32:33]
	v_lshl_add_u64 v[38:39], v[16:17], 0, v[38:39]
	v_lshl_add_u64 v[36:37], v[16:17], 0, v[36:37]
	v_lshl_add_u64 v[42:43], v[16:17], 0, v[42:43]
	v_lshl_add_u64 v[40:41], v[16:17], 0, v[40:41]
	v_lshl_add_u64 v[46:47], v[16:17], 0, v[46:47]
	v_lshl_add_u64 v[44:45], v[16:17], 0, v[44:45]
	v_lshl_add_u64 v[50:51], v[16:17], 0, v[50:51]
	v_lshl_add_u64 v[48:49], v[16:17], 0, v[48:49]
	v_lshl_add_u64 v[54:55], v[16:17], 0, v[54:55]
	v_lshl_add_u64 v[52:53], v[16:17], 0, v[52:53]
	v_lshl_add_u64 v[58:59], v[16:17], 0, v[58:59]
	v_lshl_add_u64 v[56:57], v[16:17], 0, v[56:57]
	global_load_dword v71, v[30:31], off
	global_load_dword v72, v[18:19], off
	global_load_dword v73, v[34:35], off
	global_load_dword v74, v[32:33], off
	global_load_dword v75, v[38:39], off
	global_load_dword v76, v[36:37], off
	global_load_dword v77, v[42:43], off
	global_load_dword v78, v[40:41], off
	global_load_dword v79, v[46:47], off
	global_load_dword v80, v[44:45], off
	global_load_dword v81, v[50:51], off
	global_load_dword v82, v[48:49], off
	global_load_dword v83, v[54:55], off
	global_load_dword v84, v[52:53], off
	global_load_dword v85, v[58:59], off
	global_load_dword v86, v[56:57], off
	s_add_i32 s37, s37, 16
	s_add_i32 s36, s36, 16
	s_add_i32 s58, s58, -16
	v_mad_u64_u32 v[18:19], s[60:61], v9, s33, v[6:7]
	v_mad_u64_u32 v[30:31], s[60:61], v4, s33, v[6:7]
	v_mad_u64_u32 v[32:33], s[60:61], v15, s33, v[6:7]
	v_mad_u64_u32 v[34:35], s[60:61], v11, s33, v[6:7]
	v_mad_u64_u32 v[36:37], s[60:61], v60, s33, v[6:7]
	v_mad_u64_u32 v[38:39], s[60:61], v29, s33, v[6:7]
	v_mad_u64_u32 v[40:41], s[60:61], v62, s33, v[6:7]
	v_mad_u64_u32 v[42:43], s[60:61], v61, s33, v[6:7]
	v_mad_u64_u32 v[44:45], s[60:61], v64, s33, v[6:7]
	v_mad_u64_u32 v[46:47], s[60:61], v63, s33, v[6:7]
	v_mad_u64_u32 v[48:49], s[60:61], v66, s33, v[6:7]
	v_mad_u64_u32 v[50:51], s[60:61], v65, s33, v[6:7]
	v_mad_u64_u32 v[52:53], s[60:61], v68, s33, v[6:7]
	v_mad_u64_u32 v[54:55], s[60:61], v67, s33, v[6:7]
	v_mad_u64_u32 v[56:57], s[60:61], v70, s33, v[6:7]
	v_mad_u64_u32 v[58:59], s[60:61], v69, s33, v[6:7]
	s_waitcnt vmcnt(31)
	ds_write_b32 v118, v171
	s_waitcnt vmcnt(30)
	ds_write_b32 v130, v172
	s_waitcnt vmcnt(29)
	ds_write_b32 v132, v173
	s_waitcnt vmcnt(28)
	ds_write_b32 v134, v174
	s_waitcnt vmcnt(27)
	ds_write_b32 v136, v175
	s_waitcnt vmcnt(26)
	ds_write_b32 v138, v176
	s_waitcnt vmcnt(25)
	ds_write_b32 v140, v177
	s_waitcnt vmcnt(24)
	ds_write_b32 v142, v178
	s_waitcnt vmcnt(23)
	ds_write_b32 v144, v179
	s_waitcnt vmcnt(22)
	ds_write_b32 v146, v180
	s_waitcnt vmcnt(21)
	ds_write_b32 v148, v181
	s_waitcnt vmcnt(20)
	ds_write_b32 v150, v182
	s_waitcnt vmcnt(19)
	ds_write_b32 v152, v183
	s_waitcnt vmcnt(18)
	ds_write_b32 v154, v184
	s_waitcnt vmcnt(17)
	ds_write_b32 v156, v185
	s_waitcnt vmcnt(16)
	ds_write_b32 v158, v186
	s_waitcnt vmcnt(15)
	ds_write_b32 v18, v71
	s_waitcnt vmcnt(14)
	ds_write_b32 v30, v72
	s_waitcnt vmcnt(13)
	ds_write_b32 v32, v73
	s_waitcnt vmcnt(12)
	ds_write_b32 v34, v74
	s_waitcnt vmcnt(11)
	ds_write_b32 v36, v75
	s_waitcnt vmcnt(10)
	ds_write_b32 v38, v76
	s_waitcnt vmcnt(9)
	ds_write_b32 v40, v77
	s_waitcnt vmcnt(8)
	ds_write_b32 v42, v78
	s_waitcnt vmcnt(7)
	ds_write_b32 v44, v79
	s_waitcnt vmcnt(6)
	ds_write_b32 v46, v80
	s_waitcnt vmcnt(5)
	ds_write_b32 v48, v81
	s_waitcnt vmcnt(4)
	ds_write_b32 v50, v82
	s_waitcnt vmcnt(3)
	ds_write_b32 v52, v83
	s_waitcnt vmcnt(2)
	ds_write_b32 v54, v84
	s_waitcnt vmcnt(1)
	ds_write_b32 v56, v85
	s_waitcnt vmcnt(0)
	ds_write_b32 v58, v86
	s_waitcnt lgkmcnt(0)
	ds_read2_b32 v[18:19], v22 offset1:8
	ds_read2_b32 v[32:33], v22 offset0:33 offset1:41
	ds_read2_b32 v[34:35], v22 offset0:66 offset1:74
	ds_read2_b32 v[36:37], v22 offset0:99 offset1:107
	v_mov_b64_e32 v[16:17], s[12:13]
	s_waitcnt lgkmcnt(3)
	v_bfe_u32 v3, v18, 16, 1
	v_mad_i64_i32 v[16:17], s[36:37], v12, s50, v[16:17]
	v_mov_b32_e32 v15, v5
	v_add3_u32 v3, v18, v3, s45
	s_waitcnt lgkmcnt(2)
	v_bfe_u32 v4, v32, 16, 1
	ds_read2_b32 v[38:39], v22 offset0:132 offset1:140
	v_lshl_add_u64 v[14:15], v[14:15], 1, v[16:17]
	v_mov_b32_e32 v11, v5
	v_lshrrev_b32_e32 v3, 16, v3
	v_add3_u32 v4, v32, v4, s45
	ds_read2_b32 v[40:41], v22 offset0:165 offset1:173
	v_lshl_add_u64 v[30:31], v[14:15], 0, v[10:11]
	v_and_or_b32 v14, v4, s46, v3
	s_waitcnt lgkmcnt(3)
	v_bfe_u32 v3, v34, 16, 1
	v_add3_u32 v3, v34, v3, s45
	s_waitcnt lgkmcnt(2)
	v_bfe_u32 v4, v36, 16, 1
	ds_read2_b32 v[42:43], v22 offset0:198 offset1:206
	v_lshrrev_b32_e32 v3, 16, v3
	v_add3_u32 v4, v36, v4, s45
	ds_read2_b32 v[44:45], v22 offset0:231 offset1:239
	v_and_or_b32 v15, v4, s46, v3
	s_waitcnt lgkmcnt(3)
	v_bfe_u32 v3, v38, 16, 1
	v_add3_u32 v3, v38, v3, s45
	s_waitcnt lgkmcnt(2)
	v_bfe_u32 v4, v40, 16, 1
	v_lshrrev_b32_e32 v3, 16, v3
	v_add3_u32 v4, v40, v4, s45
	v_and_or_b32 v16, v4, s46, v3
	s_waitcnt lgkmcnt(1)
	v_bfe_u32 v3, v42, 16, 1
	v_add3_u32 v3, v42, v3, s45
	s_waitcnt lgkmcnt(0)
	v_bfe_u32 v4, v44, 16, 1
	v_lshrrev_b32_e32 v3, 16, v3
	v_add3_u32 v4, v44, v4, s45
	v_and_or_b32 v17, v4, s46, v3
	v_or_b32_e32 v3, v13, v21
	v_mul_u32_u24_e32 v3, 0x1600, v3
	v_lshlrev_b32_e32 v4, 1, v3
	v_bfe_u32 v3, v19, 16, 1
	v_lshl_add_u64 v[46:47], v[30:31], 0, v[4:5]
	v_add3_u32 v3, v19, v3, s45
	v_bfe_u32 v4, v33, 16, 1
	v_lshrrev_b32_e32 v3, 16, v3
	v_add3_u32 v4, v33, v4, s45
	global_store_dwordx4 v[46:47], v[14:17], off
	ds_read2_b32 v[18:19], v22 offset0:16 offset1:24
	v_readlane_b32 s66, v253, 1
	v_and_or_b32 v14, v4, s46, v3
	v_bfe_u32 v3, v35, 16, 1
	v_add3_u32 v3, v35, v3, s45
	v_bfe_u32 v4, v37, 16, 1
	v_lshrrev_b32_e32 v3, 16, v3
	v_add3_u32 v4, v37, v4, s45
	v_and_or_b32 v15, v4, s46, v3
	v_bfe_u32 v3, v39, 16, 1
	v_add3_u32 v3, v39, v3, s45
	v_bfe_u32 v4, v41, 16, 1
	v_lshrrev_b32_e32 v3, 16, v3
	v_add3_u32 v4, v41, v4, s45
	v_and_or_b32 v16, v4, s46, v3
	v_bfe_u32 v3, v43, 16, 1
	v_add3_u32 v3, v43, v3, s45
	v_bfe_u32 v4, v45, 16, 1
	v_lshrrev_b32_e32 v3, 16, v3
	v_add3_u32 v4, v45, v4, s45
	v_and_or_b32 v17, v4, s46, v3
	v_or_b32_e32 v3, v13, v23
	v_mul_u32_u24_e32 v3, 0x1600, v3
	v_lshlrev_b32_e32 v4, 1, v3
	v_lshl_add_u64 v[32:33], v[30:31], 0, v[4:5]
	global_store_dwordx4 v[32:33], v[14:17], off
	ds_read2_b32 v[32:33], v22 offset0:49 offset1:57
	ds_read2_b32 v[34:35], v22 offset0:82 offset1:90
	ds_read2_b32 v[36:37], v22 offset0:115 offset1:123
	s_waitcnt lgkmcnt(3)
	v_bfe_u32 v3, v18, 16, 1
	v_add3_u32 v3, v18, v3, s45
	s_waitcnt lgkmcnt(2)
	v_bfe_u32 v4, v32, 16, 1
	ds_read2_b32 v[38:39], v22 offset0:148 offset1:156
	v_lshrrev_b32_e32 v3, 16, v3
	v_add3_u32 v4, v32, v4, s45
	ds_read2_b32 v[40:41], v22 offset0:181 offset1:189
	v_and_or_b32 v14, v4, s46, v3
	s_waitcnt lgkmcnt(3)
	v_bfe_u32 v3, v34, 16, 1
	v_add3_u32 v3, v34, v3, s45
	s_waitcnt lgkmcnt(2)
	v_bfe_u32 v4, v36, 16, 1
	ds_read2_b32 v[42:43], v22 offset0:214 offset1:222
	v_lshrrev_b32_e32 v3, 16, v3
	v_add3_u32 v4, v36, v4, s45
	ds_read2_b32 v[44:45], v22 offset0:247 offset1:255
	v_and_or_b32 v15, v4, s46, v3
	s_waitcnt lgkmcnt(3)
	v_bfe_u32 v3, v38, 16, 1
	v_add3_u32 v3, v38, v3, s45
	s_waitcnt lgkmcnt(2)
	v_bfe_u32 v4, v40, 16, 1
	v_lshrrev_b32_e32 v3, 16, v3
	v_add3_u32 v4, v40, v4, s45
	v_and_or_b32 v16, v4, s46, v3
	s_waitcnt lgkmcnt(1)
	v_bfe_u32 v3, v42, 16, 1
	v_add3_u32 v3, v42, v3, s45
	s_waitcnt lgkmcnt(0)
	v_bfe_u32 v4, v44, 16, 1
	v_lshrrev_b32_e32 v3, 16, v3
	v_add3_u32 v4, v44, v4, s45
	v_and_or_b32 v17, v4, s46, v3
	v_or_b32_e32 v3, v13, v24
	v_mul_u32_u24_e32 v3, 0x1600, v3
	v_lshlrev_b32_e32 v4, 1, v3
	v_bfe_u32 v3, v19, 16, 1
	v_lshl_add_u64 v[46:47], v[30:31], 0, v[4:5]
	v_add3_u32 v3, v19, v3, s45
	v_bfe_u32 v4, v33, 16, 1
	v_lshrrev_b32_e32 v3, 16, v3
	v_add3_u32 v4, v33, v4, s45
	global_store_dwordx4 v[46:47], v[14:17], off
	s_nop 1
	v_and_or_b32 v14, v4, s46, v3
	v_bfe_u32 v3, v35, 16, 1
	v_add3_u32 v3, v35, v3, s45
	v_bfe_u32 v4, v37, 16, 1
	v_lshrrev_b32_e32 v3, 16, v3
	v_add3_u32 v4, v37, v4, s45
	v_and_or_b32 v15, v4, s46, v3
	v_bfe_u32 v3, v39, 16, 1
	v_add3_u32 v3, v39, v3, s45
	v_bfe_u32 v4, v41, 16, 1
	v_lshrrev_b32_e32 v3, 16, v3
	v_add3_u32 v4, v41, v4, s45
	v_and_or_b32 v16, v4, s46, v3
	v_bfe_u32 v3, v43, 16, 1
	v_add3_u32 v3, v43, v3, s45
	v_bfe_u32 v4, v45, 16, 1
	v_lshrrev_b32_e32 v3, 16, v3
	v_add3_u32 v4, v45, v4, s45
	v_and_or_b32 v17, v4, s46, v3
	v_or_b32_e32 v3, v13, v25
	v_mul_u32_u24_e32 v3, 0x1600, v3
	v_lshlrev_b32_e32 v4, 1, v3
	v_lshl_add_u64 v[12:13], v[30:31], 0, v[4:5]
	global_store_dwordx4 v[12:13], v[14:17], off
	s_waitcnt lgkmcnt(0)

.LBB0_125:
	s_andn2_saveexec_b64 s[30:31], s[30:31]
	s_cbranch_execz .LBB0_129
	s_load_dwordx2 s[34:35], s[6:7], 0x98
	v_add_u16_e32 v3, 0xd1c0, v3
	v_mul_u32_u24_e32 v4, 0xba2f, v3
	v_lshrrev_b32_e32 v4, 23, v4
	v_mul_lo_u16_e32 v9, 0xb0, v4
	v_sub_u16_e32 v13, v3, v9
	s_waitcnt lgkmcnt(0)
	v_mov_b64_e32 v[16:17], s[34:35]
	v_mad_i64_i32 v[14:15], s[36:37], v12, s49, 0
	v_mad_i64_i32 v[16:17], s[34:35], v12, s49, v[16:17]
	v_lshlrev_b16_e32 v12, 6, v4
	v_lshlrev_b32_e32 v4, 7, v13
	v_lshl_add_u64 v[16:17], v[16:17], 0, v[4:5]
	v_mov_b32_e32 v9, v5
	v_lshlrev_b32_e32 v11, 5, v13
	v_lshl_add_u64 v[16:17], v[16:17], 0, v[8:9]
	v_mov_b32_e32 v3, v12
	s_mov_b32 s34, 1
	s_mov_b32 s35, 0
	s_mov_b32 s36, 32
	s_lshl_b32 s37, s34, 1
	s_lshl_b32 s58, s35, 1
	v_or_b32_e32 v104, s37, v1
	v_or_b32_e32 v109, s58, v2
	s_add_i32 s59, s37, 4
	s_add_i32 s60, s58, 4
	s_add_i32 s61, s37, 8
	s_add_i32 s62, s58, 8
	s_add_i32 s63, s37, 12
	s_add_i32 s64, s58, 12
	s_add_i32 s65, s37, 16
	s_add_i32 s66, s58, 16
	s_add_i32 s67, s37, 20
	s_add_i32 s68, s58, 20
	s_add_i32 s69, s37, 24
	s_add_i32 s70, s58, 24
	s_add_i32 s37, s37, 28
	s_add_i32 s58, s58, 28
	v_add_u32_e32 v129, v104, v3
	v_add_u32_e32 v118, v109, v12
	v_or_b32_e32 v160, s59, v1
	v_or_b32_e32 v161, s60, v2
	v_or_b32_e32 v162, s61, v1
	v_or_b32_e32 v163, s62, v2
	v_or_b32_e32 v164, s63, v1
	v_or_b32_e32 v165, s64, v2
	v_or_b32_e32 v166, s65, v1
	v_or_b32_e32 v167, s66, v2
	v_or_b32_e32 v168, s67, v1
	v_or_b32_e32 v169, s68, v2
	v_or_b32_e32 v170, s69, v1
	v_or_b32_e32 v171, s70, v2
	v_or_b32_e32 v172, s37, v1
	v_or_b32_e32 v173, s58, v2
	v_mad_u64_u32 v[118:119], s[58:59], v118, s51, v[16:17]
	v_mad_u64_u32 v[130:131], s[58:59], v129, s51, v[16:17]
	v_add_u32_e32 v129, v160, v3
	v_add_u32_e32 v132, v161, v12
	v_add_u32_e32 v138, v162, v3
	v_add_u32_e32 v136, v163, v12
	v_add_u32_e32 v142, v164, v3
	v_add_u32_e32 v140, v165, v12
	v_add_u32_e32 v146, v166, v3
	v_add_u32_e32 v144, v167, v12
	v_add_u32_e32 v150, v168, v3
	v_add_u32_e32 v148, v169, v12
	v_add_u32_e32 v154, v170, v3
	v_add_u32_e32 v152, v171, v12
	v_add_u32_e32 v158, v172, v3
	v_add_u32_e32 v156, v173, v12
	v_mad_u64_u32 v[132:133], s[58:59], v132, s51, v[16:17]
	v_mad_u64_u32 v[134:135], s[58:59], v129, s51, v[16:17]
	v_mad_u64_u32 v[136:137], s[58:59], v136, s51, v[16:17]
	v_mad_u64_u32 v[138:139], s[58:59], v138, s51, v[16:17]
	v_mad_u64_u32 v[140:141], s[58:59], v140, s51, v[16:17]
	v_mad_u64_u32 v[142:143], s[58:59], v142, s51, v[16:17]
	v_mad_u64_u32 v[144:145], s[58:59], v144, s51, v[16:17]
	v_mad_u64_u32 v[146:147], s[58:59], v146, s51, v[16:17]
	v_mad_u64_u32 v[148:149], s[58:59], v148, s51, v[16:17]
	v_mad_u64_u32 v[150:151], s[58:59], v150, s51, v[16:17]
	v_mad_u64_u32 v[152:153], s[58:59], v152, s51, v[16:17]
	v_mad_u64_u32 v[154:155], s[58:59], v154, s51, v[16:17]
	v_mad_u64_u32 v[156:157], s[58:59], v156, s51, v[16:17]
	v_mad_u64_u32 v[158:159], s[58:59], v158, s51, v[16:17]
	global_load_dword v129, v[118:119], off
	global_load_dword v174, v[130:131], off
	global_load_dword v175, v[132:133], off
	global_load_dword v176, v[134:135], off
	global_load_dword v177, v[136:137], off
	global_load_dword v178, v[138:139], off
	global_load_dword v179, v[140:141], off
	global_load_dword v180, v[142:143], off
	global_load_dword v181, v[144:145], off
	global_load_dword v182, v[146:147], off
	global_load_dword v183, v[148:149], off
	global_load_dword v184, v[150:151], off
	global_load_dword v185, v[152:153], off
	global_load_dword v186, v[154:155], off
	global_load_dword v187, v[156:157], off
	global_load_dword v188, v[158:159], off
	s_add_i32 s35, s35, 16
	s_add_i32 s34, s34, 16
	s_add_i32 s36, s36, -16
	v_mad_u64_u32 v[118:119], s[58:59], v109, s33, v[6:7]
	v_mad_u64_u32 v[130:131], s[58:59], v104, s33, v[6:7]
	v_mad_u64_u32 v[132:133], s[58:59], v161, s33, v[6:7]
	v_mad_u64_u32 v[134:135], s[58:59], v160, s33, v[6:7]
	v_mad_u64_u32 v[136:137], s[58:59], v163, s33, v[6:7]
	v_mad_u64_u32 v[138:139], s[58:59], v162, s33, v[6:7]
	v_mad_u64_u32 v[140:141], s[58:59], v165, s33, v[6:7]
	v_mad_u64_u32 v[142:143], s[58:59], v164, s33, v[6:7]
	v_mad_u64_u32 v[144:145], s[58:59], v167, s33, v[6:7]
	v_mad_u64_u32 v[146:147], s[58:59], v166, s33, v[6:7]
	v_mad_u64_u32 v[148:149], s[58:59], v169, s33, v[6:7]
	v_mad_u64_u32 v[150:151], s[58:59], v168, s33, v[6:7]
	v_mad_u64_u32 v[152:153], s[58:59], v171, s33, v[6:7]
	v_mad_u64_u32 v[154:155], s[58:59], v170, s33, v[6:7]
	v_mad_u64_u32 v[156:157], s[58:59], v173, s33, v[6:7]
	v_mad_u64_u32 v[158:159], s[58:59], v172, s33, v[6:7]
	s_lshl_b32 s37, s34, 1
	s_lshl_b32 s58, s35, 1
	v_or_b32_e32 v4, s37, v1
	v_or_b32_e32 v9, s58, v2
	s_add_i32 s59, s37, 4
	s_add_i32 s60, s58, 4
	s_add_i32 s61, s37, 8
	s_add_i32 s62, s58, 8
	s_add_i32 s63, s37, 12
	s_add_i32 s64, s58, 12
	s_add_i32 s65, s37, 16
	s_add_i32 s66, s58, 16
	s_add_i32 s67, s37, 20
	s_add_i32 s68, s58, 20
	s_add_i32 s69, s37, 24
	s_add_i32 s70, s58, 24
	s_add_i32 s37, s37, 28
	s_add_i32 s58, s58, 28
	v_add_u32_e32 v29, v4, v3
	v_add_u32_e32 v18, v9, v12
	v_or_b32_e32 v60, s59, v1
	v_or_b32_e32 v61, s60, v2
	v_or_b32_e32 v62, s61, v1
	v_or_b32_e32 v63, s62, v2
	v_or_b32_e32 v64, s63, v1
	v_or_b32_e32 v65, s64, v2
	v_or_b32_e32 v66, s65, v1
	v_or_b32_e32 v67, s66, v2
	v_or_b32_e32 v68, s67, v1
	v_or_b32_e32 v69, s68, v2
	v_or_b32_e32 v70, s69, v1
	v_or_b32_e32 v71, s70, v2
	v_or_b32_e32 v72, s37, v1
	v_or_b32_e32 v73, s58, v2
	v_mad_u64_u32 v[18:19], s[58:59], v18, s51, v[16:17]
	v_mad_u64_u32 v[30:31], s[58:59], v29, s51, v[16:17]
	v_add_u32_e32 v29, v60, v3
	v_add_u32_e32 v32, v61, v12
	v_add_u32_e32 v38, v62, v3
	v_add_u32_e32 v36, v63, v12
	v_add_u32_e32 v42, v64, v3
	v_add_u32_e32 v40, v65, v12
	v_add_u32_e32 v46, v66, v3
	v_add_u32_e32 v44, v67, v12
	v_add_u32_e32 v50, v68, v3
	v_add_u32_e32 v48, v69, v12
	v_add_u32_e32 v54, v70, v3
	v_add_u32_e32 v52, v71, v12
	v_add_u32_e32 v58, v72, v3
	v_add_u32_e32 v56, v73, v12
	v_mad_u64_u32 v[32:33], s[58:59], v32, s51, v[16:17]
	v_mad_u64_u32 v[34:35], s[58:59], v29, s51, v[16:17]
	v_mad_u64_u32 v[36:37], s[58:59], v36, s51, v[16:17]
	v_mad_u64_u32 v[38:39], s[58:59], v38, s51, v[16:17]
	v_mad_u64_u32 v[40:41], s[58:59], v40, s51, v[16:17]
	v_mad_u64_u32 v[42:43], s[58:59], v42, s51, v[16:17]
	v_mad_u64_u32 v[44:45], s[58:59], v44, s51, v[16:17]
	v_mad_u64_u32 v[46:47], s[58:59], v46, s51, v[16:17]
	v_mad_u64_u32 v[48:49], s[58:59], v48, s51, v[16:17]
	v_mad_u64_u32 v[50:51], s[58:59], v50, s51, v[16:17]
	v_mad_u64_u32 v[52:53], s[58:59], v52, s51, v[16:17]
	v_mad_u64_u32 v[54:55], s[58:59], v54, s51, v[16:17]
	v_mad_u64_u32 v[56:57], s[58:59], v56, s51, v[16:17]
	v_mad_u64_u32 v[58:59], s[58:59], v58, s51, v[16:17]
	global_load_dword v29, v[18:19], off
	global_load_dword v74, v[30:31], off
	global_load_dword v75, v[32:33], off
	global_load_dword v76, v[34:35], off
	global_load_dword v77, v[36:37], off
	global_load_dword v78, v[38:39], off
	global_load_dword v79, v[40:41], off
	global_load_dword v80, v[42:43], off
	global_load_dword v81, v[44:45], off
	global_load_dword v82, v[46:47], off
	global_load_dword v83, v[48:49], off
	global_load_dword v84, v[50:51], off
	global_load_dword v85, v[52:53], off
	global_load_dword v86, v[54:55], off
	global_load_dword v87, v[56:57], off
	global_load_dword v88, v[58:59], off
	s_add_i32 s35, s35, 16
	s_add_i32 s34, s34, 16
	s_add_i32 s36, s36, -16
	v_mad_u64_u32 v[18:19], s[58:59], v9, s33, v[6:7]
	v_mad_u64_u32 v[30:31], s[58:59], v4, s33, v[6:7]
	v_mad_u64_u32 v[32:33], s[58:59], v61, s33, v[6:7]
	v_mad_u64_u32 v[34:35], s[58:59], v60, s33, v[6:7]
	v_mad_u64_u32 v[36:37], s[58:59], v63, s33, v[6:7]
	v_mad_u64_u32 v[38:39], s[58:59], v62, s33, v[6:7]
	v_mad_u64_u32 v[40:41], s[58:59], v65, s33, v[6:7]
	v_mad_u64_u32 v[42:43], s[58:59], v64, s33, v[6:7]
	v_mad_u64_u32 v[44:45], s[58:59], v67, s33, v[6:7]
	v_mad_u64_u32 v[46:47], s[58:59], v66, s33, v[6:7]
	v_mad_u64_u32 v[48:49], s[58:59], v69, s33, v[6:7]
	v_mad_u64_u32 v[50:51], s[58:59], v68, s33, v[6:7]
	v_mad_u64_u32 v[52:53], s[58:59], v71, s33, v[6:7]
	v_mad_u64_u32 v[54:55], s[58:59], v70, s33, v[6:7]
	v_mad_u64_u32 v[56:57], s[58:59], v73, s33, v[6:7]
	v_mad_u64_u32 v[58:59], s[58:59], v72, s33, v[6:7]
	s_waitcnt vmcnt(31)
	ds_write_b32 v118, v129
	s_waitcnt vmcnt(30)
	ds_write_b32 v130, v174
	s_waitcnt vmcnt(29)
	ds_write_b32 v132, v175
	s_waitcnt vmcnt(28)
	ds_write_b32 v134, v176
	s_waitcnt vmcnt(27)
	ds_write_b32 v136, v177
	s_waitcnt vmcnt(26)
	ds_write_b32 v138, v178
	s_waitcnt vmcnt(25)
	ds_write_b32 v140, v179
	s_waitcnt vmcnt(24)
	ds_write_b32 v142, v180
	s_waitcnt vmcnt(23)
	ds_write_b32 v144, v181
	s_waitcnt vmcnt(22)
	ds_write_b32 v146, v182
	s_waitcnt vmcnt(21)
	ds_write_b32 v148, v183
	s_waitcnt vmcnt(20)
	ds_write_b32 v150, v184
	s_waitcnt vmcnt(19)
	ds_write_b32 v152, v185
	s_waitcnt vmcnt(18)
	ds_write_b32 v154, v186
	s_waitcnt vmcnt(17)
	ds_write_b32 v156, v187
	s_waitcnt vmcnt(16)
	ds_write_b32 v158, v188
	s_waitcnt vmcnt(15)
	ds_write_b32 v18, v29
	s_waitcnt vmcnt(14)
	ds_write_b32 v30, v74
	s_waitcnt vmcnt(13)
	ds_write_b32 v32, v75
	s_waitcnt vmcnt(12)
	ds_write_b32 v34, v76
	s_waitcnt vmcnt(11)
	ds_write_b32 v36, v77
	s_waitcnt vmcnt(10)
	ds_write_b32 v38, v78
	s_waitcnt vmcnt(9)
	ds_write_b32 v40, v79
	s_waitcnt vmcnt(8)
	ds_write_b32 v42, v80
	s_waitcnt vmcnt(7)
	ds_write_b32 v44, v81
	s_waitcnt vmcnt(6)
	ds_write_b32 v46, v82
	s_waitcnt vmcnt(5)
	ds_write_b32 v48, v83
	s_waitcnt vmcnt(4)
	ds_write_b32 v50, v84
	s_waitcnt vmcnt(3)
	ds_write_b32 v52, v85
	s_waitcnt vmcnt(2)
	ds_write_b32 v54, v86
	s_waitcnt vmcnt(1)
	ds_write_b32 v56, v87
	s_waitcnt vmcnt(0)
	ds_write_b32 v58, v88
	s_waitcnt lgkmcnt(0)
	ds_read2_b32 v[16:17], v22 offset1:8
	ds_read2_b32 v[30:31], v22 offset0:33 offset1:41
	v_lshlrev_b32_e32 v3, 6, v13
	v_and_b32_e32 v3, 0x3f00, v3
	v_and_b32_e32 v4, 0x60, v11
	ds_read2_b32 v[32:33], v22 offset0:66 offset1:74
	v_lshl_add_u64 v[14:15], s[14:15], 0, v[14:15]
	v_or3_b32 v3, v3, v4, s53
	v_lshlrev_b32_e32 v4, 1, v12
	ds_read2_b32 v[34:35], v22 offset0:99 offset1:107
	v_lshl_add_u64 v[12:13], v[14:15], 0, v[4:5]
	s_waitcnt lgkmcnt(3)
	v_bfe_u32 v4, v16, 16, 1
	v_add3_u32 v4, v16, v4, s45
	s_waitcnt lgkmcnt(2)
	v_bfe_u32 v9, v30, 16, 1
	ds_read2_b32 v[36:37], v22 offset0:132 offset1:140
	v_mov_b32_e32 v11, v5
	v_lshrrev_b32_e32 v4, 16, v4
	v_add3_u32 v9, v30, v9, s45
	ds_read2_b32 v[38:39], v22 offset0:165 offset1:173
	v_lshl_add_u64 v[18:19], v[12:13], 0, v[10:11]
	v_and_or_b32 v12, v9, s46, v4
	s_waitcnt lgkmcnt(3)
	v_bfe_u32 v4, v32, 16, 1
	v_add3_u32 v4, v32, v4, s45
	s_waitcnt lgkmcnt(2)
	v_bfe_u32 v9, v34, 16, 1
	ds_read2_b32 v[40:41], v22 offset0:198 offset1:206
	v_lshrrev_b32_e32 v4, 16, v4
	v_add3_u32 v9, v34, v9, s45
	ds_read2_b32 v[42:43], v22 offset0:231 offset1:239
	v_and_or_b32 v13, v9, s46, v4
	s_waitcnt lgkmcnt(3)
	v_bfe_u32 v4, v36, 16, 1
	v_add3_u32 v4, v36, v4, s45
	s_waitcnt lgkmcnt(2)
	v_bfe_u32 v9, v38, 16, 1
	v_lshrrev_b32_e32 v4, 16, v4
	v_add3_u32 v9, v38, v9, s45
	v_and_or_b32 v14, v9, s46, v4
	s_waitcnt lgkmcnt(1)
	v_bfe_u32 v4, v40, 16, 1
	v_add3_u32 v4, v40, v4, s45
	s_waitcnt lgkmcnt(0)
	v_bfe_u32 v9, v42, 16, 1
	v_lshrrev_b32_e32 v4, 16, v4
	v_add3_u32 v9, v42, v9, s45
	v_and_or_b32 v15, v9, s46, v4
	v_or_b32_e32 v4, v3, v21
	v_lshlrev_b32_e32 v4, 12, v4
	v_lshl_add_u64 v[44:45], v[18:19], 0, v[4:5]
	v_bfe_u32 v4, v17, 16, 1
	v_add3_u32 v4, v17, v4, s45
	v_bfe_u32 v9, v31, 16, 1
	v_lshrrev_b32_e32 v4, 16, v4
	v_add3_u32 v9, v31, v9, s45
	global_store_dwordx4 v[44:45], v[12:15], off
	ds_read2_b32 v[16:17], v22 offset0:16 offset1:24
	v_readlane_b32 s66, v253, 1
	v_and_or_b32 v12, v9, s46, v4
	v_bfe_u32 v4, v33, 16, 1
	v_add3_u32 v4, v33, v4, s45
	v_bfe_u32 v9, v35, 16, 1
	v_lshrrev_b32_e32 v4, 16, v4
	v_add3_u32 v9, v35, v9, s45
	v_and_or_b32 v13, v9, s46, v4
	v_bfe_u32 v4, v37, 16, 1
	v_add3_u32 v4, v37, v4, s45
	v_bfe_u32 v9, v39, 16, 1
	v_lshrrev_b32_e32 v4, 16, v4
	v_add3_u32 v9, v39, v9, s45
	v_and_or_b32 v14, v9, s46, v4
	v_bfe_u32 v4, v41, 16, 1
	v_add3_u32 v4, v41, v4, s45
	v_bfe_u32 v9, v43, 16, 1
	v_lshrrev_b32_e32 v4, 16, v4
	v_add3_u32 v9, v43, v9, s45
	v_and_or_b32 v15, v9, s46, v4
	v_or_b32_e32 v4, v3, v23
	v_lshlrev_b32_e32 v4, 12, v4
	v_lshl_add_u64 v[30:31], v[18:19], 0, v[4:5]
	global_store_dwordx4 v[30:31], v[12:15], off
	ds_read2_b32 v[30:31], v22 offset0:49 offset1:57
	ds_read2_b32 v[32:33], v22 offset0:82 offset1:90
	ds_read2_b32 v[34:35], v22 offset0:115 offset1:123
	s_waitcnt lgkmcnt(3)
	v_bfe_u32 v4, v16, 16, 1
	v_add3_u32 v4, v16, v4, s45
	s_waitcnt lgkmcnt(2)
	v_bfe_u32 v9, v30, 16, 1
	ds_read2_b32 v[36:37], v22 offset0:148 offset1:156
	v_lshrrev_b32_e32 v4, 16, v4
	v_add3_u32 v9, v30, v9, s45
	ds_read2_b32 v[38:39], v22 offset0:181 offset1:189
	v_and_or_b32 v12, v9, s46, v4
	s_waitcnt lgkmcnt(3)
	v_bfe_u32 v4, v32, 16, 1
	v_add3_u32 v4, v32, v4, s45
	s_waitcnt lgkmcnt(2)
	v_bfe_u32 v9, v34, 16, 1
	ds_read2_b32 v[40:41], v22 offset0:214 offset1:222
	v_lshrrev_b32_e32 v4, 16, v4
	v_add3_u32 v9, v34, v9, s45
	ds_read2_b32 v[42:43], v22 offset0:247 offset1:255
	v_and_or_b32 v13, v9, s46, v4
	s_waitcnt lgkmcnt(3)
	v_bfe_u32 v4, v36, 16, 1
	v_add3_u32 v4, v36, v4, s45
	s_waitcnt lgkmcnt(2)
	v_bfe_u32 v9, v38, 16, 1
	v_lshrrev_b32_e32 v4, 16, v4
	v_add3_u32 v9, v38, v9, s45
	v_and_or_b32 v14, v9, s46, v4
	s_waitcnt lgkmcnt(1)
	v_bfe_u32 v4, v40, 16, 1
	v_add3_u32 v4, v40, v4, s45
	s_waitcnt lgkmcnt(0)
	v_bfe_u32 v9, v42, 16, 1
	v_lshrrev_b32_e32 v4, 16, v4
	v_add3_u32 v9, v42, v9, s45
	v_and_or_b32 v15, v9, s46, v4
	v_or_b32_e32 v4, v3, v24
	v_lshlrev_b32_e32 v4, 12, v4
	v_lshl_add_u64 v[44:45], v[18:19], 0, v[4:5]
	v_bfe_u32 v4, v17, 16, 1
	v_add3_u32 v4, v17, v4, s45
	v_bfe_u32 v9, v31, 16, 1
	v_lshrrev_b32_e32 v4, 16, v4
	v_add3_u32 v9, v31, v9, s45
	global_store_dwordx4 v[44:45], v[12:15], off
	v_or_b32_e32 v3, v3, v25
	s_nop 0
	v_and_or_b32 v12, v9, s46, v4
	v_bfe_u32 v4, v33, 16, 1
	v_add3_u32 v4, v33, v4, s45
	v_bfe_u32 v9, v35, 16, 1
	v_lshrrev_b32_e32 v4, 16, v4
	v_add3_u32 v9, v35, v9, s45
	v_and_or_b32 v13, v9, s46, v4
	v_bfe_u32 v4, v37, 16, 1
	v_add3_u32 v4, v37, v4, s45
	v_bfe_u32 v9, v39, 16, 1
	v_lshrrev_b32_e32 v4, 16, v4
	v_add3_u32 v9, v39, v9, s45
	v_and_or_b32 v14, v9, s46, v4
	v_bfe_u32 v4, v41, 16, 1
	v_add3_u32 v4, v41, v4, s45
	v_bfe_u32 v9, v43, 16, 1
	v_lshrrev_b32_e32 v4, 16, v4
	v_add3_u32 v9, v43, v9, s45
	v_and_or_b32 v15, v9, s46, v4
	v_lshlrev_b32_e32 v4, 12, v3
	v_lshl_add_u64 v[16:17], v[18:19], 0, v[4:5]
	global_store_dwordx4 v[16:17], v[12:15], off
	s_waitcnt lgkmcnt(0)

.LBB0_130:
	s_andn2_saveexec_b64 s[28:29], s[28:29]
	s_cbranch_execz .LBB0_134
	s_load_dwordx2 s[30:31], s[6:7], 0x90
	v_add_u16_e32 v3, 0xe7c0, v3
	v_mul_u32_u24_e32 v4, 0xba2f, v3
	v_lshrrev_b32_e32 v4, 23, v4
	v_mul_lo_u16_e32 v9, 0xb0, v4
	v_sub_u16_e32 v11, v3, v9
	s_waitcnt lgkmcnt(0)
	v_mov_b64_e32 v[16:17], s[30:31]
	v_mad_i64_i32 v[14:15], s[34:35], v12, s49, 0
	v_mad_i64_i32 v[16:17], s[30:31], v12, s49, v[16:17]
	v_lshlrev_b16_e32 v12, 6, v4
	v_lshlrev_b32_e32 v4, 7, v11
	v_lshl_add_u64 v[16:17], v[16:17], 0, v[4:5]
	v_mov_b32_e32 v9, v5
	v_lshlrev_b32_e32 v13, 5, v11
	v_lshl_add_u64 v[16:17], v[16:17], 0, v[8:9]
	v_mov_b32_e32 v3, v12
	s_mov_b32 s30, 1
	s_mov_b32 s31, 0
	s_mov_b32 s34, 32
	s_lshl_b32 s35, s30, 1
	s_lshl_b32 s36, s31, 1
	v_or_b32_e32 v104, s35, v1
	v_or_b32_e32 v109, s36, v2
	s_add_i32 s37, s35, 4
	s_add_i32 s58, s36, 4
	s_add_i32 s59, s35, 8
	s_add_i32 s60, s36, 8
	s_add_i32 s61, s35, 12
	s_add_i32 s62, s36, 12
	s_add_i32 s63, s35, 16
	s_add_i32 s64, s36, 16
	s_add_i32 s65, s35, 20
	s_add_i32 s66, s36, 20
	s_add_i32 s67, s35, 24
	s_add_i32 s68, s36, 24
	s_add_i32 s35, s35, 28
	s_add_i32 s36, s36, 28
	v_add_u32_e32 v129, v104, v3
	v_add_u32_e32 v118, v109, v12
	v_or_b32_e32 v160, s37, v1
	v_or_b32_e32 v161, s58, v2
	v_or_b32_e32 v162, s59, v1
	v_or_b32_e32 v163, s60, v2
	v_or_b32_e32 v164, s61, v1
	v_or_b32_e32 v165, s62, v2
	v_or_b32_e32 v166, s63, v1
	v_or_b32_e32 v167, s64, v2
	v_or_b32_e32 v168, s65, v1
	v_or_b32_e32 v169, s66, v2
	v_or_b32_e32 v170, s67, v1
	v_or_b32_e32 v171, s68, v2
	v_or_b32_e32 v172, s35, v1
	v_or_b32_e32 v173, s36, v2
	v_mad_u64_u32 v[118:119], s[36:37], v118, s51, v[16:17]
	v_mad_u64_u32 v[130:131], s[36:37], v129, s51, v[16:17]
	v_add_u32_e32 v129, v160, v3
	v_add_u32_e32 v132, v161, v12
	v_add_u32_e32 v138, v162, v3
	v_add_u32_e32 v136, v163, v12
	v_add_u32_e32 v142, v164, v3
	v_add_u32_e32 v140, v165, v12
	v_add_u32_e32 v146, v166, v3
	v_add_u32_e32 v144, v167, v12
	v_add_u32_e32 v150, v168, v3
	v_add_u32_e32 v148, v169, v12
	v_add_u32_e32 v154, v170, v3
	v_add_u32_e32 v152, v171, v12
	v_add_u32_e32 v158, v172, v3
	v_add_u32_e32 v156, v173, v12
	v_mad_u64_u32 v[132:133], s[36:37], v132, s51, v[16:17]
	v_mad_u64_u32 v[134:135], s[36:37], v129, s51, v[16:17]
	v_mad_u64_u32 v[136:137], s[36:37], v136, s51, v[16:17]
	v_mad_u64_u32 v[138:139], s[36:37], v138, s51, v[16:17]
	v_mad_u64_u32 v[140:141], s[36:37], v140, s51, v[16:17]
	v_mad_u64_u32 v[142:143], s[36:37], v142, s51, v[16:17]
	v_mad_u64_u32 v[144:145], s[36:37], v144, s51, v[16:17]
	v_mad_u64_u32 v[146:147], s[36:37], v146, s51, v[16:17]
	v_mad_u64_u32 v[148:149], s[36:37], v148, s51, v[16:17]
	v_mad_u64_u32 v[150:151], s[36:37], v150, s51, v[16:17]
	v_mad_u64_u32 v[152:153], s[36:37], v152, s51, v[16:17]
	v_mad_u64_u32 v[154:155], s[36:37], v154, s51, v[16:17]
	v_mad_u64_u32 v[156:157], s[36:37], v156, s51, v[16:17]
	v_mad_u64_u32 v[158:159], s[36:37], v158, s51, v[16:17]
	global_load_dword v129, v[118:119], off
	global_load_dword v174, v[130:131], off
	global_load_dword v175, v[132:133], off
	global_load_dword v176, v[134:135], off
	global_load_dword v177, v[136:137], off
	global_load_dword v178, v[138:139], off
	global_load_dword v179, v[140:141], off
	global_load_dword v180, v[142:143], off
	global_load_dword v181, v[144:145], off
	global_load_dword v182, v[146:147], off
	global_load_dword v183, v[148:149], off
	global_load_dword v184, v[150:151], off
	global_load_dword v185, v[152:153], off
	global_load_dword v186, v[154:155], off
	global_load_dword v187, v[156:157], off
	global_load_dword v188, v[158:159], off
	s_add_i32 s31, s31, 16
	s_add_i32 s30, s30, 16
	s_add_i32 s34, s34, -16
	v_mad_u64_u32 v[118:119], s[36:37], v109, s33, v[6:7]
	v_mad_u64_u32 v[130:131], s[36:37], v104, s33, v[6:7]
	v_mad_u64_u32 v[132:133], s[36:37], v161, s33, v[6:7]
	v_mad_u64_u32 v[134:135], s[36:37], v160, s33, v[6:7]
	v_mad_u64_u32 v[136:137], s[36:37], v163, s33, v[6:7]
	v_mad_u64_u32 v[138:139], s[36:37], v162, s33, v[6:7]
	v_mad_u64_u32 v[140:141], s[36:37], v165, s33, v[6:7]
	v_mad_u64_u32 v[142:143], s[36:37], v164, s33, v[6:7]
	v_mad_u64_u32 v[144:145], s[36:37], v167, s33, v[6:7]
	v_mad_u64_u32 v[146:147], s[36:37], v166, s33, v[6:7]
	v_mad_u64_u32 v[148:149], s[36:37], v169, s33, v[6:7]
	v_mad_u64_u32 v[150:151], s[36:37], v168, s33, v[6:7]
	v_mad_u64_u32 v[152:153], s[36:37], v171, s33, v[6:7]
	v_mad_u64_u32 v[154:155], s[36:37], v170, s33, v[6:7]
	v_mad_u64_u32 v[156:157], s[36:37], v173, s33, v[6:7]
	v_mad_u64_u32 v[158:159], s[36:37], v172, s33, v[6:7]
	s_lshl_b32 s35, s30, 1
	s_lshl_b32 s36, s31, 1
	v_or_b32_e32 v4, s35, v1
	v_or_b32_e32 v9, s36, v2
	s_add_i32 s37, s35, 4
	s_add_i32 s58, s36, 4
	s_add_i32 s59, s35, 8
	s_add_i32 s60, s36, 8
	s_add_i32 s61, s35, 12
	s_add_i32 s62, s36, 12
	s_add_i32 s63, s35, 16
	s_add_i32 s64, s36, 16
	s_add_i32 s65, s35, 20
	s_add_i32 s66, s36, 20
	s_add_i32 s67, s35, 24
	s_add_i32 s68, s36, 24
	s_add_i32 s35, s35, 28
	s_add_i32 s36, s36, 28
	v_add_u32_e32 v29, v4, v3
	v_add_u32_e32 v18, v9, v12
	v_or_b32_e32 v60, s37, v1
	v_or_b32_e32 v61, s58, v2
	v_or_b32_e32 v62, s59, v1
	v_or_b32_e32 v63, s60, v2
	v_or_b32_e32 v64, s61, v1
	v_or_b32_e32 v65, s62, v2
	v_or_b32_e32 v66, s63, v1
	v_or_b32_e32 v67, s64, v2
	v_or_b32_e32 v68, s65, v1
	v_or_b32_e32 v69, s66, v2
	v_or_b32_e32 v70, s67, v1
	v_or_b32_e32 v71, s68, v2
	v_or_b32_e32 v72, s35, v1
	v_or_b32_e32 v73, s36, v2
	v_mad_u64_u32 v[18:19], s[36:37], v18, s51, v[16:17]
	v_mad_u64_u32 v[30:31], s[36:37], v29, s51, v[16:17]
	v_add_u32_e32 v29, v60, v3
	v_add_u32_e32 v32, v61, v12
	v_add_u32_e32 v38, v62, v3
	v_add_u32_e32 v36, v63, v12
	v_add_u32_e32 v42, v64, v3
	v_add_u32_e32 v40, v65, v12
	v_add_u32_e32 v46, v66, v3
	v_add_u32_e32 v44, v67, v12
	v_add_u32_e32 v50, v68, v3
	v_add_u32_e32 v48, v69, v12
	v_add_u32_e32 v54, v70, v3
	v_add_u32_e32 v52, v71, v12
	v_add_u32_e32 v58, v72, v3
	v_add_u32_e32 v56, v73, v12
	v_mad_u64_u32 v[32:33], s[36:37], v32, s51, v[16:17]
	v_mad_u64_u32 v[34:35], s[36:37], v29, s51, v[16:17]
	v_mad_u64_u32 v[36:37], s[36:37], v36, s51, v[16:17]
	v_mad_u64_u32 v[38:39], s[36:37], v38, s51, v[16:17]
	v_mad_u64_u32 v[40:41], s[36:37], v40, s51, v[16:17]
	v_mad_u64_u32 v[42:43], s[36:37], v42, s51, v[16:17]
	v_mad_u64_u32 v[44:45], s[36:37], v44, s51, v[16:17]
	v_mad_u64_u32 v[46:47], s[36:37], v46, s51, v[16:17]
	v_mad_u64_u32 v[48:49], s[36:37], v48, s51, v[16:17]
	v_mad_u64_u32 v[50:51], s[36:37], v50, s51, v[16:17]
	v_mad_u64_u32 v[52:53], s[36:37], v52, s51, v[16:17]
	v_mad_u64_u32 v[54:55], s[36:37], v54, s51, v[16:17]
	v_mad_u64_u32 v[56:57], s[36:37], v56, s51, v[16:17]
	v_mad_u64_u32 v[58:59], s[36:37], v58, s51, v[16:17]
	global_load_dword v29, v[18:19], off
	global_load_dword v74, v[30:31], off
	global_load_dword v75, v[32:33], off
	global_load_dword v76, v[34:35], off
	global_load_dword v77, v[36:37], off
	global_load_dword v78, v[38:39], off
	global_load_dword v79, v[40:41], off
	global_load_dword v80, v[42:43], off
	global_load_dword v81, v[44:45], off
	global_load_dword v82, v[46:47], off
	global_load_dword v83, v[48:49], off
	global_load_dword v84, v[50:51], off
	global_load_dword v85, v[52:53], off
	global_load_dword v86, v[54:55], off
	global_load_dword v87, v[56:57], off
	global_load_dword v88, v[58:59], off
	s_add_i32 s31, s31, 16
	s_add_i32 s30, s30, 16
	s_add_i32 s34, s34, -16
	v_mad_u64_u32 v[18:19], s[36:37], v9, s33, v[6:7]
	v_mad_u64_u32 v[30:31], s[36:37], v4, s33, v[6:7]
	v_mad_u64_u32 v[32:33], s[36:37], v61, s33, v[6:7]
	v_mad_u64_u32 v[34:35], s[36:37], v60, s33, v[6:7]
	v_mad_u64_u32 v[36:37], s[36:37], v63, s33, v[6:7]
	v_mad_u64_u32 v[38:39], s[36:37], v62, s33, v[6:7]
	v_mad_u64_u32 v[40:41], s[36:37], v65, s33, v[6:7]
	v_mad_u64_u32 v[42:43], s[36:37], v64, s33, v[6:7]
	v_mad_u64_u32 v[44:45], s[36:37], v67, s33, v[6:7]
	v_mad_u64_u32 v[46:47], s[36:37], v66, s33, v[6:7]
	v_mad_u64_u32 v[48:49], s[36:37], v69, s33, v[6:7]
	v_mad_u64_u32 v[50:51], s[36:37], v68, s33, v[6:7]
	v_mad_u64_u32 v[52:53], s[36:37], v71, s33, v[6:7]
	v_mad_u64_u32 v[54:55], s[36:37], v70, s33, v[6:7]
	v_mad_u64_u32 v[56:57], s[36:37], v73, s33, v[6:7]
	v_mad_u64_u32 v[58:59], s[36:37], v72, s33, v[6:7]
	s_waitcnt vmcnt(31)
	ds_write_b32 v118, v129
	s_waitcnt vmcnt(30)
	ds_write_b32 v130, v174
	s_waitcnt vmcnt(29)
	ds_write_b32 v132, v175
	s_waitcnt vmcnt(28)
	ds_write_b32 v134, v176
	s_waitcnt vmcnt(27)
	ds_write_b32 v136, v177
	s_waitcnt vmcnt(26)
	ds_write_b32 v138, v178
	s_waitcnt vmcnt(25)
	ds_write_b32 v140, v179
	s_waitcnt vmcnt(24)
	ds_write_b32 v142, v180
	s_waitcnt vmcnt(23)
	ds_write_b32 v144, v181
	s_waitcnt vmcnt(22)
	ds_write_b32 v146, v182
	s_waitcnt vmcnt(21)
	ds_write_b32 v148, v183
	s_waitcnt vmcnt(20)
	ds_write_b32 v150, v184
	s_waitcnt vmcnt(19)
	ds_write_b32 v152, v185
	s_waitcnt vmcnt(18)
	ds_write_b32 v154, v186
	s_waitcnt vmcnt(17)
	ds_write_b32 v156, v187
	s_waitcnt vmcnt(16)
	ds_write_b32 v158, v188
	s_waitcnt vmcnt(15)
	ds_write_b32 v18, v29
	s_waitcnt vmcnt(14)
	ds_write_b32 v30, v74
	s_waitcnt vmcnt(13)
	ds_write_b32 v32, v75
	s_waitcnt vmcnt(12)
	ds_write_b32 v34, v76
	s_waitcnt vmcnt(11)
	ds_write_b32 v36, v77
	s_waitcnt vmcnt(10)
	ds_write_b32 v38, v78
	s_waitcnt vmcnt(9)
	ds_write_b32 v40, v79
	s_waitcnt vmcnt(8)
	ds_write_b32 v42, v80
	s_waitcnt vmcnt(7)
	ds_write_b32 v44, v81
	s_waitcnt vmcnt(6)
	ds_write_b32 v46, v82
	s_waitcnt vmcnt(5)
	ds_write_b32 v48, v83
	s_waitcnt vmcnt(4)
	ds_write_b32 v50, v84
	s_waitcnt vmcnt(3)
	ds_write_b32 v52, v85
	s_waitcnt vmcnt(2)
	ds_write_b32 v54, v86
	s_waitcnt vmcnt(1)
	ds_write_b32 v56, v87
	s_waitcnt vmcnt(0)
	ds_write_b32 v58, v88
	s_waitcnt lgkmcnt(0)
	ds_read2_b32 v[16:17], v22 offset1:8
	ds_read2_b32 v[30:31], v22 offset0:33 offset1:41
	v_lshlrev_b32_e32 v3, 6, v11
	v_and_b32_e32 v4, 0x60, v13
	ds_read2_b32 v[32:33], v22 offset0:66 offset1:74
	v_lshl_add_u64 v[14:15], s[14:15], 0, v[14:15]
	v_and_or_b32 v3, v3, s52, v4
	v_lshlrev_b32_e32 v4, 1, v12
	ds_read2_b32 v[34:35], v22 offset0:99 offset1:107
	v_lshl_add_u64 v[12:13], v[14:15], 0, v[4:5]
	s_waitcnt lgkmcnt(3)
	v_bfe_u32 v4, v16, 16, 1
	v_add3_u32 v4, v16, v4, s45
	s_waitcnt lgkmcnt(2)
	v_bfe_u32 v9, v30, 16, 1
	ds_read2_b32 v[36:37], v22 offset0:132 offset1:140
	v_mov_b32_e32 v11, v5
	v_lshrrev_b32_e32 v4, 16, v4
	v_add3_u32 v9, v30, v9, s45
	ds_read2_b32 v[38:39], v22 offset0:165 offset1:173
	v_lshl_add_u64 v[18:19], v[12:13], 0, v[10:11]
	v_and_or_b32 v12, v9, s46, v4
	s_waitcnt lgkmcnt(3)
	v_bfe_u32 v4, v32, 16, 1
	v_add3_u32 v4, v32, v4, s45
	s_waitcnt lgkmcnt(2)
	v_bfe_u32 v9, v34, 16, 1
	ds_read2_b32 v[40:41], v22 offset0:198 offset1:206
	v_lshrrev_b32_e32 v4, 16, v4
	v_add3_u32 v9, v34, v9, s45
	ds_read2_b32 v[42:43], v22 offset0:231 offset1:239
	v_and_or_b32 v13, v9, s46, v4
	s_waitcnt lgkmcnt(3)
	v_bfe_u32 v4, v36, 16, 1
	v_add3_u32 v4, v36, v4, s45
	s_waitcnt lgkmcnt(2)
	v_bfe_u32 v9, v38, 16, 1
	v_lshrrev_b32_e32 v4, 16, v4
	v_add3_u32 v9, v38, v9, s45
	v_and_or_b32 v14, v9, s46, v4
	s_waitcnt lgkmcnt(1)
	v_bfe_u32 v4, v40, 16, 1
	v_add3_u32 v4, v40, v4, s45
	s_waitcnt lgkmcnt(0)
	v_bfe_u32 v9, v42, 16, 1
	v_lshrrev_b32_e32 v4, 16, v4
	v_add3_u32 v9, v42, v9, s45
	v_and_or_b32 v15, v9, s46, v4
	v_or_b32_e32 v4, v3, v21
	v_lshlrev_b32_e32 v4, 12, v4
	v_lshl_add_u64 v[44:45], v[18:19], 0, v[4:5]
	v_bfe_u32 v4, v17, 16, 1
	v_add3_u32 v4, v17, v4, s45
	v_bfe_u32 v9, v31, 16, 1
	v_lshrrev_b32_e32 v4, 16, v4
	v_add3_u32 v9, v31, v9, s45
	global_store_dwordx4 v[44:45], v[12:15], off
	ds_read2_b32 v[16:17], v22 offset0:16 offset1:24
	v_readlane_b32 s66, v253, 1
	v_and_or_b32 v12, v9, s46, v4
	v_bfe_u32 v4, v33, 16, 1
	v_add3_u32 v4, v33, v4, s45
	v_bfe_u32 v9, v35, 16, 1
	v_lshrrev_b32_e32 v4, 16, v4
	v_add3_u32 v9, v35, v9, s45
	v_and_or_b32 v13, v9, s46, v4
	v_bfe_u32 v4, v37, 16, 1
	v_add3_u32 v4, v37, v4, s45
	v_bfe_u32 v9, v39, 16, 1
	v_lshrrev_b32_e32 v4, 16, v4
	v_add3_u32 v9, v39, v9, s45
	v_and_or_b32 v14, v9, s46, v4
	v_bfe_u32 v4, v41, 16, 1
	v_add3_u32 v4, v41, v4, s45
	v_bfe_u32 v9, v43, 16, 1
	v_lshrrev_b32_e32 v4, 16, v4
	v_add3_u32 v9, v43, v9, s45
	v_and_or_b32 v15, v9, s46, v4
	v_or_b32_e32 v4, v3, v23
	v_lshlrev_b32_e32 v4, 12, v4
	v_lshl_add_u64 v[30:31], v[18:19], 0, v[4:5]
	global_store_dwordx4 v[30:31], v[12:15], off
	ds_read2_b32 v[30:31], v22 offset0:49 offset1:57
	ds_read2_b32 v[32:33], v22 offset0:82 offset1:90
	ds_read2_b32 v[34:35], v22 offset0:115 offset1:123
	s_waitcnt lgkmcnt(3)
	v_bfe_u32 v4, v16, 16, 1
	v_add3_u32 v4, v16, v4, s45
	s_waitcnt lgkmcnt(2)
	v_bfe_u32 v9, v30, 16, 1
	ds_read2_b32 v[36:37], v22 offset0:148 offset1:156
	v_lshrrev_b32_e32 v4, 16, v4
	v_add3_u32 v9, v30, v9, s45
	ds_read2_b32 v[38:39], v22 offset0:181 offset1:189
	v_and_or_b32 v12, v9, s46, v4
	s_waitcnt lgkmcnt(3)
	v_bfe_u32 v4, v32, 16, 1
	v_add3_u32 v4, v32, v4, s45
	s_waitcnt lgkmcnt(2)
	v_bfe_u32 v9, v34, 16, 1
	ds_read2_b32 v[40:41], v22 offset0:214 offset1:222
	v_lshrrev_b32_e32 v4, 16, v4
	v_add3_u32 v9, v34, v9, s45
	ds_read2_b32 v[42:43], v22 offset0:247 offset1:255
	v_and_or_b32 v13, v9, s46, v4
	s_waitcnt lgkmcnt(3)
	v_bfe_u32 v4, v36, 16, 1
	v_add3_u32 v4, v36, v4, s45
	s_waitcnt lgkmcnt(2)
	v_bfe_u32 v9, v38, 16, 1
	v_lshrrev_b32_e32 v4, 16, v4
	v_add3_u32 v9, v38, v9, s45
	v_and_or_b32 v14, v9, s46, v4
	s_waitcnt lgkmcnt(1)
	v_bfe_u32 v4, v40, 16, 1
	v_add3_u32 v4, v40, v4, s45
	s_waitcnt lgkmcnt(0)
	v_bfe_u32 v9, v42, 16, 1
	v_lshrrev_b32_e32 v4, 16, v4
	v_add3_u32 v9, v42, v9, s45
	v_and_or_b32 v15, v9, s46, v4
	v_or_b32_e32 v4, v3, v24
	v_lshlrev_b32_e32 v4, 12, v4
	v_lshl_add_u64 v[44:45], v[18:19], 0, v[4:5]
	v_bfe_u32 v4, v17, 16, 1
	v_add3_u32 v4, v17, v4, s45
	v_bfe_u32 v9, v31, 16, 1
	v_lshrrev_b32_e32 v4, 16, v4
	v_add3_u32 v9, v31, v9, s45
	global_store_dwordx4 v[44:45], v[12:15], off
	v_or_b32_e32 v3, v3, v25
	s_nop 0
	v_and_or_b32 v12, v9, s46, v4
	v_bfe_u32 v4, v33, 16, 1
	v_add3_u32 v4, v33, v4, s45
	v_bfe_u32 v9, v35, 16, 1
	v_lshrrev_b32_e32 v4, 16, v4
	v_add3_u32 v9, v35, v9, s45
	v_and_or_b32 v13, v9, s46, v4
	v_bfe_u32 v4, v37, 16, 1
	v_add3_u32 v4, v37, v4, s45
	v_bfe_u32 v9, v39, 16, 1
	v_lshrrev_b32_e32 v4, 16, v4
	v_add3_u32 v9, v39, v9, s45
	v_and_or_b32 v14, v9, s46, v4
	v_bfe_u32 v4, v41, 16, 1
	v_add3_u32 v4, v41, v4, s45
	v_bfe_u32 v9, v43, 16, 1
	v_lshrrev_b32_e32 v4, 16, v4
	v_add3_u32 v9, v43, v9, s45
	v_and_or_b32 v15, v9, s46, v4
	v_lshlrev_b32_e32 v4, 12, v3
	v_lshl_add_u64 v[16:17], v[18:19], 0, v[4:5]
	global_store_dwordx4 v[16:17], v[12:15], off
	s_waitcnt lgkmcnt(0)

.LBB0_135:
	s_andn2_saveexec_b64 s[26:27], s[26:27]
	s_cbranch_execz .LBB0_139
	s_load_dwordx2 s[28:29], s[6:7], 0x78
	v_and_b32_e32 v4, 0x1fc0, v3
	v_ashrrev_i32_e32 v13, 31, v12
	v_lshlrev_b32_e32 v3, 5, v3
	v_lshlrev_b64 v[16:17], 22, v[12:13]
	v_lshlrev_b64 v[12:13], 24, v[12:13]
	v_and_b32_e32 v18, 0x7e0, v3
	v_add_u32_e32 v14, 0xffffefc0, v4
	s_waitcnt lgkmcnt(0)
	v_lshl_add_u64 v[12:13], s[28:29], 0, v[12:13]
	v_lshlrev_b32_e32 v4, 2, v18
	v_lshl_add_u64 v[12:13], v[12:13], 0, v[4:5]
	v_mov_b32_e32 v9, v5
	v_lshl_add_u64 v[12:13], v[12:13], 0, v[8:9]
	v_mov_b32_e32 v3, v14
	s_mov_b32 s28, 1
	s_mov_b32 s29, 0
	s_mov_b32 s30, 32
	s_lshl_b32 s31, s28, 1
	s_lshl_b32 s34, s29, 1
	v_or_b32_e32 v104, s31, v1
	v_or_b32_e32 v109, s34, v2
	s_add_i32 s35, s31, 4
	s_add_i32 s36, s34, 4
	s_add_i32 s37, s31, 8
	s_add_i32 s58, s34, 8
	s_add_i32 s59, s31, 12
	s_add_i32 s60, s34, 12
	s_add_i32 s61, s31, 16
	s_add_i32 s62, s34, 16
	s_add_i32 s63, s31, 20
	s_add_i32 s64, s34, 20
	s_add_i32 s65, s31, 24
	s_add_i32 s66, s34, 24
	s_add_i32 s31, s31, 28
	s_add_i32 s34, s34, 28
	v_add_u32_e32 v132, v109, v14
	v_or_b32_e32 v111, s35, v1
	v_or_b32_e32 v115, s36, v2
	v_or_b32_e32 v119, s37, v1
	v_or_b32_e32 v129, s58, v2
	v_or_b32_e32 v162, s59, v1
	v_or_b32_e32 v163, s60, v2
	v_or_b32_e32 v164, s61, v1
	v_or_b32_e32 v165, s62, v2
	v_or_b32_e32 v166, s63, v1
	v_or_b32_e32 v167, s64, v2
	v_or_b32_e32 v168, s65, v1
	v_or_b32_e32 v169, s66, v2
	v_or_b32_e32 v170, s31, v1
	v_or_b32_e32 v171, s34, v2
	v_add_u32_e32 v130, v104, v3
	v_ashrrev_i32_e32 v133, 31, v132
	v_add_u32_e32 v134, v111, v3
	v_add_u32_e32 v136, v115, v14
	v_add_u32_e32 v138, v119, v3
	v_add_u32_e32 v140, v129, v14
	v_add_u32_e32 v142, v162, v3
	v_add_u32_e32 v144, v163, v14
	v_add_u32_e32 v146, v164, v3
	v_add_u32_e32 v148, v165, v14
	v_add_u32_e32 v150, v166, v3
	v_add_u32_e32 v152, v167, v14
	v_add_u32_e32 v154, v168, v3
	v_add_u32_e32 v156, v169, v14
	v_add_u32_e32 v158, v170, v3
	v_add_u32_e32 v160, v171, v14
	v_ashrrev_i32_e32 v131, 31, v130
	v_lshlrev_b64 v[132:133], 13, v[132:133]
	v_ashrrev_i32_e32 v137, 31, v136
	v_ashrrev_i32_e32 v135, 31, v134
	v_ashrrev_i32_e32 v141, 31, v140
	v_ashrrev_i32_e32 v139, 31, v138
	v_ashrrev_i32_e32 v145, 31, v144
	v_ashrrev_i32_e32 v143, 31, v142
	v_ashrrev_i32_e32 v149, 31, v148
	v_ashrrev_i32_e32 v147, 31, v146
	v_ashrrev_i32_e32 v153, 31, v152
	v_ashrrev_i32_e32 v151, 31, v150
	v_ashrrev_i32_e32 v157, 31, v156
	v_ashrrev_i32_e32 v155, 31, v154
	v_ashrrev_i32_e32 v161, 31, v160
	v_ashrrev_i32_e32 v159, 31, v158
	v_lshlrev_b64 v[130:131], 13, v[130:131]
	v_lshl_add_u64 v[132:133], v[12:13], 0, v[132:133]
	v_lshlrev_b64 v[134:135], 13, v[134:135]
	v_lshlrev_b64 v[136:137], 13, v[136:137]
	v_lshlrev_b64 v[138:139], 13, v[138:139]
	v_lshlrev_b64 v[140:141], 13, v[140:141]
	v_lshlrev_b64 v[142:143], 13, v[142:143]
	v_lshlrev_b64 v[144:145], 13, v[144:145]
	v_lshlrev_b64 v[146:147], 13, v[146:147]
	v_lshlrev_b64 v[148:149], 13, v[148:149]
	v_lshlrev_b64 v[150:151], 13, v[150:151]
	v_lshlrev_b64 v[152:153], 13, v[152:153]
	v_lshlrev_b64 v[154:155], 13, v[154:155]
	v_lshlrev_b64 v[156:157], 13, v[156:157]
	v_lshlrev_b64 v[158:159], 13, v[158:159]
	v_lshlrev_b64 v[160:161], 13, v[160:161]
	v_lshl_add_u64 v[130:131], v[12:13], 0, v[130:131]
	v_lshl_add_u64 v[136:137], v[12:13], 0, v[136:137]
	v_lshl_add_u64 v[134:135], v[12:13], 0, v[134:135]
	v_lshl_add_u64 v[140:141], v[12:13], 0, v[140:141]
	v_lshl_add_u64 v[138:139], v[12:13], 0, v[138:139]
	v_lshl_add_u64 v[144:145], v[12:13], 0, v[144:145]
	v_lshl_add_u64 v[142:143], v[12:13], 0, v[142:143]
	v_lshl_add_u64 v[148:149], v[12:13], 0, v[148:149]
	v_lshl_add_u64 v[146:147], v[12:13], 0, v[146:147]
	v_lshl_add_u64 v[152:153], v[12:13], 0, v[152:153]
	v_lshl_add_u64 v[150:151], v[12:13], 0, v[150:151]
	v_lshl_add_u64 v[156:157], v[12:13], 0, v[156:157]
	v_lshl_add_u64 v[154:155], v[12:13], 0, v[154:155]
	v_lshl_add_u64 v[160:161], v[12:13], 0, v[160:161]
	v_lshl_add_u64 v[158:159], v[12:13], 0, v[158:159]
	global_load_dword v172, v[132:133], off
	global_load_dword v173, v[130:131], off
	global_load_dword v174, v[136:137], off
	global_load_dword v175, v[134:135], off
	global_load_dword v176, v[140:141], off
	global_load_dword v177, v[138:139], off
	global_load_dword v178, v[144:145], off
	global_load_dword v179, v[142:143], off
	global_load_dword v180, v[148:149], off
	global_load_dword v181, v[146:147], off
	global_load_dword v182, v[152:153], off
	global_load_dword v183, v[150:151], off
	global_load_dword v184, v[156:157], off
	global_load_dword v185, v[154:155], off
	global_load_dword v186, v[160:161], off
	global_load_dword v187, v[158:159], off
	s_add_i32 s29, s29, 16
	s_add_i32 s28, s28, 16
	s_add_i32 s30, s30, -16
	v_mad_u64_u32 v[130:131], s[34:35], v109, s33, v[6:7]
	v_mad_u64_u32 v[132:133], s[34:35], v104, s33, v[6:7]
	v_mad_u64_u32 v[134:135], s[34:35], v115, s33, v[6:7]
	v_mad_u64_u32 v[136:137], s[34:35], v111, s33, v[6:7]
	v_mad_u64_u32 v[138:139], s[34:35], v129, s33, v[6:7]
	v_mad_u64_u32 v[140:141], s[34:35], v119, s33, v[6:7]
	v_mad_u64_u32 v[142:143], s[34:35], v163, s33, v[6:7]
	v_mad_u64_u32 v[144:145], s[34:35], v162, s33, v[6:7]
	v_mad_u64_u32 v[146:147], s[34:35], v165, s33, v[6:7]
	v_mad_u64_u32 v[148:149], s[34:35], v164, s33, v[6:7]
	v_mad_u64_u32 v[150:151], s[34:35], v167, s33, v[6:7]
	v_mad_u64_u32 v[152:153], s[34:35], v166, s33, v[6:7]
	v_mad_u64_u32 v[154:155], s[34:35], v169, s33, v[6:7]
	v_mad_u64_u32 v[156:157], s[34:35], v168, s33, v[6:7]
	v_mad_u64_u32 v[158:159], s[34:35], v171, s33, v[6:7]
	v_mad_u64_u32 v[160:161], s[34:35], v170, s33, v[6:7]
	s_lshl_b32 s31, s28, 1
	s_lshl_b32 s34, s29, 1
	v_or_b32_e32 v4, s31, v1
	v_or_b32_e32 v9, s34, v2
	s_add_i32 s35, s31, 4
	s_add_i32 s36, s34, 4
	s_add_i32 s37, s31, 8
	s_add_i32 s58, s34, 8
	s_add_i32 s59, s31, 12
	s_add_i32 s60, s34, 12
	s_add_i32 s61, s31, 16
	s_add_i32 s62, s34, 16
	s_add_i32 s63, s31, 20
	s_add_i32 s64, s34, 20
	s_add_i32 s65, s31, 24
	s_add_i32 s66, s34, 24
	s_add_i32 s31, s31, 28
	s_add_i32 s34, s34, 28
	v_add_u32_e32 v32, v9, v14
	v_or_b32_e32 v11, s35, v1
	v_or_b32_e32 v15, s36, v2
	v_or_b32_e32 v19, s37, v1
	v_or_b32_e32 v29, s58, v2
	v_or_b32_e32 v62, s59, v1
	v_or_b32_e32 v63, s60, v2
	v_or_b32_e32 v64, s61, v1
	v_or_b32_e32 v65, s62, v2
	v_or_b32_e32 v66, s63, v1
	v_or_b32_e32 v67, s64, v2
	v_or_b32_e32 v68, s65, v1
	v_or_b32_e32 v69, s66, v2
	v_or_b32_e32 v70, s31, v1
	v_or_b32_e32 v71, s34, v2
	v_add_u32_e32 v30, v4, v3
	v_ashrrev_i32_e32 v33, 31, v32
	v_add_u32_e32 v34, v11, v3
	v_add_u32_e32 v36, v15, v14
	v_add_u32_e32 v38, v19, v3
	v_add_u32_e32 v40, v29, v14
	v_add_u32_e32 v42, v62, v3
	v_add_u32_e32 v44, v63, v14
	v_add_u32_e32 v46, v64, v3
	v_add_u32_e32 v48, v65, v14
	v_add_u32_e32 v50, v66, v3
	v_add_u32_e32 v52, v67, v14
	v_add_u32_e32 v54, v68, v3
	v_add_u32_e32 v56, v69, v14
	v_add_u32_e32 v58, v70, v3
	v_add_u32_e32 v60, v71, v14
	v_ashrrev_i32_e32 v31, 31, v30
	v_lshlrev_b64 v[32:33], 13, v[32:33]
	v_ashrrev_i32_e32 v37, 31, v36
	v_ashrrev_i32_e32 v35, 31, v34
	v_ashrrev_i32_e32 v41, 31, v40
	v_ashrrev_i32_e32 v39, 31, v38
	v_ashrrev_i32_e32 v45, 31, v44
	v_ashrrev_i32_e32 v43, 31, v42
	v_ashrrev_i32_e32 v49, 31, v48
	v_ashrrev_i32_e32 v47, 31, v46
	v_ashrrev_i32_e32 v53, 31, v52
	v_ashrrev_i32_e32 v51, 31, v50
	v_ashrrev_i32_e32 v57, 31, v56
	v_ashrrev_i32_e32 v55, 31, v54
	v_ashrrev_i32_e32 v61, 31, v60
	v_ashrrev_i32_e32 v59, 31, v58
	v_lshlrev_b64 v[30:31], 13, v[30:31]
	v_lshl_add_u64 v[32:33], v[12:13], 0, v[32:33]
	v_lshlrev_b64 v[34:35], 13, v[34:35]
	v_lshlrev_b64 v[36:37], 13, v[36:37]
	v_lshlrev_b64 v[38:39], 13, v[38:39]
	v_lshlrev_b64 v[40:41], 13, v[40:41]
	v_lshlrev_b64 v[42:43], 13, v[42:43]
	v_lshlrev_b64 v[44:45], 13, v[44:45]
	v_lshlrev_b64 v[46:47], 13, v[46:47]
	v_lshlrev_b64 v[48:49], 13, v[48:49]
	v_lshlrev_b64 v[50:51], 13, v[50:51]
	v_lshlrev_b64 v[52:53], 13, v[52:53]
	v_lshlrev_b64 v[54:55], 13, v[54:55]
	v_lshlrev_b64 v[56:57], 13, v[56:57]
	v_lshlrev_b64 v[58:59], 13, v[58:59]
	v_lshlrev_b64 v[60:61], 13, v[60:61]
	v_lshl_add_u64 v[30:31], v[12:13], 0, v[30:31]
	v_lshl_add_u64 v[36:37], v[12:13], 0, v[36:37]
	v_lshl_add_u64 v[34:35], v[12:13], 0, v[34:35]
	v_lshl_add_u64 v[40:41], v[12:13], 0, v[40:41]
	v_lshl_add_u64 v[38:39], v[12:13], 0, v[38:39]
	v_lshl_add_u64 v[44:45], v[12:13], 0, v[44:45]
	v_lshl_add_u64 v[42:43], v[12:13], 0, v[42:43]
	v_lshl_add_u64 v[48:49], v[12:13], 0, v[48:49]
	v_lshl_add_u64 v[46:47], v[12:13], 0, v[46:47]
	v_lshl_add_u64 v[52:53], v[12:13], 0, v[52:53]
	v_lshl_add_u64 v[50:51], v[12:13], 0, v[50:51]
	v_lshl_add_u64 v[56:57], v[12:13], 0, v[56:57]
	v_lshl_add_u64 v[54:55], v[12:13], 0, v[54:55]
	v_lshl_add_u64 v[60:61], v[12:13], 0, v[60:61]
	v_lshl_add_u64 v[58:59], v[12:13], 0, v[58:59]
	global_load_dword v72, v[32:33], off
	global_load_dword v73, v[30:31], off
	global_load_dword v74, v[36:37], off
	global_load_dword v75, v[34:35], off
	global_load_dword v76, v[40:41], off
	global_load_dword v77, v[38:39], off
	global_load_dword v78, v[44:45], off
	global_load_dword v79, v[42:43], off
	global_load_dword v80, v[48:49], off
	global_load_dword v81, v[46:47], off
	global_load_dword v82, v[52:53], off
	global_load_dword v83, v[50:51], off
	global_load_dword v84, v[56:57], off
	global_load_dword v85, v[54:55], off
	global_load_dword v86, v[60:61], off
	global_load_dword v87, v[58:59], off
	s_add_i32 s29, s29, 16
	s_add_i32 s28, s28, 16
	s_add_i32 s30, s30, -16
	v_mad_u64_u32 v[30:31], s[34:35], v9, s33, v[6:7]
	v_mad_u64_u32 v[32:33], s[34:35], v4, s33, v[6:7]
	v_mad_u64_u32 v[34:35], s[34:35], v15, s33, v[6:7]
	v_mad_u64_u32 v[36:37], s[34:35], v11, s33, v[6:7]
	v_mad_u64_u32 v[38:39], s[34:35], v29, s33, v[6:7]
	v_mad_u64_u32 v[40:41], s[34:35], v19, s33, v[6:7]
	v_mad_u64_u32 v[42:43], s[34:35], v63, s33, v[6:7]
	v_mad_u64_u32 v[44:45], s[34:35], v62, s33, v[6:7]
	v_mad_u64_u32 v[46:47], s[34:35], v65, s33, v[6:7]
	v_mad_u64_u32 v[48:49], s[34:35], v64, s33, v[6:7]
	v_mad_u64_u32 v[50:51], s[34:35], v67, s33, v[6:7]
	v_mad_u64_u32 v[52:53], s[34:35], v66, s33, v[6:7]
	v_mad_u64_u32 v[54:55], s[34:35], v69, s33, v[6:7]
	v_mad_u64_u32 v[56:57], s[34:35], v68, s33, v[6:7]
	v_mad_u64_u32 v[58:59], s[34:35], v71, s33, v[6:7]
	v_mad_u64_u32 v[60:61], s[34:35], v70, s33, v[6:7]
	s_waitcnt vmcnt(31)
	ds_write_b32 v130, v172
	s_waitcnt vmcnt(30)
	ds_write_b32 v132, v173
	s_waitcnt vmcnt(29)
	ds_write_b32 v134, v174
	s_waitcnt vmcnt(28)
	ds_write_b32 v136, v175
	s_waitcnt vmcnt(27)
	ds_write_b32 v138, v176
	s_waitcnt vmcnt(26)
	ds_write_b32 v140, v177
	s_waitcnt vmcnt(25)
	ds_write_b32 v142, v178
	s_waitcnt vmcnt(24)
	ds_write_b32 v144, v179
	s_waitcnt vmcnt(23)
	ds_write_b32 v146, v180
	s_waitcnt vmcnt(22)
	ds_write_b32 v148, v181
	s_waitcnt vmcnt(21)
	ds_write_b32 v150, v182
	s_waitcnt vmcnt(20)
	ds_write_b32 v152, v183
	s_waitcnt vmcnt(19)
	ds_write_b32 v154, v184
	s_waitcnt vmcnt(18)
	ds_write_b32 v156, v185
	s_waitcnt vmcnt(17)
	ds_write_b32 v158, v186
	s_waitcnt vmcnt(16)
	ds_write_b32 v160, v187
	s_waitcnt vmcnt(15)
	ds_write_b32 v30, v72
	s_waitcnt vmcnt(14)
	ds_write_b32 v32, v73
	s_waitcnt vmcnt(13)
	ds_write_b32 v34, v74
	s_waitcnt vmcnt(12)
	ds_write_b32 v36, v75
	s_waitcnt vmcnt(11)
	ds_write_b32 v38, v76
	s_waitcnt vmcnt(10)
	ds_write_b32 v40, v77
	s_waitcnt vmcnt(9)
	ds_write_b32 v42, v78
	s_waitcnt vmcnt(8)
	ds_write_b32 v44, v79
	s_waitcnt vmcnt(7)
	ds_write_b32 v46, v80
	s_waitcnt vmcnt(6)
	ds_write_b32 v48, v81
	s_waitcnt vmcnt(5)
	ds_write_b32 v50, v82
	s_waitcnt vmcnt(4)
	ds_write_b32 v52, v83
	s_waitcnt vmcnt(3)
	ds_write_b32 v54, v84
	s_waitcnt vmcnt(2)
	ds_write_b32 v56, v85
	s_waitcnt vmcnt(1)
	ds_write_b32 v58, v86
	s_waitcnt vmcnt(0)
	ds_write_b32 v60, v87
	s_waitcnt lgkmcnt(0)
	v_lshl_add_u64 v[12:13], v[16:17], 1, s[16:17]
	ds_read2_b32 v[16:17], v22 offset1:8
	ds_read2_b32 v[32:33], v22 offset0:33 offset1:41
	ds_read2_b32 v[34:35], v22 offset0:66 offset1:74
	ds_read2_b32 v[36:37], v22 offset0:99 offset1:107
	v_mov_b32_e32 v15, v5
	s_waitcnt lgkmcnt(3)
	v_bfe_u32 v3, v16, 16, 1
	v_add3_u32 v3, v16, v3, s45
	s_waitcnt lgkmcnt(2)
	v_bfe_u32 v4, v32, 16, 1
	ds_read2_b32 v[38:39], v22 offset0:132 offset1:140
	v_lshl_add_u64 v[12:13], v[14:15], 1, v[12:13]
	v_mov_b32_e32 v11, v5
	v_lshrrev_b32_e32 v3, 16, v3
	v_add3_u32 v4, v32, v4, s45
	ds_read2_b32 v[40:41], v22 offset0:165 offset1:173
	v_lshl_add_u64 v[30:31], v[12:13], 0, v[10:11]
	v_and_or_b32 v12, v4, s46, v3
	s_waitcnt lgkmcnt(3)
	v_bfe_u32 v3, v34, 16, 1
	v_add3_u32 v3, v34, v3, s45
	s_waitcnt lgkmcnt(2)
	v_bfe_u32 v4, v36, 16, 1
	ds_read2_b32 v[42:43], v22 offset0:198 offset1:206
	v_lshrrev_b32_e32 v3, 16, v3
	v_add3_u32 v4, v36, v4, s45
	ds_read2_b32 v[44:45], v22 offset0:231 offset1:239
	v_and_or_b32 v13, v4, s46, v3
	s_waitcnt lgkmcnt(3)
	v_bfe_u32 v3, v38, 16, 1
	v_add3_u32 v3, v38, v3, s45
	s_waitcnt lgkmcnt(2)
	v_bfe_u32 v4, v40, 16, 1
	v_lshrrev_b32_e32 v3, 16, v3
	v_add3_u32 v4, v40, v4, s45
	v_and_or_b32 v14, v4, s46, v3
	s_waitcnt lgkmcnt(1)
	v_bfe_u32 v3, v42, 16, 1
	v_add3_u32 v3, v42, v3, s45
	s_waitcnt lgkmcnt(0)
	v_bfe_u32 v4, v44, 16, 1
	v_lshrrev_b32_e32 v3, 16, v3
	v_add3_u32 v4, v44, v4, s45
	v_and_or_b32 v15, v4, s46, v3
	v_or_b32_e32 v3, v18, v21
	v_lshlrev_b32_e32 v4, 12, v3
	v_bfe_u32 v3, v17, 16, 1
	v_lshl_add_u64 v[46:47], v[30:31], 0, v[4:5]
	v_add3_u32 v3, v17, v3, s45
	v_bfe_u32 v4, v33, 16, 1
	v_lshrrev_b32_e32 v3, 16, v3
	v_add3_u32 v4, v33, v4, s45
	global_store_dwordx4 v[46:47], v[12:15], off
	ds_read2_b32 v[16:17], v22 offset0:16 offset1:24
	v_readlane_b32 s66, v253, 1
	v_and_or_b32 v12, v4, s46, v3
	v_bfe_u32 v3, v35, 16, 1
	v_add3_u32 v3, v35, v3, s45
	v_bfe_u32 v4, v37, 16, 1
	v_lshrrev_b32_e32 v3, 16, v3
	v_add3_u32 v4, v37, v4, s45
	v_and_or_b32 v13, v4, s46, v3
	v_bfe_u32 v3, v39, 16, 1
	v_add3_u32 v3, v39, v3, s45
	v_bfe_u32 v4, v41, 16, 1
	v_lshrrev_b32_e32 v3, 16, v3
	v_add3_u32 v4, v41, v4, s45
	v_and_or_b32 v14, v4, s46, v3
	v_bfe_u32 v3, v43, 16, 1
	v_add3_u32 v3, v43, v3, s45
	v_bfe_u32 v4, v45, 16, 1
	v_lshrrev_b32_e32 v3, 16, v3
	v_add3_u32 v4, v45, v4, s45
	v_and_or_b32 v15, v4, s46, v3
	v_or_b32_e32 v3, v18, v23
	v_lshlrev_b32_e32 v4, 12, v3
	v_lshl_add_u64 v[32:33], v[30:31], 0, v[4:5]
	global_store_dwordx4 v[32:33], v[12:15], off
	ds_read2_b32 v[32:33], v22 offset0:49 offset1:57
	ds_read2_b32 v[34:35], v22 offset0:82 offset1:90
	ds_read2_b32 v[36:37], v22 offset0:115 offset1:123
	s_waitcnt lgkmcnt(3)
	v_bfe_u32 v3, v16, 16, 1
	v_add3_u32 v3, v16, v3, s45
	s_waitcnt lgkmcnt(2)
	v_bfe_u32 v4, v32, 16, 1
	ds_read2_b32 v[38:39], v22 offset0:148 offset1:156
	v_lshrrev_b32_e32 v3, 16, v3
	v_add3_u32 v4, v32, v4, s45
	ds_read2_b32 v[40:41], v22 offset0:181 offset1:189
	v_and_or_b32 v12, v4, s46, v3
	s_waitcnt lgkmcnt(3)
	v_bfe_u32 v3, v34, 16, 1
	v_add3_u32 v3, v34, v3, s45
	s_waitcnt lgkmcnt(2)
	v_bfe_u32 v4, v36, 16, 1
	ds_read2_b32 v[42:43], v22 offset0:214 offset1:222
	v_lshrrev_b32_e32 v3, 16, v3
	v_add3_u32 v4, v36, v4, s45
	ds_read2_b32 v[44:45], v22 offset0:247 offset1:255
	v_and_or_b32 v13, v4, s46, v3
	s_waitcnt lgkmcnt(3)
	v_bfe_u32 v3, v38, 16, 1
	v_add3_u32 v3, v38, v3, s45
	s_waitcnt lgkmcnt(2)
	v_bfe_u32 v4, v40, 16, 1
	v_lshrrev_b32_e32 v3, 16, v3
	v_add3_u32 v4, v40, v4, s45
	v_and_or_b32 v14, v4, s46, v3
	s_waitcnt lgkmcnt(1)
	v_bfe_u32 v3, v42, 16, 1
	v_add3_u32 v3, v42, v3, s45
	s_waitcnt lgkmcnt(0)
	v_bfe_u32 v4, v44, 16, 1
	v_lshrrev_b32_e32 v3, 16, v3
	v_add3_u32 v4, v44, v4, s45
	v_and_or_b32 v15, v4, s46, v3
	v_or_b32_e32 v3, v18, v24
	v_lshlrev_b32_e32 v4, 12, v3
	v_bfe_u32 v3, v17, 16, 1
	v_lshl_add_u64 v[46:47], v[30:31], 0, v[4:5]
	v_add3_u32 v3, v17, v3, s45
	v_bfe_u32 v4, v33, 16, 1
	v_lshrrev_b32_e32 v3, 16, v3
	v_add3_u32 v4, v33, v4, s45
	global_store_dwordx4 v[46:47], v[12:15], off
	s_nop 1
	v_and_or_b32 v12, v4, s46, v3
	v_bfe_u32 v3, v35, 16, 1
	v_add3_u32 v3, v35, v3, s45
	v_bfe_u32 v4, v37, 16, 1
	v_lshrrev_b32_e32 v3, 16, v3
	v_add3_u32 v4, v37, v4, s45
	v_and_or_b32 v13, v4, s46, v3
	v_bfe_u32 v3, v39, 16, 1
	v_add3_u32 v3, v39, v3, s45
	v_bfe_u32 v4, v41, 16, 1
	v_lshrrev_b32_e32 v3, 16, v3
	v_add3_u32 v4, v41, v4, s45
	v_and_or_b32 v14, v4, s46, v3
	v_bfe_u32 v3, v43, 16, 1
	v_add3_u32 v3, v43, v3, s45
	v_bfe_u32 v4, v45, 16, 1
	v_lshrrev_b32_e32 v3, 16, v3
	v_add3_u32 v4, v45, v4, s45
	v_and_or_b32 v15, v4, s46, v3
	v_or_b32_e32 v3, v18, v25
	v_lshlrev_b32_e32 v4, 12, v3
	v_lshl_add_u64 v[16:17], v[30:31], 0, v[4:5]
	global_store_dwordx4 v[16:17], v[12:15], off
	s_waitcnt lgkmcnt(0)

.LBB0_140:
	s_andn2_saveexec_b64 s[24:25], s[24:25]
	s_cbranch_execz .LBB0_105
	s_load_dwordx2 s[26:27], s[6:7], 0x30
	v_mul_i32_i24_e32 v4, 0xfc1, v3
	v_lshrrev_b32_e32 v9, 31, v4
	v_ashrrev_i32_e32 v4, 19, v4
	v_add_u16_e32 v4, v4, v9
	v_mul_lo_u16_e32 v9, 0x82, v4
	v_sub_u16_e32 v3, v3, v9
	s_waitcnt lgkmcnt(0)
	v_mov_b64_e32 v[14:15], s[26:27]
	v_mad_i64_i32 v[18:19], s[26:27], v12, s54, v[14:15]
	v_lshlrev_b32_sdwa v14, v26, sext(v3) dst_sel:DWORD dst_unused:UNUSED_PAD src0_sel:DWORD src1_sel:WORD_0
	v_ashrrev_i32_e32 v15, 31, v14
	v_lshlrev_b32_sdwa v16, v28, sext(v4) dst_sel:DWORD dst_unused:UNUSED_PAD src0_sel:DWORD src1_sel:WORD_0
	v_lshl_add_u64 v[18:19], v[14:15], 2, v[18:19]
	v_mov_b32_e32 v9, v5
	v_lshl_add_u64 v[18:19], v[18:19], 0, v[8:9]
	v_mov_b32_e32 v3, v16
	s_mov_b32 s26, 1
	s_mov_b32 s27, 0
	s_mov_b32 s28, 32
	s_lshl_b32 s29, s26, 1
	s_lshl_b32 s30, s27, 1
	v_or_b32_e32 v104, s29, v1
	v_or_b32_e32 v109, s30, v2
	s_add_i32 s31, s29, 4
	s_add_i32 s34, s30, 4
	s_add_i32 s35, s29, 8
	s_add_i32 s36, s30, 8
	s_add_i32 s37, s29, 12
	s_add_i32 s58, s30, 12
	s_add_i32 s59, s29, 16
	s_add_i32 s60, s30, 16
	s_add_i32 s61, s29, 20
	s_add_i32 s62, s30, 20
	s_add_i32 s63, s29, 24
	s_add_i32 s64, s30, 24
	s_add_i32 s29, s29, 28
	s_add_i32 s30, s30, 28
	v_add_u32_e32 v111, v104, v3
	v_add_u32_e32 v113, v109, v16
	v_or_b32_e32 v115, s31, v1
	v_or_b32_e32 v117, s34, v2
	v_or_b32_e32 v129, s35, v1
	v_or_b32_e32 v162, s36, v2
	v_or_b32_e32 v163, s37, v1
	v_or_b32_e32 v164, s58, v2
	v_or_b32_e32 v165, s59, v1
	v_or_b32_e32 v166, s60, v2
	v_or_b32_e32 v167, s61, v1
	v_or_b32_e32 v168, s62, v2
	v_or_b32_e32 v169, s63, v1
	v_or_b32_e32 v170, s64, v2
	v_or_b32_e32 v171, s29, v1
	v_or_b32_e32 v172, s30, v2
	v_mad_i64_i32 v[130:131], s[30:31], v113, s55, v[18:19]
	v_mad_i64_i32 v[132:133], s[30:31], v111, s55, v[18:19]
	v_add_u32_e32 v111, v115, v3
	v_add_u32_e32 v113, v117, v16
	v_add_u32_e32 v140, v129, v3
	v_add_u32_e32 v138, v162, v16
	v_add_u32_e32 v144, v163, v3
	v_add_u32_e32 v142, v164, v16
	v_add_u32_e32 v148, v165, v3
	v_add_u32_e32 v146, v166, v16
	v_add_u32_e32 v152, v167, v3
	v_add_u32_e32 v150, v168, v16
	v_add_u32_e32 v156, v169, v3
	v_add_u32_e32 v154, v170, v16
	v_add_u32_e32 v160, v171, v3
	v_add_u32_e32 v158, v172, v16
	v_mad_i64_i32 v[134:135], s[30:31], v113, s55, v[18:19]
	v_mad_i64_i32 v[136:137], s[30:31], v111, s55, v[18:19]
	v_mad_i64_i32 v[138:139], s[30:31], v138, s55, v[18:19]
	v_mad_i64_i32 v[140:141], s[30:31], v140, s55, v[18:19]
	v_mad_i64_i32 v[142:143], s[30:31], v142, s55, v[18:19]
	v_mad_i64_i32 v[144:145], s[30:31], v144, s55, v[18:19]
	v_mad_i64_i32 v[146:147], s[30:31], v146, s55, v[18:19]
	v_mad_i64_i32 v[148:149], s[30:31], v148, s55, v[18:19]
	v_mad_i64_i32 v[150:151], s[30:31], v150, s55, v[18:19]
	v_mad_i64_i32 v[152:153], s[30:31], v152, s55, v[18:19]
	v_mad_i64_i32 v[154:155], s[30:31], v154, s55, v[18:19]
	v_mad_i64_i32 v[156:157], s[30:31], v156, s55, v[18:19]
	v_mad_i64_i32 v[158:159], s[30:31], v158, s55, v[18:19]
	v_mad_i64_i32 v[160:161], s[30:31], v160, s55, v[18:19]
	global_load_dword v111, v[130:131], off
	global_load_dword v113, v[132:133], off
	global_load_dword v173, v[134:135], off
	global_load_dword v174, v[136:137], off
	global_load_dword v175, v[138:139], off
	global_load_dword v176, v[140:141], off
	global_load_dword v177, v[142:143], off
	global_load_dword v178, v[144:145], off
	global_load_dword v179, v[146:147], off
	global_load_dword v180, v[148:149], off
	global_load_dword v181, v[150:151], off
	global_load_dword v182, v[152:153], off
	global_load_dword v183, v[154:155], off
	global_load_dword v184, v[156:157], off
	global_load_dword v185, v[158:159], off
	global_load_dword v186, v[160:161], off
	s_add_i32 s27, s27, 16
	s_add_i32 s26, s26, 16
	s_add_i32 s28, s28, -16
	v_mad_u64_u32 v[130:131], s[30:31], v109, s33, v[6:7]
	v_mad_u64_u32 v[132:133], s[30:31], v104, s33, v[6:7]
	v_mad_u64_u32 v[134:135], s[30:31], v117, s33, v[6:7]
	v_mad_u64_u32 v[136:137], s[30:31], v115, s33, v[6:7]
	v_mad_u64_u32 v[138:139], s[30:31], v162, s33, v[6:7]
	v_mad_u64_u32 v[140:141], s[30:31], v129, s33, v[6:7]
	v_mad_u64_u32 v[142:143], s[30:31], v164, s33, v[6:7]
	v_mad_u64_u32 v[144:145], s[30:31], v163, s33, v[6:7]
	v_mad_u64_u32 v[146:147], s[30:31], v166, s33, v[6:7]
	v_mad_u64_u32 v[148:149], s[30:31], v165, s33, v[6:7]
	v_mad_u64_u32 v[150:151], s[30:31], v168, s33, v[6:7]
	v_mad_u64_u32 v[152:153], s[30:31], v167, s33, v[6:7]
	v_mad_u64_u32 v[154:155], s[30:31], v170, s33, v[6:7]
	v_mad_u64_u32 v[156:157], s[30:31], v169, s33, v[6:7]
	v_mad_u64_u32 v[158:159], s[30:31], v172, s33, v[6:7]
	v_mad_u64_u32 v[160:161], s[30:31], v171, s33, v[6:7]
	s_lshl_b32 s29, s26, 1
	s_lshl_b32 s30, s27, 1
	v_or_b32_e32 v4, s29, v1
	v_or_b32_e32 v9, s30, v2
	s_add_i32 s31, s29, 4
	s_add_i32 s34, s30, 4
	s_add_i32 s35, s29, 8
	s_add_i32 s36, s30, 8
	s_add_i32 s37, s29, 12
	s_add_i32 s58, s30, 12
	s_add_i32 s59, s29, 16
	s_add_i32 s60, s30, 16
	s_add_i32 s61, s29, 20
	s_add_i32 s62, s30, 20
	s_add_i32 s63, s29, 24
	s_add_i32 s64, s30, 24
	s_add_i32 s29, s29, 28
	s_add_i32 s30, s30, 28
	v_add_u32_e32 v11, v4, v3
	v_add_u32_e32 v13, v9, v16
	v_or_b32_e32 v15, s31, v1
	v_or_b32_e32 v17, s34, v2
	v_or_b32_e32 v29, s35, v1
	v_or_b32_e32 v62, s36, v2
	v_or_b32_e32 v63, s37, v1
	v_or_b32_e32 v64, s58, v2
	v_or_b32_e32 v65, s59, v1
	v_or_b32_e32 v66, s60, v2
	v_or_b32_e32 v67, s61, v1
	v_or_b32_e32 v68, s62, v2
	v_or_b32_e32 v69, s63, v1
	v_or_b32_e32 v70, s64, v2
	v_or_b32_e32 v71, s29, v1
	v_or_b32_e32 v72, s30, v2
	v_mad_i64_i32 v[30:31], s[30:31], v13, s55, v[18:19]
	v_mad_i64_i32 v[32:33], s[30:31], v11, s55, v[18:19]
	v_add_u32_e32 v11, v15, v3
	v_add_u32_e32 v13, v17, v16
	v_add_u32_e32 v40, v29, v3
	v_add_u32_e32 v38, v62, v16
	v_add_u32_e32 v44, v63, v3
	v_add_u32_e32 v42, v64, v16
	v_add_u32_e32 v48, v65, v3
	v_add_u32_e32 v46, v66, v16
	v_add_u32_e32 v52, v67, v3
	v_add_u32_e32 v50, v68, v16
	v_add_u32_e32 v56, v69, v3
	v_add_u32_e32 v54, v70, v16
	v_add_u32_e32 v60, v71, v3
	v_add_u32_e32 v58, v72, v16
	v_mad_i64_i32 v[34:35], s[30:31], v13, s55, v[18:19]
	v_mad_i64_i32 v[36:37], s[30:31], v11, s55, v[18:19]
	v_mad_i64_i32 v[38:39], s[30:31], v38, s55, v[18:19]
	v_mad_i64_i32 v[40:41], s[30:31], v40, s55, v[18:19]
	v_mad_i64_i32 v[42:43], s[30:31], v42, s55, v[18:19]
	v_mad_i64_i32 v[44:45], s[30:31], v44, s55, v[18:19]
	v_mad_i64_i32 v[46:47], s[30:31], v46, s55, v[18:19]
	v_mad_i64_i32 v[48:49], s[30:31], v48, s55, v[18:19]
	v_mad_i64_i32 v[50:51], s[30:31], v50, s55, v[18:19]
	v_mad_i64_i32 v[52:53], s[30:31], v52, s55, v[18:19]
	v_mad_i64_i32 v[54:55], s[30:31], v54, s55, v[18:19]
	v_mad_i64_i32 v[56:57], s[30:31], v56, s55, v[18:19]
	v_mad_i64_i32 v[58:59], s[30:31], v58, s55, v[18:19]
	v_mad_i64_i32 v[60:61], s[30:31], v60, s55, v[18:19]
	global_load_dword v11, v[30:31], off
	global_load_dword v13, v[32:33], off
	global_load_dword v73, v[34:35], off
	global_load_dword v74, v[36:37], off
	global_load_dword v75, v[38:39], off
	global_load_dword v76, v[40:41], off
	global_load_dword v77, v[42:43], off
	global_load_dword v78, v[44:45], off
	global_load_dword v79, v[46:47], off
	global_load_dword v80, v[48:49], off
	global_load_dword v81, v[50:51], off
	global_load_dword v82, v[52:53], off
	global_load_dword v83, v[54:55], off
	global_load_dword v84, v[56:57], off
	global_load_dword v85, v[58:59], off
	global_load_dword v86, v[60:61], off
	s_add_i32 s27, s27, 16
	s_add_i32 s26, s26, 16
	s_add_i32 s28, s28, -16
	v_mad_u64_u32 v[30:31], s[30:31], v9, s33, v[6:7]
	v_mad_u64_u32 v[32:33], s[30:31], v4, s33, v[6:7]
	v_mad_u64_u32 v[34:35], s[30:31], v17, s33, v[6:7]
	v_mad_u64_u32 v[36:37], s[30:31], v15, s33, v[6:7]
	v_mad_u64_u32 v[38:39], s[30:31], v62, s33, v[6:7]
	v_mad_u64_u32 v[40:41], s[30:31], v29, s33, v[6:7]
	v_mad_u64_u32 v[42:43], s[30:31], v64, s33, v[6:7]
	v_mad_u64_u32 v[44:45], s[30:31], v63, s33, v[6:7]
	v_mad_u64_u32 v[46:47], s[30:31], v66, s33, v[6:7]
	v_mad_u64_u32 v[48:49], s[30:31], v65, s33, v[6:7]
	v_mad_u64_u32 v[50:51], s[30:31], v68, s33, v[6:7]
	v_mad_u64_u32 v[52:53], s[30:31], v67, s33, v[6:7]
	v_mad_u64_u32 v[54:55], s[30:31], v70, s33, v[6:7]
	v_mad_u64_u32 v[56:57], s[30:31], v69, s33, v[6:7]
	v_mad_u64_u32 v[58:59], s[30:31], v72, s33, v[6:7]
	v_mad_u64_u32 v[60:61], s[30:31], v71, s33, v[6:7]
	s_waitcnt vmcnt(31)
	ds_write_b32 v130, v111
	s_waitcnt vmcnt(30)
	ds_write_b32 v132, v113
	s_waitcnt vmcnt(29)
	ds_write_b32 v134, v173
	s_waitcnt vmcnt(28)
	ds_write_b32 v136, v174
	s_waitcnt vmcnt(27)
	ds_write_b32 v138, v175
	s_waitcnt vmcnt(26)
	ds_write_b32 v140, v176
	s_waitcnt vmcnt(25)
	ds_write_b32 v142, v177
	s_waitcnt vmcnt(24)
	ds_write_b32 v144, v178
	s_waitcnt vmcnt(23)
	ds_write_b32 v146, v179
	s_waitcnt vmcnt(22)
	ds_write_b32 v148, v180
	s_waitcnt vmcnt(21)
	ds_write_b32 v150, v181
	s_waitcnt vmcnt(20)
	ds_write_b32 v152, v182
	s_waitcnt vmcnt(19)
	ds_write_b32 v154, v183
	s_waitcnt vmcnt(18)
	ds_write_b32 v156, v184
	s_waitcnt vmcnt(17)
	ds_write_b32 v158, v185
	s_waitcnt vmcnt(16)
	ds_write_b32 v160, v186
	s_waitcnt vmcnt(15)
	ds_write_b32 v30, v11
	s_waitcnt vmcnt(14)
	ds_write_b32 v32, v13
	s_waitcnt vmcnt(13)
	ds_write_b32 v34, v73
	s_waitcnt vmcnt(12)
	ds_write_b32 v36, v74
	s_waitcnt vmcnt(11)
	ds_write_b32 v38, v75
	s_waitcnt vmcnt(10)
	ds_write_b32 v40, v76
	s_waitcnt vmcnt(9)
	ds_write_b32 v42, v77
	s_waitcnt vmcnt(8)
	ds_write_b32 v44, v78
	s_waitcnt vmcnt(7)
	ds_write_b32 v46, v79
	s_waitcnt vmcnt(6)
	ds_write_b32 v48, v80
	s_waitcnt vmcnt(5)
	ds_write_b32 v50, v81
	s_waitcnt vmcnt(4)
	ds_write_b32 v52, v82
	s_waitcnt vmcnt(3)
	ds_write_b32 v54, v83
	s_waitcnt vmcnt(2)
	ds_write_b32 v56, v84
	s_waitcnt vmcnt(1)
	ds_write_b32 v58, v85
	s_waitcnt vmcnt(0)
	ds_write_b32 v60, v86
	s_waitcnt lgkmcnt(0)
	ds_read2_b32 v[30:31], v22 offset1:8
	ds_read2_b32 v[32:33], v22 offset0:33 offset1:41
	ds_read2_b32 v[34:35], v22 offset0:66 offset1:74
	ds_read2_b32 v[36:37], v22 offset0:99 offset1:107
	v_mov_b64_e32 v[18:19], s[18:19]
	s_waitcnt lgkmcnt(3)
	v_bfe_u32 v3, v30, 16, 1
	v_add3_u32 v3, v30, v3, s45
	s_waitcnt lgkmcnt(2)
	v_bfe_u32 v4, v32, 16, 1
	ds_read2_b32 v[38:39], v22 offset0:132 offset1:140
	v_mad_i64_i32 v[12:13], s[26:27], v12, s56, v[18:19]
	v_ashrrev_i32_e32 v17, 31, v16
	v_lshrrev_b32_e32 v3, 16, v3
	v_add3_u32 v4, v32, v4, s45
	ds_read2_b32 v[40:41], v22 offset0:165 offset1:173
	v_lshl_add_u64 v[12:13], v[16:17], 1, v[12:13]
	v_and_or_b32 v16, v4, s46, v3
	s_waitcnt lgkmcnt(3)
	v_bfe_u32 v3, v34, 16, 1
	v_add3_u32 v3, v34, v3, s45
	s_waitcnt lgkmcnt(2)
	v_bfe_u32 v4, v36, 16, 1
	ds_read2_b32 v[42:43], v22 offset0:198 offset1:206
	v_lshrrev_b32_e32 v3, 16, v3
	v_add3_u32 v4, v36, v4, s45
	ds_read2_b32 v[44:45], v22 offset0:231 offset1:239
	v_and_or_b32 v17, v4, s46, v3
	s_waitcnt lgkmcnt(3)
	v_bfe_u32 v3, v38, 16, 1
	v_add3_u32 v3, v38, v3, s45
	s_waitcnt lgkmcnt(2)
	v_bfe_u32 v4, v40, 16, 1
	v_lshrrev_b32_e32 v3, 16, v3
	v_add3_u32 v4, v40, v4, s45
	v_and_or_b32 v18, v4, s46, v3
	s_waitcnt lgkmcnt(1)
	v_bfe_u32 v3, v42, 16, 1
	v_add3_u32 v3, v42, v3, s45
	s_waitcnt lgkmcnt(0)
	v_bfe_u32 v4, v44, 16, 1
	v_lshrrev_b32_e32 v3, 16, v3
	v_add3_u32 v4, v44, v4, s45
	v_or_b32_e32 v46, v14, v21
	v_mov_b32_e32 v11, v5
	v_and_or_b32 v19, v4, s46, v3
	v_ashrrev_i32_e32 v47, 31, v46
	v_bfe_u32 v3, v31, 16, 1
	v_lshl_add_u64 v[12:13], v[12:13], 0, v[10:11]
	v_lshlrev_b64 v[46:47], 12, v[46:47]
	v_add3_u32 v3, v31, v3, s45
	v_bfe_u32 v4, v33, 16, 1
	v_lshl_add_u64 v[46:47], v[12:13], 0, v[46:47]
	v_lshrrev_b32_e32 v3, 16, v3
	v_add3_u32 v4, v33, v4, s45
	global_store_dwordx4 v[46:47], v[16:19], off
	v_or_b32_e32 v30, v14, v23
	v_ashrrev_i32_e32 v31, 31, v30
	v_and_or_b32 v16, v4, s46, v3
	v_bfe_u32 v3, v35, 16, 1
	v_add3_u32 v3, v35, v3, s45
	v_bfe_u32 v4, v37, 16, 1
	v_lshrrev_b32_e32 v3, 16, v3
	v_add3_u32 v4, v37, v4, s45
	v_and_or_b32 v17, v4, s46, v3
	v_bfe_u32 v3, v39, 16, 1
	v_add3_u32 v3, v39, v3, s45
	v_bfe_u32 v4, v41, 16, 1
	v_lshrrev_b32_e32 v3, 16, v3
	v_add3_u32 v4, v41, v4, s45
	v_and_or_b32 v18, v4, s46, v3
	v_bfe_u32 v3, v43, 16, 1
	v_add3_u32 v3, v43, v3, s45
	v_bfe_u32 v4, v45, 16, 1
	v_lshrrev_b32_e32 v3, 16, v3
	v_add3_u32 v4, v45, v4, s45
	v_lshlrev_b64 v[30:31], 12, v[30:31]
	v_and_or_b32 v19, v4, s46, v3
	ds_read2_b32 v[32:33], v22 offset0:16 offset1:24
	v_lshl_add_u64 v[30:31], v[12:13], 0, v[30:31]
	global_store_dwordx4 v[30:31], v[16:19], off
	ds_read2_b32 v[30:31], v22 offset0:49 offset1:57
	ds_read2_b32 v[34:35], v22 offset0:82 offset1:90
	ds_read2_b32 v[36:37], v22 offset0:115 offset1:123
	s_waitcnt lgkmcnt(3)
	v_bfe_u32 v3, v32, 16, 1
	v_add3_u32 v3, v32, v3, s45
	s_waitcnt lgkmcnt(2)
	v_bfe_u32 v4, v30, 16, 1
	ds_read2_b32 v[38:39], v22 offset0:148 offset1:156
	v_lshrrev_b32_e32 v3, 16, v3
	v_add3_u32 v4, v30, v4, s45
	ds_read2_b32 v[40:41], v22 offset0:181 offset1:189
	v_and_or_b32 v16, v4, s46, v3
	s_waitcnt lgkmcnt(3)
	v_bfe_u32 v3, v34, 16, 1
	v_add3_u32 v3, v34, v3, s45
	s_waitcnt lgkmcnt(2)
	v_bfe_u32 v4, v36, 16, 1
	ds_read2_b32 v[42:43], v22 offset0:214 offset1:222
	v_lshrrev_b32_e32 v3, 16, v3
	v_add3_u32 v4, v36, v4, s45
	ds_read2_b32 v[44:45], v22 offset0:247 offset1:255
	v_and_or_b32 v17, v4, s46, v3
	s_waitcnt lgkmcnt(3)
	v_bfe_u32 v3, v38, 16, 1
	v_add3_u32 v3, v38, v3, s45
	s_waitcnt lgkmcnt(2)
	v_bfe_u32 v4, v40, 16, 1
	v_lshrrev_b32_e32 v3, 16, v3
	v_add3_u32 v4, v40, v4, s45
	v_and_or_b32 v18, v4, s46, v3
	s_waitcnt lgkmcnt(1)
	v_bfe_u32 v3, v42, 16, 1
	v_add3_u32 v3, v42, v3, s45
	s_waitcnt lgkmcnt(0)
	v_bfe_u32 v4, v44, 16, 1
	v_lshrrev_b32_e32 v3, 16, v3
	v_add3_u32 v4, v44, v4, s45
	v_or_b32_e32 v46, v14, v24
	v_and_or_b32 v19, v4, s46, v3
	v_ashrrev_i32_e32 v47, 31, v46
	v_bfe_u32 v3, v33, 16, 1
	v_lshlrev_b64 v[46:47], 12, v[46:47]
	v_add3_u32 v3, v33, v3, s45
	v_bfe_u32 v4, v31, 16, 1
	v_lshl_add_u64 v[46:47], v[12:13], 0, v[46:47]
	v_lshrrev_b32_e32 v3, 16, v3
	v_add3_u32 v4, v31, v4, s45
	global_store_dwordx4 v[46:47], v[16:19], off
	v_or_b32_e32 v14, v14, v25
	v_ashrrev_i32_e32 v15, 31, v14
	v_and_or_b32 v16, v4, s46, v3
	v_bfe_u32 v3, v35, 16, 1
	v_add3_u32 v3, v35, v3, s45
	v_bfe_u32 v4, v37, 16, 1
	v_lshrrev_b32_e32 v3, 16, v3
	v_add3_u32 v4, v37, v4, s45
	v_and_or_b32 v17, v4, s46, v3
	v_bfe_u32 v3, v39, 16, 1
	v_add3_u32 v3, v39, v3, s45
	v_bfe_u32 v4, v41, 16, 1
	v_lshrrev_b32_e32 v3, 16, v3
	v_add3_u32 v4, v41, v4, s45
	v_and_or_b32 v18, v4, s46, v3
	v_bfe_u32 v3, v43, 16, 1
	v_add3_u32 v3, v43, v3, s45
	v_bfe_u32 v4, v45, 16, 1
	v_lshrrev_b32_e32 v3, 16, v3
	v_add3_u32 v4, v45, v4, s45
	v_lshlrev_b64 v[14:15], 12, v[14:15]
	v_and_or_b32 v19, v4, s46, v3
	v_lshl_add_u64 v[12:13], v[12:13], 0, v[14:15]
	global_store_dwordx4 v[12:13], v[16:19], off
	s_waitcnt lgkmcnt(0)
	s_branch .LBB0_105
